# K-loop scalar bookkeeping moved out of the load parts into MFMA-burst gaps; per-tile precomputed LDS read addresses instead of per-iteration VALU adds
# speedup vs baseline: 1.0056x; 1.0003x over previous
; #define PG8_STAGE(bufoff, gbase, voff) do { _Pragma("unroll") for (int _i = 0; _i < 2; ++_i) \
;         __builtin_amdgcn_global_load_lds((const unsigned*)((const char*)(gbase) + (voff)[_i]), (LAS unsigned*)(lds + (bufoff) + ldsw + _i * 8192), 16, 0, 0); } while (0)
; #define PG8_LDA(dst, b, h) do { _Pragma("unroll") for (int m = 0; m < 4; ++m) _Pragma("unroll") for (int k = 0; k < 2; ++k) dst[m][k] = *(const LAS bf16x8*)(lds + PG8_SA(b, h) + aoff + m * 2048 + k * 1024); } while (0)
; #define PG8_LDB(dst, b, h) do { _Pragma("unroll") for (int n = 0; n < 2; ++n) _Pragma("unroll") for (int k = 0; k < 2; ++k) dst[n][k] = *(const LAS bf16x8*)(lds + PG8_SB(b, h) + boff + n * 2048 + k * 1024); } while (0)
; #define PG8_MMA(ai, bj, At, Bt) do { __builtin_amdgcn_s_setprio(1); _Pragma("unroll") for (int m = 0; m < 4; ++m) _Pragma("unroll") for (int n = 0; n < 2; ++n) _Pragma("unroll") for (int k = 0; k < 2; ++k) \
;         acc[ai][bj][m][n] = __builtin_amdgcn_mfma_f32_16x16x32_bf16(Bt[n][k], At[m][k], acc[ai][bj][m][n], 0, 0, 0); __builtin_amdgcn_s_setprio(0); } while (0)
; #define PG8_WAIT_V(n) asm volatile("s_waitcnt vmcnt(" #n ")" ::: "memory")
; #define PG8_WAIT_L(n) asm volatile("s_waitcnt lgkmcnt(" #n ")" ::: "memory")
; #define PG8_BAR __builtin_amdgcn_s_barrier()
; template <class Epi>
; DI void gemm_phase(LAS unsigned char* lds, const Gemm g, const StaticOrder& S, const Epi& E) {
;     ...
;         for (int t = 0; t < nt; t += 2) {
;             const bool last = (t == nt - 2);
;             const char* a1 = cA + (size_t)(t + 1) * kstep;
;             const char* a2 = last ? nA : cA + (size_t)(t + 2) * kstep; const char* b2 = last ? nB : cB + (size_t)(t + 2) * kstep;
;             const char* a3 = a2 + kstep; const char* b3 = b2 + kstep;
;             PG8_LDB(B0, 0, 0); PG8_SCHED; PG8_LDA(At, 0, 0); PG8_STAGE(PG8_SA(1, 1), a1 + hstep, voffA);
;             PG8_WAIT_L(8); PG8_BAR; PG8_WAIT_L(0); PG8_MMA(0, 0, At, B0); PG8_BAR; PG8_SCHED;
;             PG8_LDB(B1, 0, 1); PG8_STAGE(PG8_SB(0, 0), b2, voffB);
;             PG8_BAR; PG8_WAIT_L(0); PG8_MMA(0, 1, At, B1); PG8_BAR;
;             PG8_LDA(At, 0, 1); PG8_STAGE(PG8_SA(0, 0), a2, voffA);
;             PG8_BAR; PG8_WAIT_L(0); PG8_MMA(1, 0, At, B0); PG8_BAR; PG8_SCHED;
;             PG8_STAGE(PG8_SB(0, 1), b2 + hstep, voffB);
;             PG8_WAIT_V(6); PG8_BAR; PG8_MMA(1, 1, At, B1); PG8_BAR;
.LBB0_210:
	s_ashr_i32 s17, s16, 31
	v_cmp_lt_i64_e32 vcc, s[18:19], v[140:141]
	s_lshl_b64 s[18:19], s[16:17], 19
	s_add_u32 s18, s43, s18
	s_addc_u32 s19, s44, s19
	s_and_b64 s[22:23], vcc, exec
	s_cselect_b32 s17, s19, s25
	s_cselect_b32 s76, s18, s24
	s_ashr_i32 s15, s14, 31
	s_lshl_b64 s[22:23], s[14:15], 19
	s_add_u32 s22, s30, s22
	s_addc_u32 s23, s31, s23
	s_and_b64 s[40:41], vcc, exec
	s_cselect_b32 s15, s23, s39
	s_cselect_b32 s77, s22, s38
	s_add_u32 s24, s24, 0x40080
	s_addc_u32 s25, s25, 0
	s_add_u32 s78, s38, 0x100
	s_addc_u32 s79, s39, 0
	s_mov_b32 s80, -2
	v_add_u32_e32 v253, 0x18000, v145
	v_add_u32_e32 v252, 0x1c000, v145
	ds_read_b128 v[150:153], v147
	ds_read_b128 v[154:157], v147 offset:1024
	ds_read_b128 v[158:161], v147 offset:2048
	ds_read_b128 v[162:165], v147 offset:3072
	s_add_u32 s38, s24, 0xfffc0080
	s_addc_u32 s39, s25, -1
	s_cmp_eq_u32 s80, 12
	s_cselect_b32 s41, s17, s39
	s_cselect_b32 s40, s76, s38
	s_cselect_b32 s39, s15, s79
	s_cselect_b32 s38, s77, s78
	s_add_i32 m0, s13, 0xc000
	ds_read_b128 v[166:169], v148
	ds_read_b128 v[170:173], v148 offset:1024
	ds_read_b128 v[174:177], v148 offset:2048
	ds_read_b128 v[182:185], v148 offset:3072
	ds_read_b128 v[186:189], v148 offset:4096
	ds_read_b128 v[190:193], v148 offset:5120
	ds_read_b128 v[194:197], v148 offset:6144
	ds_read_b128 v[198:201], v148 offset:7168
	global_load_lds_dwordx4 v136, s[24:25]
	s_add_i32 m0, s13, 0xe000
	s_nop 0
	global_load_lds_dwordx4 v138, s[24:25]
	s_waitcnt lgkmcnt(8)
	s_barrier
	s_waitcnt lgkmcnt(7)
	v_mfma_f32_16x16x32_bf16 v[124:127], v[150:153], v[166:169], 0
	v_mfma_f32_16x16x32_bf16 v[120:123], v[158:161], v[166:169], 0
	s_waitcnt lgkmcnt(5)
	v_mfma_f32_16x16x32_bf16 v[116:119], v[150:153], v[174:177], 0
	v_mfma_f32_16x16x32_bf16 v[112:115], v[158:161], v[174:177], 0
	s_waitcnt lgkmcnt(3)
	v_mfma_f32_16x16x32_bf16 v[100:103], v[150:153], v[186:189], 0
	v_mfma_f32_16x16x32_bf16 v[96:99], v[158:161], v[186:189], 0
	s_waitcnt lgkmcnt(1)
	v_mfma_f32_16x16x32_bf16 v[84:87], v[150:153], v[194:197], 0
	v_mfma_f32_16x16x32_bf16 v[80:83], v[158:161], v[194:197], 0
	v_mfma_f32_16x16x32_bf16 v[124:127], v[154:157], v[170:173], v[124:127]
	v_mfma_f32_16x16x32_bf16 v[120:123], v[162:165], v[170:173], v[120:123]
	v_mfma_f32_16x16x32_bf16 v[116:119], v[154:157], v[182:185], v[116:119]
	v_mfma_f32_16x16x32_bf16 v[112:115], v[162:165], v[182:185], v[112:115]
	v_mfma_f32_16x16x32_bf16 v[100:103], v[154:157], v[190:193], v[100:103]
	v_mfma_f32_16x16x32_bf16 v[96:99], v[162:165], v[190:193], v[96:99]
	s_add_i32 s81, s71, s45
	s_add_u32 s86, s38, s8
	s_waitcnt lgkmcnt(0)
	v_mfma_f32_16x16x32_bf16 v[84:87], v[154:157], v[198:201], v[84:87]
	s_addc_u32 s87, s39, s9
	s_mov_b32 m0, s81
	v_mfma_f32_16x16x32_bf16 v[80:83], v[162:165], v[198:201], v[80:83]
	s_barrier
	ds_read_b128 v[202:205], v149
	ds_read_b128 v[206:209], v149 offset:1024
	ds_read_b128 v[210:213], v149 offset:2048
	ds_read_b128 v[214:217], v149 offset:3072
	global_load_lds_dwordx4 v132, s[38:39]
	s_add_i32 m0, s81, 0x2000
	s_nop 0
	global_load_lds_dwordx4 v128, s[38:39]
	s_barrier
	s_waitcnt lgkmcnt(3)
	v_mfma_f32_16x16x32_bf16 v[108:111], v[202:205], v[166:169], 0
	s_waitcnt lgkmcnt(1)
	v_mfma_f32_16x16x32_bf16 v[104:107], v[210:213], v[166:169], 0
	v_mfma_f32_16x16x32_bf16 v[92:95], v[202:205], v[174:177], 0
	v_mfma_f32_16x16x32_bf16 v[88:91], v[210:213], v[174:177], 0
	v_mfma_f32_16x16x32_bf16 v[76:79], v[202:205], v[186:189], 0
	v_mfma_f32_16x16x32_bf16 v[72:75], v[210:213], v[186:189], 0
	v_mfma_f32_16x16x32_bf16 v[68:71], v[202:205], v[194:197], 0
	v_mfma_f32_16x16x32_bf16 v[64:67], v[210:213], v[194:197], 0
	v_mfma_f32_16x16x32_bf16 v[108:111], v[206:209], v[170:173], v[108:111]
	s_waitcnt lgkmcnt(0)
	v_mfma_f32_16x16x32_bf16 v[104:107], v[214:217], v[170:173], v[104:107]
	v_mfma_f32_16x16x32_bf16 v[92:95], v[206:209], v[182:185], v[92:95]
	v_mfma_f32_16x16x32_bf16 v[88:91], v[214:217], v[182:185], v[88:91]
	v_mfma_f32_16x16x32_bf16 v[76:79], v[206:209], v[190:193], v[76:79]
	v_mfma_f32_16x16x32_bf16 v[72:75], v[214:217], v[190:193], v[72:75]
	s_mov_b32 m0, s13
	s_add_u32 s88, s40, s8
	v_mfma_f32_16x16x32_bf16 v[68:71], v[206:209], v[198:201], v[68:71]
	s_addc_u32 s89, s41, s9
	v_mfma_f32_16x16x32_bf16 v[64:67], v[214:217], v[198:201], v[64:67]
	s_barrier
	ds_read_b128 v[166:169], v148 offset:16384
	ds_read_b128 v[170:173], v148 offset:17408
	ds_read_b128 v[174:177], v148 offset:18432
	ds_read_b128 v[182:185], v148 offset:19456
	ds_read_b128 v[186:189], v148 offset:20480
	ds_read_b128 v[190:193], v148 offset:21504
	ds_read_b128 v[194:197], v148 offset:22528
	ds_read_b128 v[198:201], v148 offset:23552
	global_load_lds_dwordx4 v134, s[40:41]
	s_mov_b32 m0, s48
	s_nop 0
	global_load_lds_dwordx4 v130, s[40:41]
	s_barrier
	s_waitcnt lgkmcnt(7)
	v_mfma_f32_16x16x32_bf16 v[60:63], v[150:153], v[166:169], 0
	v_mfma_f32_16x16x32_bf16 v[56:59], v[158:161], v[166:169], 0
	s_waitcnt lgkmcnt(5)
	v_mfma_f32_16x16x32_bf16 v[52:55], v[150:153], v[174:177], 0
	v_mfma_f32_16x16x32_bf16 v[48:51], v[158:161], v[174:177], 0
	s_waitcnt lgkmcnt(3)
	v_mfma_f32_16x16x32_bf16 v[36:39], v[150:153], v[186:189], 0
	v_mfma_f32_16x16x32_bf16 v[32:35], v[158:161], v[186:189], 0
	s_waitcnt lgkmcnt(1)
	v_mfma_f32_16x16x32_bf16 v[20:23], v[150:153], v[194:197], 0
	v_mfma_f32_16x16x32_bf16 v[16:19], v[158:161], v[194:197], 0
	v_mfma_f32_16x16x32_bf16 v[60:63], v[154:157], v[170:173], v[60:63]
	v_mfma_f32_16x16x32_bf16 v[56:59], v[162:165], v[170:173], v[56:59]
	v_mfma_f32_16x16x32_bf16 v[52:55], v[154:157], v[182:185], v[52:55]
	v_mfma_f32_16x16x32_bf16 v[48:51], v[162:165], v[182:185], v[48:51]
	v_mfma_f32_16x16x32_bf16 v[36:39], v[154:157], v[190:193], v[36:39]
	v_mfma_f32_16x16x32_bf16 v[32:35], v[162:165], v[190:193], v[32:35]
	s_add_u32 s82, s38, 0x40000
	s_addc_u32 s83, s39, 0
	s_waitcnt lgkmcnt(0)
	v_mfma_f32_16x16x32_bf16 v[20:23], v[154:157], v[198:201], v[20:23]
	s_add_i32 s81, s72, s45
	s_mov_b32 m0, s81
	v_mfma_f32_16x16x32_bf16 v[16:19], v[162:165], v[198:201], v[16:19]
	s_barrier
; #define PG8_STAGE(bufoff, gbase, voff) do { _Pragma("unroll") for (int _i = 0; _i < 2; ++_i) \
;         __builtin_amdgcn_global_load_lds((const unsigned*)((const char*)(gbase) + (voff)[_i]), (LAS unsigned*)(lds + (bufoff) + ldsw + _i * 8192), 16, 0, 0); } while (0)
; #define PG8_LDA(dst, b, h) do { _Pragma("unroll") for (int m = 0; m < 4; ++m) _Pragma("unroll") for (int k = 0; k < 2; ++k) dst[m][k] = *(const LAS bf16x8*)(lds + PG8_SA(b, h) + aoff + m * 2048 + k * 1024); } while (0)
; #define PG8_LDB(dst, b, h) do { _Pragma("unroll") for (int n = 0; n < 2; ++n) _Pragma("unroll") for (int k = 0; k < 2; ++k) dst[n][k] = *(const LAS bf16x8*)(lds + PG8_SB(b, h) + boff + n * 2048 + k * 1024); } while (0)
; #define PG8_MMA(ai, bj, At, Bt) do { __builtin_amdgcn_s_setprio(1); _Pragma("unroll") for (int m = 0; m < 4; ++m) _Pragma("unroll") for (int n = 0; n < 2; ++n) _Pragma("unroll") for (int k = 0; k < 2; ++k) \
;         acc[ai][bj][m][n] = __builtin_amdgcn_mfma_f32_16x16x32_bf16(Bt[n][k], At[m][k], acc[ai][bj][m][n], 0, 0, 0); __builtin_amdgcn_s_setprio(0); } while (0)
; #define PG8_WAIT_V(n) asm volatile("s_waitcnt vmcnt(" #n ")" ::: "memory")
; #define PG8_WAIT_L(n) asm volatile("s_waitcnt lgkmcnt(" #n ")" ::: "memory")
; #define PG8_BAR __builtin_amdgcn_s_barrier()
; #define PG8_SCHED __builtin_amdgcn_sched_barrier(0)
; template <class Epi>
; DI void gemm_phase(LAS unsigned char* lds, const Gemm g, const StaticOrder& S, const Epi& E) {
;     ...
;             PG8_WAIT_V(6); PG8_BAR; PG8_MMA(1, 1, At, B1); PG8_BAR;
;             PG8_LDB(B0, 1, 0); PG8_SCHED; PG8_LDA(At, 1, 0); PG8_STAGE(PG8_SA(0, 1), a2 + hstep, voffA);
;             PG8_WAIT_L(8); PG8_BAR; PG8_WAIT_L(0); PG8_MMA(0, 0, At, B0); PG8_BAR; PG8_SCHED;
;             PG8_LDB(B1, 1, 1); PG8_STAGE(PG8_SB(1, 0), b3, voffB);
;             PG8_BAR; PG8_WAIT_L(0); PG8_MMA(0, 1, At, B1); PG8_BAR;
;             PG8_LDA(At, 1, 1); PG8_STAGE(PG8_SA(1, 0), a3, voffA);
	global_load_lds_dwordx4 v132, s[82:83]
	s_add_i32 m0, s81, 0x2000
	s_nop 0
	global_load_lds_dwordx4 v128, s[82:83]
	s_waitcnt vmcnt(6)
	s_barrier
	v_mfma_f32_16x16x32_bf16 v[44:47], v[202:205], v[166:169], 0
	v_mfma_f32_16x16x32_bf16 v[40:43], v[210:213], v[166:169], 0
	v_mfma_f32_16x16x32_bf16 v[28:31], v[202:205], v[174:177], 0
	v_mfma_f32_16x16x32_bf16 v[24:27], v[210:213], v[174:177], 0
	v_mfma_f32_16x16x32_bf16 v[12:15], v[202:205], v[186:189], 0
	v_mfma_f32_16x16x32_bf16 v[8:11], v[210:213], v[186:189], 0
	v_mfma_f32_16x16x32_bf16 v[4:7], v[202:205], v[194:197], 0
	v_mfma_f32_16x16x32_bf16 v[0:3], v[210:213], v[194:197], 0
	v_mfma_f32_16x16x32_bf16 v[44:47], v[206:209], v[170:173], v[44:47]
	v_mfma_f32_16x16x32_bf16 v[40:43], v[214:217], v[170:173], v[40:43]
	v_mfma_f32_16x16x32_bf16 v[28:31], v[206:209], v[182:185], v[28:31]
	v_mfma_f32_16x16x32_bf16 v[24:27], v[214:217], v[182:185], v[24:27]
	v_mfma_f32_16x16x32_bf16 v[12:15], v[206:209], v[190:193], v[12:15]
	v_mfma_f32_16x16x32_bf16 v[8:11], v[214:217], v[190:193], v[8:11]
	v_mfma_f32_16x16x32_bf16 v[4:7], v[206:209], v[198:201], v[4:7]
	s_add_i32 s81, 0, 0x18000
	v_mfma_f32_16x16x32_bf16 v[0:3], v[214:217], v[198:201], v[0:3]
	s_barrier
	ds_read_b128 v[150:153], v253
	ds_read_b128 v[154:157], v253 offset:1024
	ds_read_b128 v[158:161], v253 offset:2048
	ds_read_b128 v[162:165], v253 offset:3072
	s_add_u32 s40, s40, 0x40000
	s_addc_u32 s41, s41, 0
	s_mov_b32 m0, s49
	ds_read_b128 v[166:169], v148 offset:32768
	ds_read_b128 v[170:173], v148 offset:33792
	ds_read_b128 v[174:177], v148 offset:34816
	ds_read_b128 v[182:185], v148 offset:35840
	ds_read_b128 v[186:189], v148 offset:36864
	ds_read_b128 v[190:193], v148 offset:37888
	ds_read_b128 v[194:197], v148 offset:38912
	ds_read_b128 v[198:201], v148 offset:39936
	global_load_lds_dwordx4 v134, s[40:41]
	s_mov_b32 m0, s50
	s_nop 0
	global_load_lds_dwordx4 v130, s[40:41]
	s_waitcnt lgkmcnt(8)
	s_barrier
	s_waitcnt lgkmcnt(7)
	v_mfma_f32_16x16x32_bf16 v[124:127], v[150:153], v[166:169], v[124:127]
	v_mfma_f32_16x16x32_bf16 v[120:123], v[158:161], v[166:169], v[120:123]
	s_waitcnt lgkmcnt(5)
	v_mfma_f32_16x16x32_bf16 v[116:119], v[150:153], v[174:177], v[116:119]
	v_mfma_f32_16x16x32_bf16 v[112:115], v[158:161], v[174:177], v[112:115]
	s_waitcnt lgkmcnt(3)
	v_mfma_f32_16x16x32_bf16 v[100:103], v[150:153], v[186:189], v[100:103]
	v_mfma_f32_16x16x32_bf16 v[96:99], v[158:161], v[186:189], v[96:99]
	s_waitcnt lgkmcnt(1)
	v_mfma_f32_16x16x32_bf16 v[84:87], v[150:153], v[194:197], v[84:87]
	v_mfma_f32_16x16x32_bf16 v[80:83], v[158:161], v[194:197], v[80:83]
	v_mfma_f32_16x16x32_bf16 v[124:127], v[154:157], v[170:173], v[124:127]
	v_mfma_f32_16x16x32_bf16 v[120:123], v[162:165], v[170:173], v[120:123]
	v_mfma_f32_16x16x32_bf16 v[116:119], v[154:157], v[182:185], v[116:119]
	v_mfma_f32_16x16x32_bf16 v[112:115], v[162:165], v[182:185], v[112:115]
	v_mfma_f32_16x16x32_bf16 v[100:103], v[154:157], v[190:193], v[100:103]
	v_mfma_f32_16x16x32_bf16 v[96:99], v[162:165], v[190:193], v[96:99]
	s_add_i32 s40, 0, 0x1c000
	s_add_i32 s41, s81, s45
	s_waitcnt lgkmcnt(0)
	v_mfma_f32_16x16x32_bf16 v[84:87], v[154:157], v[198:201], v[84:87]
	s_mov_b32 m0, s41
	v_mfma_f32_16x16x32_bf16 v[80:83], v[162:165], v[198:201], v[80:83]
	s_barrier
	ds_read_b128 v[202:205], v252
	ds_read_b128 v[206:209], v252 offset:1024
	ds_read_b128 v[210:213], v252 offset:2048
	ds_read_b128 v[214:217], v252 offset:3072
	global_load_lds_dwordx4 v132, s[86:87]
	s_add_i32 m0, s41, 0x2000
	s_nop 0
	global_load_lds_dwordx4 v128, s[86:87]
	s_barrier
	s_waitcnt lgkmcnt(3)
	v_mfma_f32_16x16x32_bf16 v[108:111], v[202:205], v[166:169], v[108:111]
	s_waitcnt lgkmcnt(1)
	v_mfma_f32_16x16x32_bf16 v[104:107], v[210:213], v[166:169], v[104:107]
	v_mfma_f32_16x16x32_bf16 v[92:95], v[202:205], v[174:177], v[92:95]
	v_mfma_f32_16x16x32_bf16 v[88:91], v[210:213], v[174:177], v[88:91]
	v_mfma_f32_16x16x32_bf16 v[76:79], v[202:205], v[186:189], v[76:79]
	v_mfma_f32_16x16x32_bf16 v[72:75], v[210:213], v[186:189], v[72:75]
	v_mfma_f32_16x16x32_bf16 v[68:71], v[202:205], v[194:197], v[68:71]
	v_mfma_f32_16x16x32_bf16 v[64:67], v[210:213], v[194:197], v[64:67]
	v_mfma_f32_16x16x32_bf16 v[108:111], v[206:209], v[170:173], v[108:111]
	s_waitcnt lgkmcnt(0)
	v_mfma_f32_16x16x32_bf16 v[104:107], v[214:217], v[170:173], v[104:107]
	v_mfma_f32_16x16x32_bf16 v[92:95], v[206:209], v[182:185], v[92:95]
	v_mfma_f32_16x16x32_bf16 v[88:91], v[214:217], v[182:185], v[88:91]
	v_mfma_f32_16x16x32_bf16 v[76:79], v[206:209], v[190:193], v[76:79]
	v_mfma_f32_16x16x32_bf16 v[72:75], v[214:217], v[190:193], v[72:75]
	v_mfma_f32_16x16x32_bf16 v[68:71], v[206:209], v[198:201], v[68:71]
	s_mov_b32 m0, s66
	v_mfma_f32_16x16x32_bf16 v[64:67], v[214:217], v[198:201], v[64:67]
	s_barrier
	ds_read_b128 v[166:169], v148 offset:49152
	ds_read_b128 v[170:173], v148 offset:50176
	ds_read_b128 v[174:177], v148 offset:51200
	ds_read_b128 v[182:185], v148 offset:52224
	ds_read_b128 v[186:189], v148 offset:53248
	ds_read_b128 v[190:193], v148 offset:54272
	ds_read_b128 v[194:197], v148 offset:55296
	ds_read_b128 v[198:201], v148 offset:56320
	global_load_lds_dwordx4 v134, s[88:89]
	s_mov_b32 m0, s67
	s_nop 0
	global_load_lds_dwordx4 v130, s[88:89]
	s_barrier
; #define PG8_STAGE(bufoff, gbase, voff) do { _Pragma("unroll") for (int _i = 0; _i < 2; ++_i) \
;         __builtin_amdgcn_global_load_lds((const unsigned*)((const char*)(gbase) + (voff)[_i]), (LAS unsigned*)(lds + (bufoff) + ldsw + _i * 8192), 16, 0, 0); } while (0)
; #define PG8_LDA(dst, b, h) do { _Pragma("unroll") for (int m = 0; m < 4; ++m) _Pragma("unroll") for (int k = 0; k < 2; ++k) dst[m][k] = *(const LAS bf16x8*)(lds + PG8_SA(b, h) + aoff + m * 2048 + k * 1024); } while (0)
; #define PG8_LDB(dst, b, h) do { _Pragma("unroll") for (int n = 0; n < 2; ++n) _Pragma("unroll") for (int k = 0; k < 2; ++k) dst[n][k] = *(const LAS bf16x8*)(lds + PG8_SB(b, h) + boff + n * 2048 + k * 1024); } while (0)
; #define PG8_MMA(ai, bj, At, Bt) do { __builtin_amdgcn_s_setprio(1); _Pragma("unroll") for (int m = 0; m < 4; ++m) _Pragma("unroll") for (int n = 0; n < 2; ++n) _Pragma("unroll") for (int k = 0; k < 2; ++k) \
;         acc[ai][bj][m][n] = __builtin_amdgcn_mfma_f32_16x16x32_bf16(Bt[n][k], At[m][k], acc[ai][bj][m][n], 0, 0, 0); __builtin_amdgcn_s_setprio(0); } while (0)
; #define PG8_WAIT_V(n) asm volatile("s_waitcnt vmcnt(" #n ")" ::: "memory")
; #define PG8_WAIT_L(n) asm volatile("s_waitcnt lgkmcnt(" #n ")" ::: "memory")
; #define PG8_BAR __builtin_amdgcn_s_barrier()
; #define PG8_SCHED __builtin_amdgcn_sched_barrier(0)
; template <class Epi>
; DI void gemm_phase(LAS unsigned char* lds, const Gemm g, const StaticOrder& S, const Epi& E) {
;     ...
;         for (int t = 0; t < nt; t += 2) {
;             const bool last = (t == nt - 2);
;             const char* a1 = cA + (size_t)(t + 1) * kstep;
;             const char* a2 = last ? nA : cA + (size_t)(t + 2) * kstep; const char* b2 = last ? nB : cB + (size_t)(t + 2) * kstep;
;             const char* a3 = a2 + kstep; const char* b3 = b2 + kstep;
;             PG8_LDB(B0, 0, 0); PG8_SCHED; PG8_LDA(At, 0, 0); PG8_STAGE(PG8_SA(1, 1), a1 + hstep, voffA);
;             PG8_WAIT_L(8); PG8_BAR; PG8_WAIT_L(0); PG8_MMA(0, 0, At, B0); PG8_BAR; PG8_SCHED;
;             PG8_LDB(B1, 0, 1); PG8_STAGE(PG8_SB(0, 0), b2, voffB);
;     ...
;             PG8_BAR; PG8_WAIT_L(0); PG8_MMA(1, 0, At, B0); PG8_BAR; PG8_SCHED;
;             PG8_STAGE(PG8_SB(1, 1), b3 + hstep, voffB);
;             PG8_WAIT_V(6); PG8_BAR; PG8_MMA(1, 1, At, B1); PG8_BAR;
	s_waitcnt lgkmcnt(7)
	v_mfma_f32_16x16x32_bf16 v[60:63], v[150:153], v[166:169], v[60:63]
	v_mfma_f32_16x16x32_bf16 v[56:59], v[158:161], v[166:169], v[56:59]
	s_waitcnt lgkmcnt(5)
	v_mfma_f32_16x16x32_bf16 v[52:55], v[150:153], v[174:177], v[52:55]
	v_mfma_f32_16x16x32_bf16 v[48:51], v[158:161], v[174:177], v[48:51]
	s_waitcnt lgkmcnt(3)
	v_mfma_f32_16x16x32_bf16 v[36:39], v[150:153], v[186:189], v[36:39]
	v_mfma_f32_16x16x32_bf16 v[32:35], v[158:161], v[186:189], v[32:35]
	s_waitcnt lgkmcnt(1)
	v_mfma_f32_16x16x32_bf16 v[20:23], v[150:153], v[194:197], v[20:23]
	v_mfma_f32_16x16x32_bf16 v[16:19], v[158:161], v[194:197], v[16:19]
	v_mfma_f32_16x16x32_bf16 v[60:63], v[154:157], v[170:173], v[60:63]
	v_mfma_f32_16x16x32_bf16 v[56:59], v[162:165], v[170:173], v[56:59]
	v_mfma_f32_16x16x32_bf16 v[52:55], v[154:157], v[182:185], v[52:55]
	v_mfma_f32_16x16x32_bf16 v[48:51], v[162:165], v[182:185], v[48:51]
	v_mfma_f32_16x16x32_bf16 v[36:39], v[154:157], v[190:193], v[36:39]
	v_mfma_f32_16x16x32_bf16 v[32:35], v[162:165], v[190:193], v[32:35]
	s_add_u32 s38, s38, 0x40080
	s_addc_u32 s39, s39, 0
	s_waitcnt lgkmcnt(0)
	v_mfma_f32_16x16x32_bf16 v[20:23], v[154:157], v[198:201], v[20:23]
	s_add_i32 s40, s40, s45
	s_mov_b32 m0, s40
	v_mfma_f32_16x16x32_bf16 v[16:19], v[162:165], v[198:201], v[16:19]
	s_barrier
	global_load_lds_dwordx4 v132, s[38:39]
	s_add_i32 m0, s40, 0x2000
	s_nop 0
	global_load_lds_dwordx4 v128, s[38:39]
	s_waitcnt vmcnt(6)
	s_barrier
	v_mfma_f32_16x16x32_bf16 v[44:47], v[202:205], v[166:169], v[44:47]
	v_mfma_f32_16x16x32_bf16 v[40:43], v[210:213], v[166:169], v[40:43]
	v_mfma_f32_16x16x32_bf16 v[28:31], v[202:205], v[174:177], v[28:31]
	v_mfma_f32_16x16x32_bf16 v[24:27], v[210:213], v[174:177], v[24:27]
	v_mfma_f32_16x16x32_bf16 v[12:15], v[202:205], v[186:189], v[12:15]
	v_mfma_f32_16x16x32_bf16 v[8:11], v[210:213], v[186:189], v[8:11]
	v_mfma_f32_16x16x32_bf16 v[4:7], v[202:205], v[194:197], v[4:7]
	v_mfma_f32_16x16x32_bf16 v[0:3], v[210:213], v[194:197], v[0:3]
	v_mfma_f32_16x16x32_bf16 v[44:47], v[206:209], v[170:173], v[44:47]
	s_add_i32 s80, s80, 2
	s_add_u32 s24, s24, 0x100
	v_mfma_f32_16x16x32_bf16 v[40:43], v[214:217], v[170:173], v[40:43]
	s_addc_u32 s25, s25, 0
	s_add_u32 s78, s78, 0x100
	v_mfma_f32_16x16x32_bf16 v[28:31], v[206:209], v[182:185], v[28:31]
	s_addc_u32 s79, s79, 0
	s_add_u32 s38, s24, 0xfffc0080
	v_mfma_f32_16x16x32_bf16 v[24:27], v[214:217], v[182:185], v[24:27]
	s_addc_u32 s39, s25, -1
	s_cmp_eq_u32 s80, 12
	v_mfma_f32_16x16x32_bf16 v[12:15], v[206:209], v[190:193], v[12:15]
	s_cselect_b32 s41, s17, s39
	s_cselect_b32 s40, s76, s38
	v_mfma_f32_16x16x32_bf16 v[8:11], v[214:217], v[190:193], v[8:11]
	s_cselect_b32 s39, s15, s79
	s_cselect_b32 s38, s77, s78
	v_mfma_f32_16x16x32_bf16 v[4:7], v[206:209], v[198:201], v[4:7]
	s_add_i32 m0, s13, 0xc000
	v_mfma_f32_16x16x32_bf16 v[0:3], v[214:217], v[198:201], v[0:3]
	s_cmp_gt_u32 s80, 13
	s_barrier
.LBB0_211:
	ds_read_b128 v[150:153], v147
	ds_read_b128 v[154:157], v147 offset:1024
	ds_read_b128 v[158:161], v147 offset:2048
	ds_read_b128 v[162:165], v147 offset:3072
	ds_read_b128 v[166:169], v148
	ds_read_b128 v[170:173], v148 offset:1024
	ds_read_b128 v[174:177], v148 offset:2048
	ds_read_b128 v[182:185], v148 offset:3072
	ds_read_b128 v[186:189], v148 offset:4096
	ds_read_b128 v[190:193], v148 offset:5120
	ds_read_b128 v[194:197], v148 offset:6144
	ds_read_b128 v[198:201], v148 offset:7168
	global_load_lds_dwordx4 v136, s[24:25]
	s_add_i32 m0, s13, 0xe000
	s_nop 0
	global_load_lds_dwordx4 v138, s[24:25]
	s_waitcnt lgkmcnt(8)
	s_barrier
	s_waitcnt lgkmcnt(7)
	v_mfma_f32_16x16x32_bf16 v[124:127], v[150:153], v[166:169], v[124:127]
	v_mfma_f32_16x16x32_bf16 v[120:123], v[158:161], v[166:169], v[120:123]
	s_waitcnt lgkmcnt(5)
	v_mfma_f32_16x16x32_bf16 v[116:119], v[150:153], v[174:177], v[116:119]
	v_mfma_f32_16x16x32_bf16 v[112:115], v[158:161], v[174:177], v[112:115]
	s_waitcnt lgkmcnt(3)
	v_mfma_f32_16x16x32_bf16 v[100:103], v[150:153], v[186:189], v[100:103]
	v_mfma_f32_16x16x32_bf16 v[96:99], v[158:161], v[186:189], v[96:99]
	s_waitcnt lgkmcnt(1)
	v_mfma_f32_16x16x32_bf16 v[84:87], v[150:153], v[194:197], v[84:87]
	v_mfma_f32_16x16x32_bf16 v[80:83], v[158:161], v[194:197], v[80:83]
	v_mfma_f32_16x16x32_bf16 v[124:127], v[154:157], v[170:173], v[124:127]
	v_mfma_f32_16x16x32_bf16 v[120:123], v[162:165], v[170:173], v[120:123]
	v_mfma_f32_16x16x32_bf16 v[116:119], v[154:157], v[182:185], v[116:119]
	v_mfma_f32_16x16x32_bf16 v[112:115], v[162:165], v[182:185], v[112:115]
	v_mfma_f32_16x16x32_bf16 v[100:103], v[154:157], v[190:193], v[100:103]
	v_mfma_f32_16x16x32_bf16 v[96:99], v[162:165], v[190:193], v[96:99]
	s_add_i32 s81, s71, s45
	s_add_u32 s86, s38, s8
	s_waitcnt lgkmcnt(0)
	v_mfma_f32_16x16x32_bf16 v[84:87], v[154:157], v[198:201], v[84:87]
	s_addc_u32 s87, s39, s9
	s_mov_b32 m0, s81
	v_mfma_f32_16x16x32_bf16 v[80:83], v[162:165], v[198:201], v[80:83]
	s_barrier
	ds_read_b128 v[202:205], v149
	ds_read_b128 v[206:209], v149 offset:1024
	ds_read_b128 v[210:213], v149 offset:2048
	ds_read_b128 v[214:217], v149 offset:3072
	global_load_lds_dwordx4 v132, s[38:39]
	s_add_i32 m0, s81, 0x2000
	s_nop 0
	global_load_lds_dwordx4 v128, s[38:39]
	s_barrier
; #define PG8_STAGE(bufoff, gbase, voff) do { _Pragma("unroll") for (int _i = 0; _i < 2; ++_i) \
;         __builtin_amdgcn_global_load_lds((const unsigned*)((const char*)(gbase) + (voff)[_i]), (LAS unsigned*)(lds + (bufoff) + ldsw + _i * 8192), 16, 0, 0); } while (0)
; #define PG8_LDA(dst, b, h) do { _Pragma("unroll") for (int m = 0; m < 4; ++m) _Pragma("unroll") for (int k = 0; k < 2; ++k) dst[m][k] = *(const LAS bf16x8*)(lds + PG8_SA(b, h) + aoff + m * 2048 + k * 1024); } while (0)
; #define PG8_LDB(dst, b, h) do { _Pragma("unroll") for (int n = 0; n < 2; ++n) _Pragma("unroll") for (int k = 0; k < 2; ++k) dst[n][k] = *(const LAS bf16x8*)(lds + PG8_SB(b, h) + boff + n * 2048 + k * 1024); } while (0)
; #define PG8_MMA(ai, bj, At, Bt) do { __builtin_amdgcn_s_setprio(1); _Pragma("unroll") for (int m = 0; m < 4; ++m) _Pragma("unroll") for (int n = 0; n < 2; ++n) _Pragma("unroll") for (int k = 0; k < 2; ++k) \
;         acc[ai][bj][m][n] = __builtin_amdgcn_mfma_f32_16x16x32_bf16(Bt[n][k], At[m][k], acc[ai][bj][m][n], 0, 0, 0); __builtin_amdgcn_s_setprio(0); } while (0)
; #define PG8_WAIT_V(n) asm volatile("s_waitcnt vmcnt(" #n ")" ::: "memory")
; #define PG8_WAIT_L(n) asm volatile("s_waitcnt lgkmcnt(" #n ")" ::: "memory")
; #define PG8_BAR __builtin_amdgcn_s_barrier()
; #define PG8_SCHED __builtin_amdgcn_sched_barrier(0)
; template <class Epi>
; DI void gemm_phase(LAS unsigned char* lds, const Gemm g, const StaticOrder& S, const Epi& E) {
;     ...
;             PG8_BAR; PG8_WAIT_L(0); PG8_MMA(0, 1, At, B1); PG8_BAR;
;             PG8_LDA(At, 0, 1); PG8_STAGE(PG8_SA(0, 0), a2, voffA);
;             PG8_BAR; PG8_WAIT_L(0); PG8_MMA(1, 0, At, B0); PG8_BAR; PG8_SCHED;
;             PG8_STAGE(PG8_SB(0, 1), b2 + hstep, voffB);
;             PG8_WAIT_V(6); PG8_BAR; PG8_MMA(1, 1, At, B1); PG8_BAR;
;             PG8_LDB(B0, 1, 0); PG8_SCHED; PG8_LDA(At, 1, 0); PG8_STAGE(PG8_SA(0, 1), a2 + hstep, voffA);
;             PG8_WAIT_L(8); PG8_BAR; PG8_WAIT_L(0); PG8_MMA(0, 0, At, B0); PG8_BAR; PG8_SCHED;
;             PG8_LDB(B1, 1, 1); PG8_STAGE(PG8_SB(1, 0), b3, voffB);
	s_waitcnt lgkmcnt(3)
	v_mfma_f32_16x16x32_bf16 v[108:111], v[202:205], v[166:169], v[108:111]
	s_waitcnt lgkmcnt(1)
	v_mfma_f32_16x16x32_bf16 v[104:107], v[210:213], v[166:169], v[104:107]
	v_mfma_f32_16x16x32_bf16 v[92:95], v[202:205], v[174:177], v[92:95]
	v_mfma_f32_16x16x32_bf16 v[88:91], v[210:213], v[174:177], v[88:91]
	v_mfma_f32_16x16x32_bf16 v[76:79], v[202:205], v[186:189], v[76:79]
	v_mfma_f32_16x16x32_bf16 v[72:75], v[210:213], v[186:189], v[72:75]
	v_mfma_f32_16x16x32_bf16 v[68:71], v[202:205], v[194:197], v[68:71]
	v_mfma_f32_16x16x32_bf16 v[64:67], v[210:213], v[194:197], v[64:67]
	v_mfma_f32_16x16x32_bf16 v[108:111], v[206:209], v[170:173], v[108:111]
	s_waitcnt lgkmcnt(0)
	v_mfma_f32_16x16x32_bf16 v[104:107], v[214:217], v[170:173], v[104:107]
	v_mfma_f32_16x16x32_bf16 v[92:95], v[206:209], v[182:185], v[92:95]
	v_mfma_f32_16x16x32_bf16 v[88:91], v[214:217], v[182:185], v[88:91]
	v_mfma_f32_16x16x32_bf16 v[76:79], v[206:209], v[190:193], v[76:79]
	v_mfma_f32_16x16x32_bf16 v[72:75], v[214:217], v[190:193], v[72:75]
	s_mov_b32 m0, s13
	s_add_u32 s88, s40, s8
	v_mfma_f32_16x16x32_bf16 v[68:71], v[206:209], v[198:201], v[68:71]
	s_addc_u32 s89, s41, s9
	v_mfma_f32_16x16x32_bf16 v[64:67], v[214:217], v[198:201], v[64:67]
	s_barrier
	ds_read_b128 v[166:169], v148 offset:16384
	ds_read_b128 v[170:173], v148 offset:17408
	ds_read_b128 v[174:177], v148 offset:18432
	ds_read_b128 v[182:185], v148 offset:19456
	ds_read_b128 v[186:189], v148 offset:20480
	ds_read_b128 v[190:193], v148 offset:21504
	ds_read_b128 v[194:197], v148 offset:22528
	ds_read_b128 v[198:201], v148 offset:23552
	global_load_lds_dwordx4 v134, s[40:41]
	s_mov_b32 m0, s48
	s_nop 0
	global_load_lds_dwordx4 v130, s[40:41]
	s_barrier
	s_waitcnt lgkmcnt(7)
	v_mfma_f32_16x16x32_bf16 v[60:63], v[150:153], v[166:169], v[60:63]
	v_mfma_f32_16x16x32_bf16 v[56:59], v[158:161], v[166:169], v[56:59]
	s_waitcnt lgkmcnt(5)
	v_mfma_f32_16x16x32_bf16 v[52:55], v[150:153], v[174:177], v[52:55]
	v_mfma_f32_16x16x32_bf16 v[48:51], v[158:161], v[174:177], v[48:51]
	s_waitcnt lgkmcnt(3)
	v_mfma_f32_16x16x32_bf16 v[36:39], v[150:153], v[186:189], v[36:39]
	v_mfma_f32_16x16x32_bf16 v[32:35], v[158:161], v[186:189], v[32:35]
	s_waitcnt lgkmcnt(1)
	v_mfma_f32_16x16x32_bf16 v[20:23], v[150:153], v[194:197], v[20:23]
	v_mfma_f32_16x16x32_bf16 v[16:19], v[158:161], v[194:197], v[16:19]
	v_mfma_f32_16x16x32_bf16 v[60:63], v[154:157], v[170:173], v[60:63]
	v_mfma_f32_16x16x32_bf16 v[56:59], v[162:165], v[170:173], v[56:59]
	v_mfma_f32_16x16x32_bf16 v[52:55], v[154:157], v[182:185], v[52:55]
	v_mfma_f32_16x16x32_bf16 v[48:51], v[162:165], v[182:185], v[48:51]
	v_mfma_f32_16x16x32_bf16 v[36:39], v[154:157], v[190:193], v[36:39]
	v_mfma_f32_16x16x32_bf16 v[32:35], v[162:165], v[190:193], v[32:35]
	s_add_u32 s82, s38, 0x40000
	s_addc_u32 s83, s39, 0
	s_waitcnt lgkmcnt(0)
	v_mfma_f32_16x16x32_bf16 v[20:23], v[154:157], v[198:201], v[20:23]
	s_add_i32 s81, s72, s45
	s_mov_b32 m0, s81
	v_mfma_f32_16x16x32_bf16 v[16:19], v[162:165], v[198:201], v[16:19]
	s_barrier
	global_load_lds_dwordx4 v132, s[82:83]
	s_add_i32 m0, s81, 0x2000
	s_nop 0
	global_load_lds_dwordx4 v128, s[82:83]
	s_waitcnt vmcnt(6)
	s_barrier
	v_mfma_f32_16x16x32_bf16 v[44:47], v[202:205], v[166:169], v[44:47]
	v_mfma_f32_16x16x32_bf16 v[40:43], v[210:213], v[166:169], v[40:43]
	v_mfma_f32_16x16x32_bf16 v[28:31], v[202:205], v[174:177], v[28:31]
	v_mfma_f32_16x16x32_bf16 v[24:27], v[210:213], v[174:177], v[24:27]
	v_mfma_f32_16x16x32_bf16 v[12:15], v[202:205], v[186:189], v[12:15]
	v_mfma_f32_16x16x32_bf16 v[8:11], v[210:213], v[186:189], v[8:11]
	v_mfma_f32_16x16x32_bf16 v[4:7], v[202:205], v[194:197], v[4:7]
	v_mfma_f32_16x16x32_bf16 v[0:3], v[210:213], v[194:197], v[0:3]
	v_mfma_f32_16x16x32_bf16 v[44:47], v[206:209], v[170:173], v[44:47]
	v_mfma_f32_16x16x32_bf16 v[40:43], v[214:217], v[170:173], v[40:43]
	v_mfma_f32_16x16x32_bf16 v[28:31], v[206:209], v[182:185], v[28:31]
	v_mfma_f32_16x16x32_bf16 v[24:27], v[214:217], v[182:185], v[24:27]
	v_mfma_f32_16x16x32_bf16 v[12:15], v[206:209], v[190:193], v[12:15]
	v_mfma_f32_16x16x32_bf16 v[8:11], v[214:217], v[190:193], v[8:11]
	v_mfma_f32_16x16x32_bf16 v[4:7], v[206:209], v[198:201], v[4:7]
	s_add_i32 s81, 0, 0x18000
	v_mfma_f32_16x16x32_bf16 v[0:3], v[214:217], v[198:201], v[0:3]
	s_barrier
	ds_read_b128 v[150:153], v253
	ds_read_b128 v[154:157], v253 offset:1024
	ds_read_b128 v[158:161], v253 offset:2048
	ds_read_b128 v[162:165], v253 offset:3072
	s_add_u32 s40, s40, 0x40000
	s_addc_u32 s41, s41, 0
	s_mov_b32 m0, s49
	ds_read_b128 v[166:169], v148 offset:32768
	ds_read_b128 v[170:173], v148 offset:33792
	ds_read_b128 v[174:177], v148 offset:34816
	ds_read_b128 v[182:185], v148 offset:35840
	ds_read_b128 v[186:189], v148 offset:36864
	ds_read_b128 v[190:193], v148 offset:37888
	ds_read_b128 v[194:197], v148 offset:38912
	ds_read_b128 v[198:201], v148 offset:39936
	global_load_lds_dwordx4 v134, s[40:41]
	s_mov_b32 m0, s50
	s_nop 0
	global_load_lds_dwordx4 v130, s[40:41]
	s_waitcnt lgkmcnt(8)
	s_barrier
; #define PG8_STAGE(bufoff, gbase, voff) do { _Pragma("unroll") for (int _i = 0; _i < 2; ++_i) \
;         __builtin_amdgcn_global_load_lds((const unsigned*)((const char*)(gbase) + (voff)[_i]), (LAS unsigned*)(lds + (bufoff) + ldsw + _i * 8192), 16, 0, 0); } while (0)
; #define PG8_LDA(dst, b, h) do { _Pragma("unroll") for (int m = 0; m < 4; ++m) _Pragma("unroll") for (int k = 0; k < 2; ++k) dst[m][k] = *(const LAS bf16x8*)(lds + PG8_SA(b, h) + aoff + m * 2048 + k * 1024); } while (0)
; #define PG8_LDB(dst, b, h) do { _Pragma("unroll") for (int n = 0; n < 2; ++n) _Pragma("unroll") for (int k = 0; k < 2; ++k) dst[n][k] = *(const LAS bf16x8*)(lds + PG8_SB(b, h) + boff + n * 2048 + k * 1024); } while (0)
; #define PG8_MMA(ai, bj, At, Bt) do { __builtin_amdgcn_s_setprio(1); _Pragma("unroll") for (int m = 0; m < 4; ++m) _Pragma("unroll") for (int n = 0; n < 2; ++n) _Pragma("unroll") for (int k = 0; k < 2; ++k) \
;         acc[ai][bj][m][n] = __builtin_amdgcn_mfma_f32_16x16x32_bf16(Bt[n][k], At[m][k], acc[ai][bj][m][n], 0, 0, 0); __builtin_amdgcn_s_setprio(0); } while (0)
; #define PG8_WAIT_L(n) asm volatile("s_waitcnt lgkmcnt(" #n ")" ::: "memory")
; #define PG8_BAR __builtin_amdgcn_s_barrier()
; #define PG8_SCHED __builtin_amdgcn_sched_barrier(0)
; template <class Epi>
; DI void gemm_phase(LAS unsigned char* lds, const Gemm g, const StaticOrder& S, const Epi& E) {
;     ...
;             PG8_WAIT_L(8); PG8_BAR; PG8_WAIT_L(0); PG8_MMA(0, 0, At, B0); PG8_BAR; PG8_SCHED;
;             PG8_LDB(B1, 1, 1); PG8_STAGE(PG8_SB(1, 0), b3, voffB);
;             PG8_BAR; PG8_WAIT_L(0); PG8_MMA(0, 1, At, B1); PG8_BAR;
;             PG8_LDA(At, 1, 1); PG8_STAGE(PG8_SA(1, 0), a3, voffA);
;             PG8_BAR; PG8_WAIT_L(0); PG8_MMA(1, 0, At, B0); PG8_BAR; PG8_SCHED;
;             PG8_STAGE(PG8_SB(1, 1), b3 + hstep, voffB);
	s_waitcnt lgkmcnt(7)
	v_mfma_f32_16x16x32_bf16 v[124:127], v[150:153], v[166:169], v[124:127]
	v_mfma_f32_16x16x32_bf16 v[120:123], v[158:161], v[166:169], v[120:123]
	s_waitcnt lgkmcnt(5)
	v_mfma_f32_16x16x32_bf16 v[116:119], v[150:153], v[174:177], v[116:119]
	v_mfma_f32_16x16x32_bf16 v[112:115], v[158:161], v[174:177], v[112:115]
	s_waitcnt lgkmcnt(3)
	v_mfma_f32_16x16x32_bf16 v[100:103], v[150:153], v[186:189], v[100:103]
	v_mfma_f32_16x16x32_bf16 v[96:99], v[158:161], v[186:189], v[96:99]
	s_waitcnt lgkmcnt(1)
	v_mfma_f32_16x16x32_bf16 v[84:87], v[150:153], v[194:197], v[84:87]
	v_mfma_f32_16x16x32_bf16 v[80:83], v[158:161], v[194:197], v[80:83]
	v_mfma_f32_16x16x32_bf16 v[124:127], v[154:157], v[170:173], v[124:127]
	v_mfma_f32_16x16x32_bf16 v[120:123], v[162:165], v[170:173], v[120:123]
	v_mfma_f32_16x16x32_bf16 v[116:119], v[154:157], v[182:185], v[116:119]
	v_mfma_f32_16x16x32_bf16 v[112:115], v[162:165], v[182:185], v[112:115]
	v_mfma_f32_16x16x32_bf16 v[100:103], v[154:157], v[190:193], v[100:103]
	v_mfma_f32_16x16x32_bf16 v[96:99], v[162:165], v[190:193], v[96:99]
	s_add_i32 s40, 0, 0x1c000
	s_add_i32 s41, s81, s45
	s_waitcnt lgkmcnt(0)
	v_mfma_f32_16x16x32_bf16 v[84:87], v[154:157], v[198:201], v[84:87]
	s_mov_b32 m0, s41
	v_mfma_f32_16x16x32_bf16 v[80:83], v[162:165], v[198:201], v[80:83]
	s_barrier
	ds_read_b128 v[202:205], v252
	ds_read_b128 v[206:209], v252 offset:1024
	ds_read_b128 v[210:213], v252 offset:2048
	ds_read_b128 v[214:217], v252 offset:3072
	global_load_lds_dwordx4 v132, s[86:87]
	s_add_i32 m0, s41, 0x2000
	s_nop 0
	global_load_lds_dwordx4 v128, s[86:87]
	s_barrier
	s_waitcnt lgkmcnt(3)
	v_mfma_f32_16x16x32_bf16 v[108:111], v[202:205], v[166:169], v[108:111]
	s_waitcnt lgkmcnt(1)
	v_mfma_f32_16x16x32_bf16 v[104:107], v[210:213], v[166:169], v[104:107]
	v_mfma_f32_16x16x32_bf16 v[92:95], v[202:205], v[174:177], v[92:95]
	v_mfma_f32_16x16x32_bf16 v[88:91], v[210:213], v[174:177], v[88:91]
	v_mfma_f32_16x16x32_bf16 v[76:79], v[202:205], v[186:189], v[76:79]
	v_mfma_f32_16x16x32_bf16 v[72:75], v[210:213], v[186:189], v[72:75]
	v_mfma_f32_16x16x32_bf16 v[68:71], v[202:205], v[194:197], v[68:71]
	v_mfma_f32_16x16x32_bf16 v[64:67], v[210:213], v[194:197], v[64:67]
	v_mfma_f32_16x16x32_bf16 v[108:111], v[206:209], v[170:173], v[108:111]
	s_waitcnt lgkmcnt(0)
	v_mfma_f32_16x16x32_bf16 v[104:107], v[214:217], v[170:173], v[104:107]
	v_mfma_f32_16x16x32_bf16 v[92:95], v[206:209], v[182:185], v[92:95]
	v_mfma_f32_16x16x32_bf16 v[88:91], v[214:217], v[182:185], v[88:91]
	v_mfma_f32_16x16x32_bf16 v[76:79], v[206:209], v[190:193], v[76:79]
	v_mfma_f32_16x16x32_bf16 v[72:75], v[214:217], v[190:193], v[72:75]
	v_mfma_f32_16x16x32_bf16 v[68:71], v[206:209], v[198:201], v[68:71]
	s_mov_b32 m0, s66
	v_mfma_f32_16x16x32_bf16 v[64:67], v[214:217], v[198:201], v[64:67]
	s_barrier
	ds_read_b128 v[166:169], v148 offset:49152
	ds_read_b128 v[170:173], v148 offset:50176
	ds_read_b128 v[174:177], v148 offset:51200
	ds_read_b128 v[182:185], v148 offset:52224
	ds_read_b128 v[186:189], v148 offset:53248
	ds_read_b128 v[190:193], v148 offset:54272
	ds_read_b128 v[194:197], v148 offset:55296
	ds_read_b128 v[198:201], v148 offset:56320
	global_load_lds_dwordx4 v134, s[88:89]
	s_mov_b32 m0, s67
	s_nop 0
	global_load_lds_dwordx4 v130, s[88:89]
	s_barrier
	s_waitcnt lgkmcnt(7)
	v_mfma_f32_16x16x32_bf16 v[60:63], v[150:153], v[166:169], v[60:63]
	v_mfma_f32_16x16x32_bf16 v[56:59], v[158:161], v[166:169], v[56:59]
	s_waitcnt lgkmcnt(5)
	v_mfma_f32_16x16x32_bf16 v[52:55], v[150:153], v[174:177], v[52:55]
	v_mfma_f32_16x16x32_bf16 v[48:51], v[158:161], v[174:177], v[48:51]
	s_waitcnt lgkmcnt(3)
	v_mfma_f32_16x16x32_bf16 v[36:39], v[150:153], v[186:189], v[36:39]
	v_mfma_f32_16x16x32_bf16 v[32:35], v[158:161], v[186:189], v[32:35]
	s_waitcnt lgkmcnt(1)
	v_mfma_f32_16x16x32_bf16 v[20:23], v[150:153], v[194:197], v[20:23]
	v_mfma_f32_16x16x32_bf16 v[16:19], v[158:161], v[194:197], v[16:19]
	v_mfma_f32_16x16x32_bf16 v[60:63], v[154:157], v[170:173], v[60:63]
	v_mfma_f32_16x16x32_bf16 v[56:59], v[162:165], v[170:173], v[56:59]
	v_mfma_f32_16x16x32_bf16 v[52:55], v[154:157], v[182:185], v[52:55]
	v_mfma_f32_16x16x32_bf16 v[48:51], v[162:165], v[182:185], v[48:51]
	v_mfma_f32_16x16x32_bf16 v[36:39], v[154:157], v[190:193], v[36:39]
	v_mfma_f32_16x16x32_bf16 v[32:35], v[162:165], v[190:193], v[32:35]
	s_add_u32 s38, s38, 0x40080
	s_addc_u32 s39, s39, 0
	s_waitcnt lgkmcnt(0)
	v_mfma_f32_16x16x32_bf16 v[20:23], v[154:157], v[198:201], v[20:23]
	s_add_i32 s40, s40, s45
	s_mov_b32 m0, s40
	v_mfma_f32_16x16x32_bf16 v[16:19], v[162:165], v[198:201], v[16:19]
	s_barrier
	global_load_lds_dwordx4 v132, s[38:39]
	s_add_i32 m0, s40, 0x2000
	s_nop 0
	global_load_lds_dwordx4 v128, s[38:39]
	s_waitcnt vmcnt(6)
	s_barrier
; DI unsigned pk2(float a, float b) { f32x2 v = {a, b}; bf16x2_t r = __builtin_convertvector(v, bf16x2_t); return __builtin_bit_cast(unsigned, r); }
; #define PG8_MMA(ai, bj, At, Bt) do { __builtin_amdgcn_s_setprio(1); _Pragma("unroll") for (int m = 0; m < 4; ++m) _Pragma("unroll") for (int n = 0; n < 2; ++n) _Pragma("unroll") for (int k = 0; k < 2; ++k) \
;         acc[ai][bj][m][n] = __builtin_amdgcn_mfma_f32_16x16x32_bf16(Bt[n][k], At[m][k], acc[ai][bj][m][n], 0, 0, 0); __builtin_amdgcn_s_setprio(0); } while (0)
; #define PG8_WAIT_V(n) asm volatile("s_waitcnt vmcnt(" #n ")" ::: "memory")
; #define PG8_BAR __builtin_amdgcn_s_barrier()
; template <class Epi>
; DI void gemm_phase(LAS unsigned char* lds, const Gemm g, const StaticOrder& S, const Epi& E) {
;     ...
;             PG8_WAIT_V(6); PG8_BAR; PG8_MMA(1, 1, At, B1); PG8_BAR;
;         }
;         E(acc, cur, wr, wc, fr, fq);
;         if (!has_next) break;
; #pragma unroll
;         for (int a = 0; a < 2; ++a)
; #pragma unroll
;             for (int b = 0; b < 2; ++b)
; #pragma unroll
;                 for (int m = 0; m < 4; ++m)
; #pragma unroll
;                     for (int n = 0; n < 2; ++n) acc[a][b][m][n] = (f32x4){0.f, 0.f, 0.f, 0.f};
;         cur = nxt; cA = nA; cB = nB; ++ui;
;     }
;     PG8_WAIT_V(0);
;     if (wr == 0) PG8_BAR;
;     PG8_BAR;
;     DI void operator()(const f32x4 (&acc)[2][2][4][2], const Unit& u, int wr, int wc, int fr, int fq) const {
;         const bool first = u.pn < 6; const int ldc = first ? P1W : P2W;
;         const int row0 = u.pm * BM + wr * 64 + fr, col0 = (first ? u.pn : u.pn - 6) * BM + wc * 32 + 8 * fq;
;         bf16_t* O = first ? O1 : O2;
; #pragma unroll
;         for (int ai = 0; ai < 2; ++ai)
; #pragma unroll
;             for (int m = 0; m < 4; ++m) { bf16_t* rowp = O + (size_t)(row0 + ai * HALF + m * 16) * ldc + col0;
; #pragma unroll
;                 for (int bj = 0; bj < 2; ++bj) { const f32x4 v0 = acc[ai][bj][m][0], v1 = acc[ai][bj][m][1];
;                     u32x4 w; w.x = pk2(v0[0], v0[1]); w.y = pk2(v0[2], v0[3]); w.z = pk2(v1[0], v1[1]); w.w = pk2(v1[2], v1[3]);
;                     *(u32x4*)(rowp + bj * HALF) = w; } }
	v_mfma_f32_16x16x32_bf16 v[44:47], v[202:205], v[166:169], v[44:47]
	v_mfma_f32_16x16x32_bf16 v[40:43], v[210:213], v[166:169], v[40:43]
	v_mfma_f32_16x16x32_bf16 v[28:31], v[202:205], v[174:177], v[28:31]
	v_mfma_f32_16x16x32_bf16 v[24:27], v[210:213], v[174:177], v[24:27]
	v_mfma_f32_16x16x32_bf16 v[12:15], v[202:205], v[186:189], v[12:15]
	v_mfma_f32_16x16x32_bf16 v[8:11], v[210:213], v[186:189], v[8:11]
	v_mfma_f32_16x16x32_bf16 v[4:7], v[202:205], v[194:197], v[4:7]
	v_mfma_f32_16x16x32_bf16 v[0:3], v[210:213], v[194:197], v[0:3]
	v_mfma_f32_16x16x32_bf16 v[44:47], v[206:209], v[170:173], v[44:47]
	s_add_i32 s80, s80, 2
	s_add_u32 s24, s24, 0x100
	v_mfma_f32_16x16x32_bf16 v[40:43], v[214:217], v[170:173], v[40:43]
	s_addc_u32 s25, s25, 0
	s_add_u32 s78, s78, 0x100
	v_mfma_f32_16x16x32_bf16 v[28:31], v[206:209], v[182:185], v[28:31]
	s_addc_u32 s79, s79, 0
	s_add_u32 s38, s24, 0xfffc0080
	v_mfma_f32_16x16x32_bf16 v[24:27], v[214:217], v[182:185], v[24:27]
	s_addc_u32 s39, s25, -1
	s_cmp_eq_u32 s80, 12
	v_mfma_f32_16x16x32_bf16 v[12:15], v[206:209], v[190:193], v[12:15]
	s_cselect_b32 s41, s17, s39
	s_cselect_b32 s40, s76, s38
	v_mfma_f32_16x16x32_bf16 v[8:11], v[214:217], v[190:193], v[8:11]
	s_cselect_b32 s39, s15, s79
	s_cselect_b32 s38, s77, s78
	v_mfma_f32_16x16x32_bf16 v[4:7], v[206:209], v[198:201], v[4:7]
	s_add_i32 m0, s13, 0xc000
	v_mfma_f32_16x16x32_bf16 v[0:3], v[214:217], v[198:201], v[0:3]
	s_cmp_gt_u32 s80, 13
	s_barrier
	s_cbranch_scc0 .LBB0_211
	s_lshl_b32 s15, s75, 8
	s_add_i32 s17, s15, 0xfffffa00
	s_cmp_lt_i32 s75, 6
	v_lshl_add_u32 v154, s12, 8, v144
	s_cselect_b32 s12, s15, s17
	v_or_b32_e32 v150, s12, v146
	s_cselect_b32 s12, s74, 0x1ef76000
	s_cselect_b32 s38, s73, 0xa00
	s_add_u32 s24, s30, s12
	s_addc_u32 s25, s31, 0
	v_ashrrev_i32_e32 v151, 31, v150
	v_lshl_add_u64 v[150:151], v[150:151], 1, s[24:25]
	v_mad_i64_i32 v[152:153], s[24:25], s38, v154, 0
	v_cvt_pk_bf16_f32 v108, v108, v109
	v_cvt_pk_bf16_f32 v109, v110, v111
	v_cvt_pk_bf16_f32 v110, v104, v105
	v_or_b32_e32 v104, 16, v154
	v_lshl_add_u64 v[152:153], v[152:153], 1, v[150:151]
	v_cvt_pk_bf16_f32 v111, v106, v107
	v_mad_i64_i32 v[104:105], s[24:25], s38, v104, 0
	v_cvt_pk_bf16_f32 v92, v92, v93
	v_cvt_pk_bf16_f32 v93, v94, v95
	v_cvt_pk_bf16_f32 v94, v88, v89
	v_or_b32_e32 v88, 32, v154
	v_cvt_pk_bf16_f32 v124, v124, v125
	v_cvt_pk_bf16_f32 v125, v126, v127
	v_cvt_pk_bf16_f32 v126, v120, v121
	v_cvt_pk_bf16_f32 v127, v122, v123
	global_store_dwordx4 v[152:153], v[108:111], off offset:256
	v_cvt_pk_bf16_f32 v95, v90, v91
	v_mad_i64_i32 v[88:89], s[24:25], s38, v88, 0
	v_lshl_add_u64 v[108:109], v[104:105], 1, v[150:151]
	v_cvt_pk_bf16_f32 v76, v76, v77
	v_cvt_pk_bf16_f32 v77, v78, v79
	v_cvt_pk_bf16_f32 v78, v72, v73
	v_or_b32_e32 v72, 48, v154
	v_cvt_pk_bf16_f32 v68, v68, v69
	v_cvt_pk_bf16_f32 v69, v70, v71
	v_cvt_pk_bf16_f32 v70, v64, v65
	v_add_u32_e32 v64, 0x80, v154
	global_store_dwordx4 v[152:153], v[124:127], off
	v_cvt_pk_bf16_f32 v104, v116, v117
	v_cvt_pk_bf16_f32 v105, v118, v119
	v_cvt_pk_bf16_f32 v106, v112, v113
	v_cvt_pk_bf16_f32 v107, v114, v115
	global_store_dwordx4 v[108:109], v[92:95], off offset:256
	v_cvt_pk_bf16_f32 v79, v74, v75
	v_mad_i64_i32 v[72:73], s[24:25], s38, v72, 0
	v_lshl_add_u64 v[92:93], v[88:89], 1, v[150:151]
	v_mad_i64_i32 v[64:65], s[24:25], s38, v64, 0
	v_cvt_pk_bf16_f32 v44, v44, v45
	v_cvt_pk_bf16_f32 v45, v46, v47
	v_cvt_pk_bf16_f32 v46, v40, v41
	v_add_u32_e32 v40, 0x90, v154
	global_store_dwordx4 v[108:109], v[104:107], off
	v_cvt_pk_bf16_f32 v88, v100, v101
	v_cvt_pk_bf16_f32 v89, v102, v103
	v_cvt_pk_bf16_f32 v90, v96, v97
	v_cvt_pk_bf16_f32 v91, v98, v99
	global_store_dwordx4 v[92:93], v[76:79], off offset:256
	v_cvt_pk_bf16_f32 v74, v80, v81
	v_cvt_pk_bf16_f32 v75, v82, v83
	v_lshl_add_u64 v[76:77], v[72:73], 1, v[150:151]
	v_cvt_pk_bf16_f32 v72, v84, v85
	v_cvt_pk_bf16_f32 v73, v86, v87
	v_cvt_pk_bf16_f32 v71, v66, v67
	v_lshl_add_u64 v[64:65], v[64:65], 1, v[150:151]
	v_cvt_pk_bf16_f32 v47, v42, v43
	v_mad_i64_i32 v[40:41], s[24:25], s38, v40, 0
	v_cvt_pk_bf16_f32 v28, v28, v29
	v_cvt_pk_bf16_f32 v29, v30, v31
	v_cvt_pk_bf16_f32 v30, v24, v25
	v_add_u32_e32 v24, 0xa0, v154
	global_store_dwordx4 v[92:93], v[88:91], off
	global_store_dwordx4 v[76:77], v[72:75], off
	global_store_dwordx4 v[76:77], v[68:71], off offset:256
	v_cvt_pk_bf16_f32 v60, v60, v61
	v_cvt_pk_bf16_f32 v61, v62, v63
	v_cvt_pk_bf16_f32 v62, v56, v57
	v_cvt_pk_bf16_f32 v63, v58, v59
	global_store_dwordx4 v[64:65], v[44:47], off offset:256
	v_cvt_pk_bf16_f32 v31, v26, v27
	v_mad_i64_i32 v[24:25], s[24:25], s38, v24, 0
	v_lshl_add_u64 v[44:45], v[40:41], 1, v[150:151]
	v_cvt_pk_bf16_f32 v12, v12, v13
	v_cvt_pk_bf16_f32 v13, v14, v15
	v_cvt_pk_bf16_f32 v14, v8, v9
	v_add_u32_e32 v8, 0xb0, v154
	global_store_dwordx4 v[64:65], v[60:63], off
	v_cvt_pk_bf16_f32 v40, v52, v53
	v_cvt_pk_bf16_f32 v41, v54, v55
	v_cvt_pk_bf16_f32 v42, v48, v49
	v_cvt_pk_bf16_f32 v43, v50, v51
	global_store_dwordx4 v[44:45], v[28:31], off offset:256
	v_cvt_pk_bf16_f32 v15, v10, v11
	v_mad_i64_i32 v[8:9], s[24:25], s38, v8, 0
	v_lshl_add_u64 v[28:29], v[24:25], 1, v[150:151]
	global_store_dwordx4 v[44:45], v[40:43], off
	v_cvt_pk_bf16_f32 v24, v36, v37
	v_cvt_pk_bf16_f32 v25, v38, v39
	v_cvt_pk_bf16_f32 v26, v32, v33
	v_cvt_pk_bf16_f32 v27, v34, v35
	global_store_dwordx4 v[28:29], v[12:15], off offset:256
	v_cvt_pk_bf16_f32 v10, v16, v17
	v_cvt_pk_bf16_f32 v11, v18, v19
	v_lshl_add_u64 v[12:13], v[8:9], 1, v[150:151]
	v_cvt_pk_bf16_f32 v8, v20, v21
	v_cvt_pk_bf16_f32 v9, v22, v23
	v_cvt_pk_bf16_f32 v4, v4, v5
	v_cvt_pk_bf16_f32 v5, v6, v7
	v_cvt_pk_bf16_f32 v6, v0, v1
	v_cvt_pk_bf16_f32 v7, v2, v3
	s_and_b64 vcc, exec, s[4:5]
	s_mov_b32 s75, s14
	s_mov_b32 s12, s16
	s_mov_b64 s[38:39], s[22:23]
	s_mov_b64 s[24:25], s[18:19]
	global_store_dwordx4 v[28:29], v[24:27], off
	global_store_dwordx4 v[12:13], v[8:11], off
	global_store_dwordx4 v[12:13], v[4:7], off offset:256
	s_cbranch_vccz .LBB0_208
	s_waitcnt vmcnt(0)
	s_cmpk_gt_u32 s42, 0xff
	s_cbranch_scc1 .LBB0_215
	s_barrier

; #define PG8_STAGE(bufoff, gbase, voff) do { _Pragma("unroll") for (int _i = 0; _i < 2; ++_i) \
;         __builtin_amdgcn_global_load_lds((const unsigned*)((const char*)(gbase) + (voff)[_i]), (LAS unsigned*)(lds + (bufoff) + ldsw + _i * 8192), 16, 0, 0); } while (0)
; #define PG8_LDA(dst, b, h) do { _Pragma("unroll") for (int m = 0; m < 4; ++m) _Pragma("unroll") for (int k = 0; k < 2; ++k) dst[m][k] = *(const LAS bf16x8*)(lds + PG8_SA(b, h) + aoff + m * 2048 + k * 1024); } while (0)
; #define PG8_LDB(dst, b, h) do { _Pragma("unroll") for (int n = 0; n < 2; ++n) _Pragma("unroll") for (int k = 0; k < 2; ++k) dst[n][k] = *(const LAS bf16x8*)(lds + PG8_SB(b, h) + boff + n * 2048 + k * 1024); } while (0)
; #define PG8_MMA(ai, bj, At, Bt) do { __builtin_amdgcn_s_setprio(1); _Pragma("unroll") for (int m = 0; m < 4; ++m) _Pragma("unroll") for (int n = 0; n < 2; ++n) _Pragma("unroll") for (int k = 0; k < 2; ++k) \
;         acc[ai][bj][m][n] = __builtin_amdgcn_mfma_f32_16x16x32_bf16(Bt[n][k], At[m][k], acc[ai][bj][m][n], 0, 0, 0); __builtin_amdgcn_s_setprio(0); } while (0)
; #define PG8_WAIT_V(n) asm volatile("s_waitcnt vmcnt(" #n ")" ::: "memory")
; #define PG8_WAIT_L(n) asm volatile("s_waitcnt lgkmcnt(" #n ")" ::: "memory")
; #define PG8_BAR __builtin_amdgcn_s_barrier()
; template <class Epi>
; DI void gemm_phase(LAS unsigned char* lds, const Gemm g, const StaticOrder& S, const Epi& E) {
;     ...
;         for (int t = 0; t < nt; t += 2) {
;             const bool last = (t == nt - 2);
;             const char* a1 = cA + (size_t)(t + 1) * kstep;
;             const char* a2 = last ? nA : cA + (size_t)(t + 2) * kstep; const char* b2 = last ? nB : cB + (size_t)(t + 2) * kstep;
;             const char* a3 = a2 + kstep; const char* b3 = b2 + kstep;
;             PG8_LDB(B0, 0, 0); PG8_SCHED; PG8_LDA(At, 0, 0); PG8_STAGE(PG8_SA(1, 1), a1 + hstep, voffA);
;             PG8_WAIT_L(8); PG8_BAR; PG8_WAIT_L(0); PG8_MMA(0, 0, At, B0); PG8_BAR; PG8_SCHED;
;             PG8_LDB(B1, 0, 1); PG8_STAGE(PG8_SB(0, 0), b2, voffB);
;             PG8_BAR; PG8_WAIT_L(0); PG8_MMA(0, 1, At, B1); PG8_BAR;
;             PG8_LDA(At, 0, 1); PG8_STAGE(PG8_SA(0, 0), a2, voffA);
;             PG8_BAR; PG8_WAIT_L(0); PG8_MMA(1, 0, At, B0); PG8_BAR; PG8_SCHED;
;             PG8_STAGE(PG8_SB(0, 1), b2 + hstep, voffB);
;             PG8_WAIT_V(6); PG8_BAR; PG8_MMA(1, 1, At, B1); PG8_BAR;
.LBB0_723:
	s_ashr_i32 s39, s38, 31
	v_cmp_lt_i64_e32 vcc, s[40:41], v[156:157]
	s_lshl_b64 s[40:41], s[38:39], 19
	s_add_u32 s40, s54, s40
	s_addc_u32 s41, s55, s41
	s_and_b64 s[42:43], vcc, exec
	s_cselect_b32 s39, s41, s47
	s_cselect_b32 s73, s40, s46
	s_ashr_i32 s25, s24, 31
	s_lshl_b64 s[42:43], s[24:25], 19
	s_add_u32 s42, s56, s42
	s_addc_u32 s43, s57, s43
	s_and_b64 s[50:51], vcc, exec
	s_cselect_b32 s25, s43, s49
	s_cselect_b32 s74, s42, s48
	s_add_u32 s46, s46, 0x40080
	s_addc_u32 s47, s47, 0
	s_add_u32 s75, s48, 0x100
	s_addc_u32 s76, s49, 0
	s_mov_b32 s77, -2
	v_add_u32_e32 v253, 0x18000, v163
	v_add_u32_e32 v252, 0x1c000, v163
	ds_read_b128 v[128:131], v165
	ds_read_b128 v[132:135], v165 offset:1024
	ds_read_b128 v[136:139], v165 offset:2048
	ds_read_b128 v[140:143], v165 offset:3072
	s_add_u32 s48, s46, 0xfffc0080
	s_addc_u32 s49, s47, -1
	s_cmp_eq_u32 s77, 12
	s_cselect_b32 s51, s39, s49
	s_cselect_b32 s50, s73, s48
	s_cselect_b32 s49, s25, s76
	s_cselect_b32 s48, s74, s75
	s_add_i32 m0, s45, 0xc000
	ds_read_b128 v[168:171], v166
	ds_read_b128 v[172:175], v166 offset:1024
	ds_read_b128 v[176:179], v166 offset:2048
	ds_read_b128 v[182:185], v166 offset:3072
	ds_read_b128 v[186:189], v166 offset:4096
	ds_read_b128 v[190:193], v166 offset:5120
	ds_read_b128 v[194:197], v166 offset:6144
	ds_read_b128 v[198:201], v166 offset:7168
	global_load_lds_dwordx4 v152, s[46:47]
	s_add_i32 m0, s45, 0xe000
	s_nop 0
	global_load_lds_dwordx4 v154, s[46:47]
	s_waitcnt lgkmcnt(8)
	s_barrier
	s_waitcnt lgkmcnt(7)
	v_mfma_f32_16x16x32_bf16 v[124:127], v[128:131], v[168:171], 0
	v_mfma_f32_16x16x32_bf16 v[120:123], v[136:139], v[168:171], 0
	s_waitcnt lgkmcnt(5)
	v_mfma_f32_16x16x32_bf16 v[108:111], v[128:131], v[176:179], 0
	v_mfma_f32_16x16x32_bf16 v[104:107], v[136:139], v[176:179], 0
	s_waitcnt lgkmcnt(3)
	v_mfma_f32_16x16x32_bf16 v[92:95], v[128:131], v[186:189], 0
	v_mfma_f32_16x16x32_bf16 v[88:91], v[136:139], v[186:189], 0
	s_waitcnt lgkmcnt(1)
	v_mfma_f32_16x16x32_bf16 v[76:79], v[128:131], v[194:197], 0
	v_mfma_f32_16x16x32_bf16 v[72:75], v[136:139], v[194:197], 0
	v_mfma_f32_16x16x32_bf16 v[124:127], v[132:135], v[172:175], v[124:127]
	v_mfma_f32_16x16x32_bf16 v[120:123], v[140:143], v[172:175], v[120:123]
	v_mfma_f32_16x16x32_bf16 v[108:111], v[132:135], v[182:185], v[108:111]
	v_mfma_f32_16x16x32_bf16 v[104:107], v[140:143], v[182:185], v[104:107]
	v_mfma_f32_16x16x32_bf16 v[92:95], v[132:135], v[190:193], v[92:95]
	v_mfma_f32_16x16x32_bf16 v[88:91], v[140:143], v[190:193], v[88:91]
	s_add_i32 s78, s70, s58
	s_add_u32 s86, s48, s12
	s_waitcnt lgkmcnt(0)
	v_mfma_f32_16x16x32_bf16 v[76:79], v[132:135], v[198:201], v[76:79]
	s_addc_u32 s87, s49, s13
	s_mov_b32 m0, s78
	v_mfma_f32_16x16x32_bf16 v[72:75], v[140:143], v[198:201], v[72:75]
	s_barrier
	ds_read_b128 v[202:205], v167
	ds_read_b128 v[206:209], v167 offset:1024
	ds_read_b128 v[210:213], v167 offset:2048
	ds_read_b128 v[214:217], v167 offset:3072
	global_load_lds_dwordx4 v146, s[48:49]
	s_add_i32 m0, s78, 0x2000
	s_nop 0
	global_load_lds_dwordx4 v150, s[48:49]
	s_barrier
	s_waitcnt lgkmcnt(3)
	v_mfma_f32_16x16x32_bf16 v[116:119], v[202:205], v[168:171], 0
	s_waitcnt lgkmcnt(1)
	v_mfma_f32_16x16x32_bf16 v[112:115], v[210:213], v[168:171], 0
	v_mfma_f32_16x16x32_bf16 v[100:103], v[202:205], v[176:179], 0
	v_mfma_f32_16x16x32_bf16 v[96:99], v[210:213], v[176:179], 0
	v_mfma_f32_16x16x32_bf16 v[84:87], v[202:205], v[186:189], 0
	v_mfma_f32_16x16x32_bf16 v[80:83], v[210:213], v[186:189], 0
	v_mfma_f32_16x16x32_bf16 v[68:71], v[202:205], v[194:197], 0
	v_mfma_f32_16x16x32_bf16 v[64:67], v[210:213], v[194:197], 0
	v_mfma_f32_16x16x32_bf16 v[116:119], v[206:209], v[172:175], v[116:119]
	s_waitcnt lgkmcnt(0)
	v_mfma_f32_16x16x32_bf16 v[112:115], v[214:217], v[172:175], v[112:115]
	v_mfma_f32_16x16x32_bf16 v[100:103], v[206:209], v[182:185], v[100:103]
	v_mfma_f32_16x16x32_bf16 v[96:99], v[214:217], v[182:185], v[96:99]
	v_mfma_f32_16x16x32_bf16 v[84:87], v[206:209], v[190:193], v[84:87]
	v_mfma_f32_16x16x32_bf16 v[80:83], v[214:217], v[190:193], v[80:83]
	s_mov_b32 m0, s45
	s_add_u32 s88, s50, s12
	v_mfma_f32_16x16x32_bf16 v[68:71], v[206:209], v[198:201], v[68:71]
	s_addc_u32 s89, s51, s13
	v_mfma_f32_16x16x32_bf16 v[64:67], v[214:217], v[198:201], v[64:67]
	s_barrier
	ds_read_b128 v[168:171], v166 offset:16384
	ds_read_b128 v[172:175], v166 offset:17408
	ds_read_b128 v[176:179], v166 offset:18432
	ds_read_b128 v[182:185], v166 offset:19456
	ds_read_b128 v[186:189], v166 offset:20480
	ds_read_b128 v[190:193], v166 offset:21504
	ds_read_b128 v[194:197], v166 offset:22528
	ds_read_b128 v[198:201], v166 offset:23552
	global_load_lds_dwordx4 v144, s[50:51]
	s_mov_b32 m0, s59
	s_nop 0
	global_load_lds_dwordx4 v148, s[50:51]
	s_barrier
	s_waitcnt lgkmcnt(7)
	v_mfma_f32_16x16x32_bf16 v[60:63], v[128:131], v[168:171], 0
	v_mfma_f32_16x16x32_bf16 v[56:59], v[136:139], v[168:171], 0
	s_waitcnt lgkmcnt(5)
	v_mfma_f32_16x16x32_bf16 v[44:47], v[128:131], v[176:179], 0
	v_mfma_f32_16x16x32_bf16 v[40:43], v[136:139], v[176:179], 0
	s_waitcnt lgkmcnt(3)
	v_mfma_f32_16x16x32_bf16 v[28:31], v[128:131], v[186:189], 0
	v_mfma_f32_16x16x32_bf16 v[24:27], v[136:139], v[186:189], 0
	s_waitcnt lgkmcnt(1)
	v_mfma_f32_16x16x32_bf16 v[12:15], v[128:131], v[194:197], 0
	v_mfma_f32_16x16x32_bf16 v[8:11], v[136:139], v[194:197], 0
	v_mfma_f32_16x16x32_bf16 v[60:63], v[132:135], v[172:175], v[60:63]
	v_mfma_f32_16x16x32_bf16 v[56:59], v[140:143], v[172:175], v[56:59]
	s_add_u32 s78, s48, 0x40000
	s_addc_u32 s79, s49, 0
	v_mfma_f32_16x16x32_bf16 v[44:47], v[132:135], v[182:185], v[44:47]
	s_add_i32 s80, s71, s58
	s_mov_b32 m0, s80
	v_mfma_f32_16x16x32_bf16 v[40:43], v[140:143], v[182:185], v[40:43]
	s_lshl_b32 s84, s44, 20
	s_lshl_b32 s85, s72, 10
	v_mfma_f32_16x16x32_bf16 v[28:31], v[132:135], v[190:193], v[28:31]
	s_add_u32 s84, s84, s85
	s_add_i32 s85, s77, 2
	v_mfma_f32_16x16x32_bf16 v[24:27], v[140:143], v[190:193], v[24:27]
	s_lshl_b32 s85, s85, 13
	s_add_u32 s84, s84, s85
	s_waitcnt lgkmcnt(0)
	v_mfma_f32_16x16x32_bf16 v[12:15], v[132:135], v[198:201], v[12:15]
	s_add_u32 s84, s36, s84
	s_addc_u32 s85, s37, 0
	v_mfma_f32_16x16x32_bf16 v[8:11], v[140:143], v[198:201], v[8:11]
	s_barrier
; #define PG8_STAGE(bufoff, gbase, voff) do { _Pragma("unroll") for (int _i = 0; _i < 2; ++_i) \
;         __builtin_amdgcn_global_load_lds((const unsigned*)((const char*)(gbase) + (voff)[_i]), (LAS unsigned*)(lds + (bufoff) + ldsw + _i * 8192), 16, 0, 0); } while (0)
; #define PG8_LDA(dst, b, h) do { _Pragma("unroll") for (int m = 0; m < 4; ++m) _Pragma("unroll") for (int k = 0; k < 2; ++k) dst[m][k] = *(const LAS bf16x8*)(lds + PG8_SA(b, h) + aoff + m * 2048 + k * 1024); } while (0)
; #define PG8_LDB(dst, b, h) do { _Pragma("unroll") for (int n = 0; n < 2; ++n) _Pragma("unroll") for (int k = 0; k < 2; ++k) dst[n][k] = *(const LAS bf16x8*)(lds + PG8_SB(b, h) + boff + n * 2048 + k * 1024); } while (0)
; #define PG8_MMA(ai, bj, At, Bt) do { __builtin_amdgcn_s_setprio(1); _Pragma("unroll") for (int m = 0; m < 4; ++m) _Pragma("unroll") for (int n = 0; n < 2; ++n) _Pragma("unroll") for (int k = 0; k < 2; ++k) \
;         acc[ai][bj][m][n] = __builtin_amdgcn_mfma_f32_16x16x32_bf16(Bt[n][k], At[m][k], acc[ai][bj][m][n], 0, 0, 0); __builtin_amdgcn_s_setprio(0); } while (0)
; #define PG8_WAIT_V(n) asm volatile("s_waitcnt vmcnt(" #n ")" ::: "memory")
; #define PG8_WAIT_L(n) asm volatile("s_waitcnt lgkmcnt(" #n ")" ::: "memory")
; #define PG8_BAR __builtin_amdgcn_s_barrier()
; #define PG8_SCHED __builtin_amdgcn_sched_barrier(0)
; template <class Epi>
; DI void gemm_phase(LAS unsigned char* lds, const Gemm g, const StaticOrder& S, const Epi& E) {
;     ...
;             PG8_WAIT_V(6); PG8_BAR; PG8_MMA(1, 1, At, B1); PG8_BAR;
;             PG8_LDB(B0, 1, 0); PG8_SCHED; PG8_LDA(At, 1, 0); PG8_STAGE(PG8_SA(0, 1), a2 + hstep, voffA);
;             PG8_WAIT_L(8); PG8_BAR; PG8_WAIT_L(0); PG8_MMA(0, 0, At, B0); PG8_BAR; PG8_SCHED;
;             PG8_LDB(B1, 1, 1); PG8_STAGE(PG8_SB(1, 0), b3, voffB);
;             PG8_BAR; PG8_WAIT_L(0); PG8_MMA(0, 1, At, B1); PG8_BAR;
;             PG8_LDA(At, 1, 1); PG8_STAGE(PG8_SA(1, 0), a3, voffA);
	global_load_lds_dwordx4 v146, s[78:79]
	s_add_i32 m0, s80, 0x2000
	s_nop 0
	global_load_lds_dwordx4 v150, s[78:79]
	s_waitcnt vmcnt(6)
	global_load_dword v249, v248, s[84:85]
	s_barrier
	v_mfma_f32_16x16x32_bf16 v[52:55], v[202:205], v[168:171], 0
	v_mfma_f32_16x16x32_bf16 v[48:51], v[210:213], v[168:171], 0
	v_mfma_f32_16x16x32_bf16 v[36:39], v[202:205], v[176:179], 0
	v_mfma_f32_16x16x32_bf16 v[32:35], v[210:213], v[176:179], 0
	v_mfma_f32_16x16x32_bf16 v[20:23], v[202:205], v[186:189], 0
	v_mfma_f32_16x16x32_bf16 v[16:19], v[210:213], v[186:189], 0
	v_mfma_f32_16x16x32_bf16 v[4:7], v[202:205], v[194:197], 0
	v_mfma_f32_16x16x32_bf16 v[0:3], v[210:213], v[194:197], 0
	v_mfma_f32_16x16x32_bf16 v[52:55], v[206:209], v[172:175], v[52:55]
	v_mfma_f32_16x16x32_bf16 v[48:51], v[214:217], v[172:175], v[48:51]
	v_mfma_f32_16x16x32_bf16 v[36:39], v[206:209], v[182:185], v[36:39]
	v_mfma_f32_16x16x32_bf16 v[32:35], v[214:217], v[182:185], v[32:35]
	v_mfma_f32_16x16x32_bf16 v[20:23], v[206:209], v[190:193], v[20:23]
	v_mfma_f32_16x16x32_bf16 v[16:19], v[214:217], v[190:193], v[16:19]
	v_mfma_f32_16x16x32_bf16 v[4:7], v[206:209], v[198:201], v[4:7]
	s_add_i32 s78, 0, 0x18000
	v_mfma_f32_16x16x32_bf16 v[0:3], v[214:217], v[198:201], v[0:3]
	s_barrier
	ds_read_b128 v[128:131], v253
	ds_read_b128 v[132:135], v253 offset:1024
	ds_read_b128 v[136:139], v253 offset:2048
	ds_read_b128 v[140:143], v253 offset:3072
	s_add_u32 s50, s50, 0x40000
	s_addc_u32 s51, s51, 0
	s_mov_b32 m0, s60
	ds_read_b128 v[168:171], v166 offset:32768
	ds_read_b128 v[172:175], v166 offset:33792
	ds_read_b128 v[176:179], v166 offset:34816
	ds_read_b128 v[182:185], v166 offset:35840
	ds_read_b128 v[186:189], v166 offset:36864
	ds_read_b128 v[190:193], v166 offset:37888
	ds_read_b128 v[194:197], v166 offset:38912
	ds_read_b128 v[198:201], v166 offset:39936
	global_load_lds_dwordx4 v144, s[50:51]
	s_mov_b32 m0, s61
	s_nop 0
	global_load_lds_dwordx4 v148, s[50:51]
	s_waitcnt lgkmcnt(8)
	s_barrier
	s_waitcnt lgkmcnt(7)
	v_mfma_f32_16x16x32_bf16 v[124:127], v[128:131], v[168:171], v[124:127]
	v_mfma_f32_16x16x32_bf16 v[120:123], v[136:139], v[168:171], v[120:123]
	s_waitcnt lgkmcnt(5)
	v_mfma_f32_16x16x32_bf16 v[108:111], v[128:131], v[176:179], v[108:111]
	v_mfma_f32_16x16x32_bf16 v[104:107], v[136:139], v[176:179], v[104:107]
	s_waitcnt lgkmcnt(3)
	v_mfma_f32_16x16x32_bf16 v[92:95], v[128:131], v[186:189], v[92:95]
	v_mfma_f32_16x16x32_bf16 v[88:91], v[136:139], v[186:189], v[88:91]
	s_waitcnt lgkmcnt(1)
	v_mfma_f32_16x16x32_bf16 v[76:79], v[128:131], v[194:197], v[76:79]
	v_mfma_f32_16x16x32_bf16 v[72:75], v[136:139], v[194:197], v[72:75]
	v_mfma_f32_16x16x32_bf16 v[124:127], v[132:135], v[172:175], v[124:127]
	v_mfma_f32_16x16x32_bf16 v[120:123], v[140:143], v[172:175], v[120:123]
	v_mfma_f32_16x16x32_bf16 v[108:111], v[132:135], v[182:185], v[108:111]
	v_mfma_f32_16x16x32_bf16 v[104:107], v[140:143], v[182:185], v[104:107]
	v_mfma_f32_16x16x32_bf16 v[92:95], v[132:135], v[190:193], v[92:95]
	v_mfma_f32_16x16x32_bf16 v[88:91], v[140:143], v[190:193], v[88:91]
	s_add_i32 s50, 0, 0x1c000
	s_add_i32 s51, s78, s58
	s_waitcnt lgkmcnt(0)
	v_mfma_f32_16x16x32_bf16 v[76:79], v[132:135], v[198:201], v[76:79]
	s_mov_b32 m0, s51
	v_mfma_f32_16x16x32_bf16 v[72:75], v[140:143], v[198:201], v[72:75]
	s_barrier
	ds_read_b128 v[202:205], v252
	ds_read_b128 v[206:209], v252 offset:1024
	ds_read_b128 v[210:213], v252 offset:2048
	ds_read_b128 v[214:217], v252 offset:3072
	global_load_lds_dwordx4 v146, s[86:87]
	s_add_i32 m0, s51, 0x2000
	s_nop 0
	global_load_lds_dwordx4 v150, s[86:87]
	s_barrier
	s_waitcnt lgkmcnt(3)
	v_mfma_f32_16x16x32_bf16 v[116:119], v[202:205], v[168:171], v[116:119]
	s_waitcnt lgkmcnt(1)
	v_mfma_f32_16x16x32_bf16 v[112:115], v[210:213], v[168:171], v[112:115]
	v_mfma_f32_16x16x32_bf16 v[100:103], v[202:205], v[176:179], v[100:103]
	v_mfma_f32_16x16x32_bf16 v[96:99], v[210:213], v[176:179], v[96:99]
	v_mfma_f32_16x16x32_bf16 v[84:87], v[202:205], v[186:189], v[84:87]
	v_mfma_f32_16x16x32_bf16 v[80:83], v[210:213], v[186:189], v[80:83]
	v_mfma_f32_16x16x32_bf16 v[68:71], v[202:205], v[194:197], v[68:71]
	v_mfma_f32_16x16x32_bf16 v[64:67], v[210:213], v[194:197], v[64:67]
	v_mfma_f32_16x16x32_bf16 v[116:119], v[206:209], v[172:175], v[116:119]
	s_waitcnt lgkmcnt(0)
	v_mfma_f32_16x16x32_bf16 v[112:115], v[214:217], v[172:175], v[112:115]
	v_mfma_f32_16x16x32_bf16 v[100:103], v[206:209], v[182:185], v[100:103]
	v_mfma_f32_16x16x32_bf16 v[96:99], v[214:217], v[182:185], v[96:99]
	v_mfma_f32_16x16x32_bf16 v[84:87], v[206:209], v[190:193], v[84:87]
	v_mfma_f32_16x16x32_bf16 v[80:83], v[214:217], v[190:193], v[80:83]
	v_mfma_f32_16x16x32_bf16 v[68:71], v[206:209], v[198:201], v[68:71]
	s_mov_b32 m0, s65
	v_mfma_f32_16x16x32_bf16 v[64:67], v[214:217], v[198:201], v[64:67]
	s_barrier
	ds_read_b128 v[168:171], v166 offset:49152
	ds_read_b128 v[172:175], v166 offset:50176
	ds_read_b128 v[176:179], v166 offset:51200
	ds_read_b128 v[182:185], v166 offset:52224
	ds_read_b128 v[186:189], v166 offset:53248
	ds_read_b128 v[190:193], v166 offset:54272
	ds_read_b128 v[194:197], v166 offset:55296
	ds_read_b128 v[198:201], v166 offset:56320
	global_load_lds_dwordx4 v144, s[88:89]
	s_mov_b32 m0, s66
	s_nop 0
	global_load_lds_dwordx4 v148, s[88:89]
	s_barrier
; #define PG8_STAGE(bufoff, gbase, voff) do { _Pragma("unroll") for (int _i = 0; _i < 2; ++_i) \
;         __builtin_amdgcn_global_load_lds((const unsigned*)((const char*)(gbase) + (voff)[_i]), (LAS unsigned*)(lds + (bufoff) + ldsw + _i * 8192), 16, 0, 0); } while (0)
; #define PG8_LDA(dst, b, h) do { _Pragma("unroll") for (int m = 0; m < 4; ++m) _Pragma("unroll") for (int k = 0; k < 2; ++k) dst[m][k] = *(const LAS bf16x8*)(lds + PG8_SA(b, h) + aoff + m * 2048 + k * 1024); } while (0)
; #define PG8_LDB(dst, b, h) do { _Pragma("unroll") for (int n = 0; n < 2; ++n) _Pragma("unroll") for (int k = 0; k < 2; ++k) dst[n][k] = *(const LAS bf16x8*)(lds + PG8_SB(b, h) + boff + n * 2048 + k * 1024); } while (0)
; #define PG8_MMA(ai, bj, At, Bt) do { __builtin_amdgcn_s_setprio(1); _Pragma("unroll") for (int m = 0; m < 4; ++m) _Pragma("unroll") for (int n = 0; n < 2; ++n) _Pragma("unroll") for (int k = 0; k < 2; ++k) \
;         acc[ai][bj][m][n] = __builtin_amdgcn_mfma_f32_16x16x32_bf16(Bt[n][k], At[m][k], acc[ai][bj][m][n], 0, 0, 0); __builtin_amdgcn_s_setprio(0); } while (0)
; #define PG8_WAIT_V(n) asm volatile("s_waitcnt vmcnt(" #n ")" ::: "memory")
; #define PG8_WAIT_L(n) asm volatile("s_waitcnt lgkmcnt(" #n ")" ::: "memory")
; #define PG8_BAR __builtin_amdgcn_s_barrier()
; #define PG8_SCHED __builtin_amdgcn_sched_barrier(0)
; template <class Epi>
; DI void gemm_phase(LAS unsigned char* lds, const Gemm g, const StaticOrder& S, const Epi& E) {
;     ...
;         for (int t = 0; t < nt; t += 2) {
;             const bool last = (t == nt - 2);
;             const char* a1 = cA + (size_t)(t + 1) * kstep;
;             const char* a2 = last ? nA : cA + (size_t)(t + 2) * kstep; const char* b2 = last ? nB : cB + (size_t)(t + 2) * kstep;
;             const char* a3 = a2 + kstep; const char* b3 = b2 + kstep;
;             PG8_LDB(B0, 0, 0); PG8_SCHED; PG8_LDA(At, 0, 0); PG8_STAGE(PG8_SA(1, 1), a1 + hstep, voffA);
;             PG8_WAIT_L(8); PG8_BAR; PG8_WAIT_L(0); PG8_MMA(0, 0, At, B0); PG8_BAR; PG8_SCHED;
;             PG8_LDB(B1, 0, 1); PG8_STAGE(PG8_SB(0, 0), b2, voffB);
;     ...
;             PG8_BAR; PG8_WAIT_L(0); PG8_MMA(1, 0, At, B0); PG8_BAR; PG8_SCHED;
;             PG8_STAGE(PG8_SB(1, 1), b3 + hstep, voffB);
;             PG8_WAIT_V(6); PG8_BAR; PG8_MMA(1, 1, At, B1); PG8_BAR;
	s_waitcnt lgkmcnt(7)
	v_mfma_f32_16x16x32_bf16 v[60:63], v[128:131], v[168:171], v[60:63]
	v_mfma_f32_16x16x32_bf16 v[56:59], v[136:139], v[168:171], v[56:59]
	s_waitcnt lgkmcnt(5)
	v_mfma_f32_16x16x32_bf16 v[44:47], v[128:131], v[176:179], v[44:47]
	v_mfma_f32_16x16x32_bf16 v[40:43], v[136:139], v[176:179], v[40:43]
	s_waitcnt lgkmcnt(3)
	v_mfma_f32_16x16x32_bf16 v[28:31], v[128:131], v[186:189], v[28:31]
	v_mfma_f32_16x16x32_bf16 v[24:27], v[136:139], v[186:189], v[24:27]
	s_waitcnt lgkmcnt(1)
	v_mfma_f32_16x16x32_bf16 v[12:15], v[128:131], v[194:197], v[12:15]
	v_mfma_f32_16x16x32_bf16 v[8:11], v[136:139], v[194:197], v[8:11]
	v_mfma_f32_16x16x32_bf16 v[60:63], v[132:135], v[172:175], v[60:63]
	v_mfma_f32_16x16x32_bf16 v[56:59], v[140:143], v[172:175], v[56:59]
	v_mfma_f32_16x16x32_bf16 v[44:47], v[132:135], v[182:185], v[44:47]
	v_mfma_f32_16x16x32_bf16 v[40:43], v[140:143], v[182:185], v[40:43]
	v_mfma_f32_16x16x32_bf16 v[28:31], v[132:135], v[190:193], v[28:31]
	v_mfma_f32_16x16x32_bf16 v[24:27], v[140:143], v[190:193], v[24:27]
	s_add_u32 s48, s48, 0x40080
	s_addc_u32 s49, s49, 0
	s_waitcnt lgkmcnt(0)
	v_mfma_f32_16x16x32_bf16 v[12:15], v[132:135], v[198:201], v[12:15]
	s_add_i32 s50, s50, s58
	s_mov_b32 m0, s50
	v_mfma_f32_16x16x32_bf16 v[8:11], v[140:143], v[198:201], v[8:11]
	s_barrier
	global_load_lds_dwordx4 v146, s[48:49]
	s_add_i32 m0, s50, 0x2000
	s_nop 0
	global_load_lds_dwordx4 v150, s[48:49]
	s_waitcnt vmcnt(6)
	s_barrier
	v_mfma_f32_16x16x32_bf16 v[52:55], v[202:205], v[168:171], v[52:55]
	v_mfma_f32_16x16x32_bf16 v[48:51], v[210:213], v[168:171], v[48:51]
	v_mfma_f32_16x16x32_bf16 v[36:39], v[202:205], v[176:179], v[36:39]
	v_mfma_f32_16x16x32_bf16 v[32:35], v[210:213], v[176:179], v[32:35]
	v_mfma_f32_16x16x32_bf16 v[20:23], v[202:205], v[186:189], v[20:23]
	v_mfma_f32_16x16x32_bf16 v[16:19], v[210:213], v[186:189], v[16:19]
	v_mfma_f32_16x16x32_bf16 v[4:7], v[202:205], v[194:197], v[4:7]
	v_mfma_f32_16x16x32_bf16 v[0:3], v[210:213], v[194:197], v[0:3]
	v_mfma_f32_16x16x32_bf16 v[52:55], v[206:209], v[172:175], v[52:55]
	s_add_i32 s77, s77, 2
	s_add_u32 s46, s46, 0x100
	v_mfma_f32_16x16x32_bf16 v[48:51], v[214:217], v[172:175], v[48:51]
	s_addc_u32 s47, s47, 0
	s_add_u32 s75, s75, 0x100
	v_mfma_f32_16x16x32_bf16 v[36:39], v[206:209], v[182:185], v[36:39]
	s_addc_u32 s76, s76, 0
	s_add_u32 s48, s46, 0xfffc0080
	v_mfma_f32_16x16x32_bf16 v[32:35], v[214:217], v[182:185], v[32:35]
	s_addc_u32 s49, s47, -1
	s_cmp_eq_u32 s77, 12
	v_mfma_f32_16x16x32_bf16 v[20:23], v[206:209], v[190:193], v[20:23]
	s_cselect_b32 s51, s39, s49
	s_cselect_b32 s50, s73, s48
	v_mfma_f32_16x16x32_bf16 v[16:19], v[214:217], v[190:193], v[16:19]
	s_cselect_b32 s49, s25, s76
	s_cselect_b32 s48, s74, s75
	v_mfma_f32_16x16x32_bf16 v[4:7], v[206:209], v[198:201], v[4:7]
	s_add_i32 m0, s45, 0xc000
	v_mfma_f32_16x16x32_bf16 v[0:3], v[214:217], v[198:201], v[0:3]
	s_cmp_gt_u32 s77, 13
	s_barrier
.LBB0_724:
	ds_read_b128 v[128:131], v165
	ds_read_b128 v[132:135], v165 offset:1024
	ds_read_b128 v[136:139], v165 offset:2048
	ds_read_b128 v[140:143], v165 offset:3072
	ds_read_b128 v[168:171], v166
	ds_read_b128 v[172:175], v166 offset:1024
	ds_read_b128 v[176:179], v166 offset:2048
	ds_read_b128 v[182:185], v166 offset:3072
	ds_read_b128 v[186:189], v166 offset:4096
	ds_read_b128 v[190:193], v166 offset:5120
	ds_read_b128 v[194:197], v166 offset:6144
	ds_read_b128 v[198:201], v166 offset:7168
	global_load_lds_dwordx4 v152, s[46:47]
	s_add_i32 m0, s45, 0xe000
	s_nop 0
	global_load_lds_dwordx4 v154, s[46:47]
	s_waitcnt lgkmcnt(8)
	s_barrier
	s_waitcnt lgkmcnt(7)
	v_mfma_f32_16x16x32_bf16 v[124:127], v[128:131], v[168:171], v[124:127]
	v_mfma_f32_16x16x32_bf16 v[120:123], v[136:139], v[168:171], v[120:123]
	s_waitcnt lgkmcnt(5)
	v_mfma_f32_16x16x32_bf16 v[108:111], v[128:131], v[176:179], v[108:111]
	v_mfma_f32_16x16x32_bf16 v[104:107], v[136:139], v[176:179], v[104:107]
	s_waitcnt lgkmcnt(3)
	v_mfma_f32_16x16x32_bf16 v[92:95], v[128:131], v[186:189], v[92:95]
	v_mfma_f32_16x16x32_bf16 v[88:91], v[136:139], v[186:189], v[88:91]
	s_waitcnt lgkmcnt(1)
	v_mfma_f32_16x16x32_bf16 v[76:79], v[128:131], v[194:197], v[76:79]
	v_mfma_f32_16x16x32_bf16 v[72:75], v[136:139], v[194:197], v[72:75]
	v_mfma_f32_16x16x32_bf16 v[124:127], v[132:135], v[172:175], v[124:127]
	v_mfma_f32_16x16x32_bf16 v[120:123], v[140:143], v[172:175], v[120:123]
	v_mfma_f32_16x16x32_bf16 v[108:111], v[132:135], v[182:185], v[108:111]
	v_mfma_f32_16x16x32_bf16 v[104:107], v[140:143], v[182:185], v[104:107]
	v_mfma_f32_16x16x32_bf16 v[92:95], v[132:135], v[190:193], v[92:95]
	v_mfma_f32_16x16x32_bf16 v[88:91], v[140:143], v[190:193], v[88:91]
	s_add_i32 s78, s70, s58
	s_add_u32 s86, s48, s12
	s_waitcnt lgkmcnt(0)
	v_mfma_f32_16x16x32_bf16 v[76:79], v[132:135], v[198:201], v[76:79]
	s_addc_u32 s87, s49, s13
	s_mov_b32 m0, s78
	v_mfma_f32_16x16x32_bf16 v[72:75], v[140:143], v[198:201], v[72:75]
	s_barrier
	ds_read_b128 v[202:205], v167
	ds_read_b128 v[206:209], v167 offset:1024
	ds_read_b128 v[210:213], v167 offset:2048
	ds_read_b128 v[214:217], v167 offset:3072
	global_load_lds_dwordx4 v146, s[48:49]
	s_add_i32 m0, s78, 0x2000
	s_nop 0
	global_load_lds_dwordx4 v150, s[48:49]
	s_barrier
; #define PG8_STAGE(bufoff, gbase, voff) do { _Pragma("unroll") for (int _i = 0; _i < 2; ++_i) \
;         __builtin_amdgcn_global_load_lds((const unsigned*)((const char*)(gbase) + (voff)[_i]), (LAS unsigned*)(lds + (bufoff) + ldsw + _i * 8192), 16, 0, 0); } while (0)
; #define PG8_LDA(dst, b, h) do { _Pragma("unroll") for (int m = 0; m < 4; ++m) _Pragma("unroll") for (int k = 0; k < 2; ++k) dst[m][k] = *(const LAS bf16x8*)(lds + PG8_SA(b, h) + aoff + m * 2048 + k * 1024); } while (0)
; #define PG8_LDB(dst, b, h) do { _Pragma("unroll") for (int n = 0; n < 2; ++n) _Pragma("unroll") for (int k = 0; k < 2; ++k) dst[n][k] = *(const LAS bf16x8*)(lds + PG8_SB(b, h) + boff + n * 2048 + k * 1024); } while (0)
; #define PG8_MMA(ai, bj, At, Bt) do { __builtin_amdgcn_s_setprio(1); _Pragma("unroll") for (int m = 0; m < 4; ++m) _Pragma("unroll") for (int n = 0; n < 2; ++n) _Pragma("unroll") for (int k = 0; k < 2; ++k) \
;         acc[ai][bj][m][n] = __builtin_amdgcn_mfma_f32_16x16x32_bf16(Bt[n][k], At[m][k], acc[ai][bj][m][n], 0, 0, 0); __builtin_amdgcn_s_setprio(0); } while (0)
; #define PG8_WAIT_V(n) asm volatile("s_waitcnt vmcnt(" #n ")" ::: "memory")
; #define PG8_WAIT_L(n) asm volatile("s_waitcnt lgkmcnt(" #n ")" ::: "memory")
; #define PG8_BAR __builtin_amdgcn_s_barrier()
; #define PG8_SCHED __builtin_amdgcn_sched_barrier(0)
; template <class Epi>
; DI void gemm_phase(LAS unsigned char* lds, const Gemm g, const StaticOrder& S, const Epi& E) {
;     ...
;             PG8_BAR; PG8_WAIT_L(0); PG8_MMA(0, 1, At, B1); PG8_BAR;
;             PG8_LDA(At, 0, 1); PG8_STAGE(PG8_SA(0, 0), a2, voffA);
;             PG8_BAR; PG8_WAIT_L(0); PG8_MMA(1, 0, At, B0); PG8_BAR; PG8_SCHED;
;             PG8_STAGE(PG8_SB(0, 1), b2 + hstep, voffB);
;             PG8_WAIT_V(6); PG8_BAR; PG8_MMA(1, 1, At, B1); PG8_BAR;
;             PG8_LDB(B0, 1, 0); PG8_SCHED; PG8_LDA(At, 1, 0); PG8_STAGE(PG8_SA(0, 1), a2 + hstep, voffA);
;             PG8_WAIT_L(8); PG8_BAR; PG8_WAIT_L(0); PG8_MMA(0, 0, At, B0); PG8_BAR; PG8_SCHED;
;             PG8_LDB(B1, 1, 1); PG8_STAGE(PG8_SB(1, 0), b3, voffB);
	s_waitcnt lgkmcnt(3)
	v_mfma_f32_16x16x32_bf16 v[116:119], v[202:205], v[168:171], v[116:119]
	s_waitcnt lgkmcnt(1)
	v_mfma_f32_16x16x32_bf16 v[112:115], v[210:213], v[168:171], v[112:115]
	v_mfma_f32_16x16x32_bf16 v[100:103], v[202:205], v[176:179], v[100:103]
	v_mfma_f32_16x16x32_bf16 v[96:99], v[210:213], v[176:179], v[96:99]
	v_mfma_f32_16x16x32_bf16 v[84:87], v[202:205], v[186:189], v[84:87]
	v_mfma_f32_16x16x32_bf16 v[80:83], v[210:213], v[186:189], v[80:83]
	v_mfma_f32_16x16x32_bf16 v[68:71], v[202:205], v[194:197], v[68:71]
	v_mfma_f32_16x16x32_bf16 v[64:67], v[210:213], v[194:197], v[64:67]
	v_mfma_f32_16x16x32_bf16 v[116:119], v[206:209], v[172:175], v[116:119]
	s_waitcnt lgkmcnt(0)
	v_mfma_f32_16x16x32_bf16 v[112:115], v[214:217], v[172:175], v[112:115]
	v_mfma_f32_16x16x32_bf16 v[100:103], v[206:209], v[182:185], v[100:103]
	v_mfma_f32_16x16x32_bf16 v[96:99], v[214:217], v[182:185], v[96:99]
	v_mfma_f32_16x16x32_bf16 v[84:87], v[206:209], v[190:193], v[84:87]
	v_mfma_f32_16x16x32_bf16 v[80:83], v[214:217], v[190:193], v[80:83]
	s_mov_b32 m0, s45
	s_add_u32 s88, s50, s12
	v_mfma_f32_16x16x32_bf16 v[68:71], v[206:209], v[198:201], v[68:71]
	s_addc_u32 s89, s51, s13
	v_mfma_f32_16x16x32_bf16 v[64:67], v[214:217], v[198:201], v[64:67]
	s_barrier
	ds_read_b128 v[168:171], v166 offset:16384
	ds_read_b128 v[172:175], v166 offset:17408
	ds_read_b128 v[176:179], v166 offset:18432
	ds_read_b128 v[182:185], v166 offset:19456
	ds_read_b128 v[186:189], v166 offset:20480
	ds_read_b128 v[190:193], v166 offset:21504
	ds_read_b128 v[194:197], v166 offset:22528
	ds_read_b128 v[198:201], v166 offset:23552
	global_load_lds_dwordx4 v144, s[50:51]
	s_mov_b32 m0, s59
	s_nop 0
	global_load_lds_dwordx4 v148, s[50:51]
	s_barrier
	s_waitcnt lgkmcnt(7)
	v_mfma_f32_16x16x32_bf16 v[60:63], v[128:131], v[168:171], v[60:63]
	v_mfma_f32_16x16x32_bf16 v[56:59], v[136:139], v[168:171], v[56:59]
	s_waitcnt lgkmcnt(5)
	v_mfma_f32_16x16x32_bf16 v[44:47], v[128:131], v[176:179], v[44:47]
	v_mfma_f32_16x16x32_bf16 v[40:43], v[136:139], v[176:179], v[40:43]
	s_waitcnt lgkmcnt(3)
	v_mfma_f32_16x16x32_bf16 v[28:31], v[128:131], v[186:189], v[28:31]
	v_mfma_f32_16x16x32_bf16 v[24:27], v[136:139], v[186:189], v[24:27]
	s_waitcnt lgkmcnt(1)
	v_mfma_f32_16x16x32_bf16 v[12:15], v[128:131], v[194:197], v[12:15]
	v_mfma_f32_16x16x32_bf16 v[8:11], v[136:139], v[194:197], v[8:11]
	v_mfma_f32_16x16x32_bf16 v[60:63], v[132:135], v[172:175], v[60:63]
	v_mfma_f32_16x16x32_bf16 v[56:59], v[140:143], v[172:175], v[56:59]
	s_add_u32 s78, s48, 0x40000
	s_addc_u32 s79, s49, 0
	v_mfma_f32_16x16x32_bf16 v[44:47], v[132:135], v[182:185], v[44:47]
	s_add_i32 s80, s71, s58
	s_mov_b32 m0, s80
	v_mfma_f32_16x16x32_bf16 v[40:43], v[140:143], v[182:185], v[40:43]
	s_lshl_b32 s84, s44, 20
	s_lshl_b32 s85, s72, 10
	v_mfma_f32_16x16x32_bf16 v[28:31], v[132:135], v[190:193], v[28:31]
	s_add_u32 s84, s84, s85
	s_add_i32 s85, s77, 2
	v_mfma_f32_16x16x32_bf16 v[24:27], v[140:143], v[190:193], v[24:27]
	s_lshl_b32 s85, s85, 13
	s_add_u32 s84, s84, s85
	s_waitcnt lgkmcnt(0)
	v_mfma_f32_16x16x32_bf16 v[12:15], v[132:135], v[198:201], v[12:15]
	s_add_u32 s84, s36, s84
	s_addc_u32 s85, s37, 0
	v_mfma_f32_16x16x32_bf16 v[8:11], v[140:143], v[198:201], v[8:11]
	s_barrier
	global_load_lds_dwordx4 v146, s[78:79]
	s_add_i32 m0, s80, 0x2000
	s_nop 0
	global_load_lds_dwordx4 v150, s[78:79]
	s_waitcnt vmcnt(6)
	global_load_dword v249, v248, s[84:85]
	s_barrier
	v_mfma_f32_16x16x32_bf16 v[52:55], v[202:205], v[168:171], v[52:55]
	v_mfma_f32_16x16x32_bf16 v[48:51], v[210:213], v[168:171], v[48:51]
	v_mfma_f32_16x16x32_bf16 v[36:39], v[202:205], v[176:179], v[36:39]
	v_mfma_f32_16x16x32_bf16 v[32:35], v[210:213], v[176:179], v[32:35]
	v_mfma_f32_16x16x32_bf16 v[20:23], v[202:205], v[186:189], v[20:23]
	v_mfma_f32_16x16x32_bf16 v[16:19], v[210:213], v[186:189], v[16:19]
	v_mfma_f32_16x16x32_bf16 v[4:7], v[202:205], v[194:197], v[4:7]
	v_mfma_f32_16x16x32_bf16 v[0:3], v[210:213], v[194:197], v[0:3]
	v_mfma_f32_16x16x32_bf16 v[52:55], v[206:209], v[172:175], v[52:55]
	v_mfma_f32_16x16x32_bf16 v[48:51], v[214:217], v[172:175], v[48:51]
	v_mfma_f32_16x16x32_bf16 v[36:39], v[206:209], v[182:185], v[36:39]
	v_mfma_f32_16x16x32_bf16 v[32:35], v[214:217], v[182:185], v[32:35]
	v_mfma_f32_16x16x32_bf16 v[20:23], v[206:209], v[190:193], v[20:23]
	v_mfma_f32_16x16x32_bf16 v[16:19], v[214:217], v[190:193], v[16:19]
	v_mfma_f32_16x16x32_bf16 v[4:7], v[206:209], v[198:201], v[4:7]
	s_add_i32 s78, 0, 0x18000
	v_mfma_f32_16x16x32_bf16 v[0:3], v[214:217], v[198:201], v[0:3]
	s_barrier
	ds_read_b128 v[128:131], v253
	ds_read_b128 v[132:135], v253 offset:1024
	ds_read_b128 v[136:139], v253 offset:2048
	ds_read_b128 v[140:143], v253 offset:3072
	s_add_u32 s50, s50, 0x40000
	s_addc_u32 s51, s51, 0
	s_mov_b32 m0, s60
	ds_read_b128 v[168:171], v166 offset:32768
	ds_read_b128 v[172:175], v166 offset:33792
	ds_read_b128 v[176:179], v166 offset:34816
	ds_read_b128 v[182:185], v166 offset:35840
	ds_read_b128 v[186:189], v166 offset:36864
	ds_read_b128 v[190:193], v166 offset:37888
	ds_read_b128 v[194:197], v166 offset:38912
	ds_read_b128 v[198:201], v166 offset:39936
	global_load_lds_dwordx4 v144, s[50:51]
	s_mov_b32 m0, s61
	s_nop 0
	global_load_lds_dwordx4 v148, s[50:51]
	s_waitcnt lgkmcnt(8)
	s_barrier
; #define PG8_STAGE(bufoff, gbase, voff) do { _Pragma("unroll") for (int _i = 0; _i < 2; ++_i) \
;         __builtin_amdgcn_global_load_lds((const unsigned*)((const char*)(gbase) + (voff)[_i]), (LAS unsigned*)(lds + (bufoff) + ldsw + _i * 8192), 16, 0, 0); } while (0)
; #define PG8_LDA(dst, b, h) do { _Pragma("unroll") for (int m = 0; m < 4; ++m) _Pragma("unroll") for (int k = 0; k < 2; ++k) dst[m][k] = *(const LAS bf16x8*)(lds + PG8_SA(b, h) + aoff + m * 2048 + k * 1024); } while (0)
; #define PG8_LDB(dst, b, h) do { _Pragma("unroll") for (int n = 0; n < 2; ++n) _Pragma("unroll") for (int k = 0; k < 2; ++k) dst[n][k] = *(const LAS bf16x8*)(lds + PG8_SB(b, h) + boff + n * 2048 + k * 1024); } while (0)
; #define PG8_MMA(ai, bj, At, Bt) do { __builtin_amdgcn_s_setprio(1); _Pragma("unroll") for (int m = 0; m < 4; ++m) _Pragma("unroll") for (int n = 0; n < 2; ++n) _Pragma("unroll") for (int k = 0; k < 2; ++k) \
;         acc[ai][bj][m][n] = __builtin_amdgcn_mfma_f32_16x16x32_bf16(Bt[n][k], At[m][k], acc[ai][bj][m][n], 0, 0, 0); __builtin_amdgcn_s_setprio(0); } while (0)
; #define PG8_WAIT_V(n) asm volatile("s_waitcnt vmcnt(" #n ")" ::: "memory")
; #define PG8_WAIT_L(n) asm volatile("s_waitcnt lgkmcnt(" #n ")" ::: "memory")
; #define PG8_BAR __builtin_amdgcn_s_barrier()
; #define PG8_SCHED __builtin_amdgcn_sched_barrier(0)
; template <class Epi>
; DI void gemm_phase(LAS unsigned char* lds, const Gemm g, const StaticOrder& S, const Epi& E) {
;     ...
;             PG8_WAIT_L(8); PG8_BAR; PG8_WAIT_L(0); PG8_MMA(0, 0, At, B0); PG8_BAR; PG8_SCHED;
;             PG8_LDB(B1, 1, 1); PG8_STAGE(PG8_SB(1, 0), b3, voffB);
;             PG8_BAR; PG8_WAIT_L(0); PG8_MMA(0, 1, At, B1); PG8_BAR;
;             PG8_LDA(At, 1, 1); PG8_STAGE(PG8_SA(1, 0), a3, voffA);
;             PG8_BAR; PG8_WAIT_L(0); PG8_MMA(1, 0, At, B0); PG8_BAR; PG8_SCHED;
;             PG8_STAGE(PG8_SB(1, 1), b3 + hstep, voffB);
;             PG8_WAIT_V(6); PG8_BAR; PG8_MMA(1, 1, At, B1); PG8_BAR;
	s_waitcnt lgkmcnt(7)
	v_mfma_f32_16x16x32_bf16 v[124:127], v[128:131], v[168:171], v[124:127]
	v_mfma_f32_16x16x32_bf16 v[120:123], v[136:139], v[168:171], v[120:123]
	s_waitcnt lgkmcnt(5)
	v_mfma_f32_16x16x32_bf16 v[108:111], v[128:131], v[176:179], v[108:111]
	v_mfma_f32_16x16x32_bf16 v[104:107], v[136:139], v[176:179], v[104:107]
	s_waitcnt lgkmcnt(3)
	v_mfma_f32_16x16x32_bf16 v[92:95], v[128:131], v[186:189], v[92:95]
	v_mfma_f32_16x16x32_bf16 v[88:91], v[136:139], v[186:189], v[88:91]
	s_waitcnt lgkmcnt(1)
	v_mfma_f32_16x16x32_bf16 v[76:79], v[128:131], v[194:197], v[76:79]
	v_mfma_f32_16x16x32_bf16 v[72:75], v[136:139], v[194:197], v[72:75]
	v_mfma_f32_16x16x32_bf16 v[124:127], v[132:135], v[172:175], v[124:127]
	v_mfma_f32_16x16x32_bf16 v[120:123], v[140:143], v[172:175], v[120:123]
	v_mfma_f32_16x16x32_bf16 v[108:111], v[132:135], v[182:185], v[108:111]
	v_mfma_f32_16x16x32_bf16 v[104:107], v[140:143], v[182:185], v[104:107]
	v_mfma_f32_16x16x32_bf16 v[92:95], v[132:135], v[190:193], v[92:95]
	v_mfma_f32_16x16x32_bf16 v[88:91], v[140:143], v[190:193], v[88:91]
	s_add_i32 s50, 0, 0x1c000
	s_add_i32 s51, s78, s58
	s_waitcnt lgkmcnt(0)
	v_mfma_f32_16x16x32_bf16 v[76:79], v[132:135], v[198:201], v[76:79]
	s_mov_b32 m0, s51
	v_mfma_f32_16x16x32_bf16 v[72:75], v[140:143], v[198:201], v[72:75]
	s_barrier
	ds_read_b128 v[202:205], v252
	ds_read_b128 v[206:209], v252 offset:1024
	ds_read_b128 v[210:213], v252 offset:2048
	ds_read_b128 v[214:217], v252 offset:3072
	global_load_lds_dwordx4 v146, s[86:87]
	s_add_i32 m0, s51, 0x2000
	s_nop 0
	global_load_lds_dwordx4 v150, s[86:87]
	s_barrier
	s_waitcnt lgkmcnt(3)
	v_mfma_f32_16x16x32_bf16 v[116:119], v[202:205], v[168:171], v[116:119]
	s_waitcnt lgkmcnt(1)
	v_mfma_f32_16x16x32_bf16 v[112:115], v[210:213], v[168:171], v[112:115]
	v_mfma_f32_16x16x32_bf16 v[100:103], v[202:205], v[176:179], v[100:103]
	v_mfma_f32_16x16x32_bf16 v[96:99], v[210:213], v[176:179], v[96:99]
	v_mfma_f32_16x16x32_bf16 v[84:87], v[202:205], v[186:189], v[84:87]
	v_mfma_f32_16x16x32_bf16 v[80:83], v[210:213], v[186:189], v[80:83]
	v_mfma_f32_16x16x32_bf16 v[68:71], v[202:205], v[194:197], v[68:71]
	v_mfma_f32_16x16x32_bf16 v[64:67], v[210:213], v[194:197], v[64:67]
	v_mfma_f32_16x16x32_bf16 v[116:119], v[206:209], v[172:175], v[116:119]
	s_waitcnt lgkmcnt(0)
	v_mfma_f32_16x16x32_bf16 v[112:115], v[214:217], v[172:175], v[112:115]
	v_mfma_f32_16x16x32_bf16 v[100:103], v[206:209], v[182:185], v[100:103]
	v_mfma_f32_16x16x32_bf16 v[96:99], v[214:217], v[182:185], v[96:99]
	v_mfma_f32_16x16x32_bf16 v[84:87], v[206:209], v[190:193], v[84:87]
	v_mfma_f32_16x16x32_bf16 v[80:83], v[214:217], v[190:193], v[80:83]
	v_mfma_f32_16x16x32_bf16 v[68:71], v[206:209], v[198:201], v[68:71]
	s_mov_b32 m0, s65
	v_mfma_f32_16x16x32_bf16 v[64:67], v[214:217], v[198:201], v[64:67]
	s_barrier
	ds_read_b128 v[168:171], v166 offset:49152
	ds_read_b128 v[172:175], v166 offset:50176
	ds_read_b128 v[176:179], v166 offset:51200
	ds_read_b128 v[182:185], v166 offset:52224
	ds_read_b128 v[186:189], v166 offset:53248
	ds_read_b128 v[190:193], v166 offset:54272
	ds_read_b128 v[194:197], v166 offset:55296
	ds_read_b128 v[198:201], v166 offset:56320
	global_load_lds_dwordx4 v144, s[88:89]
	s_mov_b32 m0, s66
	s_nop 0
	global_load_lds_dwordx4 v148, s[88:89]
	s_barrier
	s_waitcnt lgkmcnt(7)
	v_mfma_f32_16x16x32_bf16 v[60:63], v[128:131], v[168:171], v[60:63]
	v_mfma_f32_16x16x32_bf16 v[56:59], v[136:139], v[168:171], v[56:59]
	s_waitcnt lgkmcnt(5)
	v_mfma_f32_16x16x32_bf16 v[44:47], v[128:131], v[176:179], v[44:47]
	v_mfma_f32_16x16x32_bf16 v[40:43], v[136:139], v[176:179], v[40:43]
	s_waitcnt lgkmcnt(3)
	v_mfma_f32_16x16x32_bf16 v[28:31], v[128:131], v[186:189], v[28:31]
	v_mfma_f32_16x16x32_bf16 v[24:27], v[136:139], v[186:189], v[24:27]
	s_waitcnt lgkmcnt(1)
	v_mfma_f32_16x16x32_bf16 v[12:15], v[128:131], v[194:197], v[12:15]
	v_mfma_f32_16x16x32_bf16 v[8:11], v[136:139], v[194:197], v[8:11]
	v_mfma_f32_16x16x32_bf16 v[60:63], v[132:135], v[172:175], v[60:63]
	v_mfma_f32_16x16x32_bf16 v[56:59], v[140:143], v[172:175], v[56:59]
	v_mfma_f32_16x16x32_bf16 v[44:47], v[132:135], v[182:185], v[44:47]
	v_mfma_f32_16x16x32_bf16 v[40:43], v[140:143], v[182:185], v[40:43]
	v_mfma_f32_16x16x32_bf16 v[28:31], v[132:135], v[190:193], v[28:31]
	v_mfma_f32_16x16x32_bf16 v[24:27], v[140:143], v[190:193], v[24:27]
	s_add_u32 s48, s48, 0x40080
	s_addc_u32 s49, s49, 0
	s_waitcnt lgkmcnt(0)
	v_mfma_f32_16x16x32_bf16 v[12:15], v[132:135], v[198:201], v[12:15]
	s_add_i32 s50, s50, s58
	s_mov_b32 m0, s50
	v_mfma_f32_16x16x32_bf16 v[8:11], v[140:143], v[198:201], v[8:11]
	s_barrier
	global_load_lds_dwordx4 v146, s[48:49]
	s_add_i32 m0, s50, 0x2000
	s_nop 0
	global_load_lds_dwordx4 v150, s[48:49]
	s_waitcnt vmcnt(6)
	s_barrier
	v_mfma_f32_16x16x32_bf16 v[52:55], v[202:205], v[168:171], v[52:55]
	v_mfma_f32_16x16x32_bf16 v[48:51], v[210:213], v[168:171], v[48:51]
	v_mfma_f32_16x16x32_bf16 v[36:39], v[202:205], v[176:179], v[36:39]
	v_mfma_f32_16x16x32_bf16 v[32:35], v[210:213], v[176:179], v[32:35]
	v_mfma_f32_16x16x32_bf16 v[20:23], v[202:205], v[186:189], v[20:23]
	v_mfma_f32_16x16x32_bf16 v[16:19], v[210:213], v[186:189], v[16:19]
	v_mfma_f32_16x16x32_bf16 v[4:7], v[202:205], v[194:197], v[4:7]
	v_mfma_f32_16x16x32_bf16 v[0:3], v[210:213], v[194:197], v[0:3]
	v_mfma_f32_16x16x32_bf16 v[52:55], v[206:209], v[172:175], v[52:55]
	s_add_i32 s77, s77, 2
	s_add_u32 s46, s46, 0x100
	v_mfma_f32_16x16x32_bf16 v[48:51], v[214:217], v[172:175], v[48:51]
	s_addc_u32 s47, s47, 0
	s_add_u32 s75, s75, 0x100
	v_mfma_f32_16x16x32_bf16 v[36:39], v[206:209], v[182:185], v[36:39]
	s_addc_u32 s76, s76, 0
	s_add_u32 s48, s46, 0xfffc0080
	v_mfma_f32_16x16x32_bf16 v[32:35], v[214:217], v[182:185], v[32:35]
	s_addc_u32 s49, s47, -1
	s_cmp_eq_u32 s77, 12
	v_mfma_f32_16x16x32_bf16 v[20:23], v[206:209], v[190:193], v[20:23]
	s_cselect_b32 s51, s39, s49
	s_cselect_b32 s50, s73, s48
	v_mfma_f32_16x16x32_bf16 v[16:19], v[214:217], v[190:193], v[16:19]
	s_cselect_b32 s49, s25, s76
	s_cselect_b32 s48, s74, s75
	v_mfma_f32_16x16x32_bf16 v[4:7], v[206:209], v[198:201], v[4:7]
	s_add_i32 m0, s45, 0xc000
	v_mfma_f32_16x16x32_bf16 v[0:3], v[214:217], v[198:201], v[0:3]
	s_cmp_gt_u32 s77, 13
	s_barrier
; DI unsigned pk2(float a, float b) { f32x2 v = {a, b}; bf16x2_t r = __builtin_convertvector(v, bf16x2_t); return __builtin_bit_cast(unsigned, r); }
;     DI void operator()(const f32x4 (&acc)[2][2][4][2], const Unit& u, int wr, int wc, int fr, int fq) const {
;         const int row0 = u.pm * BM + wr * 64 + fr, col0 = u.pn * BM + wc * 32 + 8 * fq;
;         const float* gp = gate + (size_t)((u.pm * BM) >> 12) * NMODC + col0;
;         f32x4 gv[2][2];
; #pragma unroll
;         for (int bj = 0; bj < 2; ++bj)
; #pragma unroll
;             for (int n = 0; n < 2; ++n) gv[bj][n] = *(const f32x4*)(gp + bj * HALF + n * 4);
; #pragma unroll
;         for (int ai = 0; ai < 2; ++ai)
; #pragma unroll
;             for (int m = 0; m < 4; ++m) { const size_t ro = (size_t)(row0 + ai * HALF + m * 16) * DM + col0;
; #pragma unroll
;                 for (int bj = 0; bj < 2; ++bj) {
;                     const f32x4 x0 = *(const f32x4*)(base + ro + bj * HALF) + gv[bj][0] * acc[ai][bj][m][0], x1 = *(const f32x4*)(base + ro + bj * HALF + 4) + gv[bj][1] * acc[ai][bj][m][1];
;                     u32x4 w; w.x = pk2(x0.x, x0.y); w.y = pk2(x0.z, x0.w); w.z = pk2(x1.x, x1.y); w.w = pk2(x1.z, x1.w);
;                     *(u32x4*)(outb + ro + bj * HALF) = w; } }
	s_cbranch_scc0 .LBB0_724
	v_lshl_add_u32 v171, s44, 8, v162
	v_lshl_or_b32 v172, s72, 8, v164
	s_ashr_i32 s25, s44, 4
	s_mul_hi_i32 s39, s25, 0x6000
	s_mulk_i32 s25, 0x6000
	s_add_u32 s46, s63, s25
	s_addc_u32 s47, s64, s39
	v_lshlrev_b32_e32 v168, 2, v172
	v_lshlrev_b32_e32 v160, 12, v171
	v_lshlrev_b32_e32 v161, 11, v171
	global_load_dwordx4 v[128:131], v168, s[46:47]
	global_load_dwordx4 v[132:135], v168, s[46:47] offset:16
	global_load_dwordx4 v[136:139], v168, s[46:47] offset:512
	global_load_dwordx4 v[140:143], v168, s[46:47] offset:528
	v_lshl_add_u32 v160, v172, 2, v160
	v_lshl_add_u32 v161, v172, 1, v161
	s_mov_b32 s72, s24
	s_mov_b32 s44, s38
	s_mov_b64 s[48:49], s[42:43]
	s_mov_b64 s[46:47], s[40:41]
	global_load_dwordx4 v[184:187], v160, s[36:37]
	global_load_dwordx4 v[188:191], v160, s[36:37] offset:16
	global_load_dwordx4 v[192:195], v160, s[36:37] offset:512
	global_load_dwordx4 v[196:199], v160, s[36:37] offset:528
	v_add_u32_e32 v169, 0x10000, v160
	global_load_dwordx4 v[200:203], v169, s[36:37]
	global_load_dwordx4 v[204:207], v169, s[36:37] offset:16
	v_add_u32_e32 v169, 0x10000, v160
	global_load_dwordx4 v[208:211], v169, s[36:37] offset:512
	global_load_dwordx4 v[212:215], v169, s[36:37] offset:528
	v_add_u32_e32 v169, 0x20000, v160
	global_load_dwordx4 v[216:219], v169, s[36:37]
	global_load_dwordx4 v[220:223], v169, s[36:37] offset:16
	v_add_u32_e32 v169, 0x20000, v160
	global_load_dwordx4 v[224:227], v169, s[36:37] offset:512
	global_load_dwordx4 v[228:231], v169, s[36:37] offset:528
	v_add_u32_e32 v169, 0x30000, v160
	global_load_dwordx4 v[232:235], v169, s[36:37]
	global_load_dwordx4 v[236:239], v169, s[36:37] offset:16
	v_add_u32_e32 v169, 0x30000, v160
	global_load_dwordx4 v[240:243], v169, s[36:37] offset:512
	global_load_dwordx4 v[244:247], v169, s[36:37] offset:528
	s_waitcnt vmcnt(14)
	v_pk_fma_f32 v[124:125], v[124:125], v[128:129], v[184:185]
	v_pk_fma_f32 v[126:127], v[126:127], v[130:131], v[186:187]
	v_pk_fma_f32 v[120:121], v[120:121], v[132:133], v[188:189]
	v_pk_fma_f32 v[122:123], v[122:123], v[134:135], v[190:191]
	v_add_u32_e32 v169, 0x80000, v160
	global_load_dwordx4 v[184:187], v169, s[36:37]
	global_load_dwordx4 v[188:191], v169, s[36:37] offset:16
	v_cvt_pk_bf16_f32 v124, v124, v125
	v_cvt_pk_bf16_f32 v125, v126, v127
	v_cvt_pk_bf16_f32 v126, v120, v121
	v_cvt_pk_bf16_f32 v127, v122, v123
	global_store_dwordx4 v161, v[124:127], s[8:9]
	s_waitcnt vmcnt(15)
	v_pk_fma_f32 v[116:117], v[116:117], v[136:137], v[192:193]
	v_pk_fma_f32 v[118:119], v[118:119], v[138:139], v[194:195]
	v_pk_fma_f32 v[112:113], v[112:113], v[140:141], v[196:197]
	v_pk_fma_f32 v[114:115], v[114:115], v[142:143], v[198:199]
	v_add_u32_e32 v169, 0x80000, v160
	global_load_dwordx4 v[192:195], v169, s[36:37] offset:512
	global_load_dwordx4 v[196:199], v169, s[36:37] offset:528
	v_cvt_pk_bf16_f32 v116, v116, v117
	v_cvt_pk_bf16_f32 v117, v118, v119
	v_cvt_pk_bf16_f32 v118, v112, v113
	v_cvt_pk_bf16_f32 v119, v114, v115
	global_store_dwordx4 v161, v[116:119], s[8:9] offset:256
	s_waitcnt vmcnt(16)
	v_pk_fma_f32 v[108:109], v[108:109], v[128:129], v[200:201]
	v_pk_fma_f32 v[110:111], v[110:111], v[130:131], v[202:203]
	v_pk_fma_f32 v[104:105], v[104:105], v[132:133], v[204:205]
	v_pk_fma_f32 v[106:107], v[106:107], v[134:135], v[206:207]
	v_add_u32_e32 v169, 0x90000, v160
	global_load_dwordx4 v[200:203], v169, s[36:37]
	global_load_dwordx4 v[204:207], v169, s[36:37] offset:16
	v_cvt_pk_bf16_f32 v108, v108, v109
	v_cvt_pk_bf16_f32 v109, v110, v111
	v_cvt_pk_bf16_f32 v110, v104, v105
	v_cvt_pk_bf16_f32 v111, v106, v107
	v_add_u32_e32 v170, 0x8000, v161
	global_store_dwordx4 v170, v[108:111], s[8:9]
	s_waitcnt vmcnt(17)
	v_pk_fma_f32 v[100:101], v[100:101], v[136:137], v[208:209]
	v_pk_fma_f32 v[102:103], v[102:103], v[138:139], v[210:211]
	v_pk_fma_f32 v[96:97], v[96:97], v[140:141], v[212:213]
	v_pk_fma_f32 v[98:99], v[98:99], v[142:143], v[214:215]
	v_add_u32_e32 v169, 0x90000, v160
	global_load_dwordx4 v[208:211], v169, s[36:37] offset:512
	global_load_dwordx4 v[212:215], v169, s[36:37] offset:528
	v_cvt_pk_bf16_f32 v100, v100, v101
	v_cvt_pk_bf16_f32 v101, v102, v103
	v_cvt_pk_bf16_f32 v102, v96, v97
	v_cvt_pk_bf16_f32 v103, v98, v99
	v_add_u32_e32 v170, 0x8000, v161
	global_store_dwordx4 v170, v[100:103], s[8:9] offset:256
	s_waitcnt vmcnt(18)
	v_pk_fma_f32 v[92:93], v[92:93], v[128:129], v[216:217]
	v_pk_fma_f32 v[94:95], v[94:95], v[130:131], v[218:219]
	v_pk_fma_f32 v[88:89], v[88:89], v[132:133], v[220:221]
	v_pk_fma_f32 v[90:91], v[90:91], v[134:135], v[222:223]
	v_add_u32_e32 v169, 0xa0000, v160
	global_load_dwordx4 v[216:219], v169, s[36:37]
	global_load_dwordx4 v[220:223], v169, s[36:37] offset:16
	v_cvt_pk_bf16_f32 v92, v92, v93
	v_cvt_pk_bf16_f32 v93, v94, v95
	v_cvt_pk_bf16_f32 v94, v88, v89
	v_cvt_pk_bf16_f32 v95, v90, v91
	v_add_u32_e32 v170, 0x10000, v161
	global_store_dwordx4 v170, v[92:95], s[8:9]
	s_waitcnt vmcnt(19)
	v_pk_fma_f32 v[84:85], v[84:85], v[136:137], v[224:225]
	v_pk_fma_f32 v[86:87], v[86:87], v[138:139], v[226:227]
	v_pk_fma_f32 v[80:81], v[80:81], v[140:141], v[228:229]
	v_pk_fma_f32 v[82:83], v[82:83], v[142:143], v[230:231]
	v_add_u32_e32 v169, 0xa0000, v160
	global_load_dwordx4 v[224:227], v169, s[36:37] offset:512
	global_load_dwordx4 v[228:231], v169, s[36:37] offset:528
	v_cvt_pk_bf16_f32 v84, v84, v85
	v_cvt_pk_bf16_f32 v85, v86, v87
	v_cvt_pk_bf16_f32 v86, v80, v81
	v_cvt_pk_bf16_f32 v87, v82, v83
	v_add_u32_e32 v170, 0x10000, v161
	global_store_dwordx4 v170, v[84:87], s[8:9] offset:256
	s_waitcnt vmcnt(20)
; DI unsigned pk2(float a, float b) { f32x2 v = {a, b}; bf16x2_t r = __builtin_convertvector(v, bf16x2_t); return __builtin_bit_cast(unsigned, r); }
; #define PG8_WAIT_V(n) asm volatile("s_waitcnt vmcnt(" #n ")" ::: "memory")
; #define PG8_BAR __builtin_amdgcn_s_barrier()
; template <class Epi>
; DI void gemm_phase(LAS unsigned char* lds, const Gemm g, const StaticOrder& S, const Epi& E) {
;     ...
;         if (!has_next) break;
; #pragma unroll
;         for (int a = 0; a < 2; ++a)
; #pragma unroll
;             for (int b = 0; b < 2; ++b)
; #pragma unroll
;                 for (int m = 0; m < 4; ++m)
; #pragma unroll
;                     for (int n = 0; n < 2; ++n) acc[a][b][m][n] = (f32x4){0.f, 0.f, 0.f, 0.f};
;         cur = nxt; cA = nA; cB = nB; ++ui;
;     }
;     PG8_WAIT_V(0);
;     if (wr == 0) PG8_BAR;
;     PG8_BAR;
;     DI void operator()(const f32x4 (&acc)[2][2][4][2], const Unit& u, int wr, int wc, int fr, int fq) const {
;     ...
; #pragma unroll
;         for (int ai = 0; ai < 2; ++ai)
; #pragma unroll
;             for (int m = 0; m < 4; ++m) { const size_t ro = (size_t)(row0 + ai * HALF + m * 16) * DM + col0;
; #pragma unroll
;                 for (int bj = 0; bj < 2; ++bj) {
;                     const f32x4 x0 = *(const f32x4*)(base + ro + bj * HALF) + gv[bj][0] * acc[ai][bj][m][0], x1 = *(const f32x4*)(base + ro + bj * HALF + 4) + gv[bj][1] * acc[ai][bj][m][1];
;                     u32x4 w; w.x = pk2(x0.x, x0.y); w.y = pk2(x0.z, x0.w); w.z = pk2(x1.x, x1.y); w.w = pk2(x1.z, x1.w);
;                     *(u32x4*)(outb + ro + bj * HALF) = w; } }
	v_pk_fma_f32 v[76:77], v[76:77], v[128:129], v[232:233]
	v_pk_fma_f32 v[78:79], v[78:79], v[130:131], v[234:235]
	v_pk_fma_f32 v[72:73], v[72:73], v[132:133], v[236:237]
	v_pk_fma_f32 v[74:75], v[74:75], v[134:135], v[238:239]
	v_add_u32_e32 v169, 0xb0000, v160
	global_load_dwordx4 v[232:235], v169, s[36:37]
	global_load_dwordx4 v[236:239], v169, s[36:37] offset:16
	v_cvt_pk_bf16_f32 v76, v76, v77
	v_cvt_pk_bf16_f32 v77, v78, v79
	v_cvt_pk_bf16_f32 v78, v72, v73
	v_cvt_pk_bf16_f32 v79, v74, v75
	v_add_u32_e32 v170, 0x18000, v161
	global_store_dwordx4 v170, v[76:79], s[8:9]
	s_waitcnt vmcnt(21)
	v_pk_fma_f32 v[68:69], v[68:69], v[136:137], v[240:241]
	v_pk_fma_f32 v[70:71], v[70:71], v[138:139], v[242:243]
	v_pk_fma_f32 v[64:65], v[64:65], v[140:141], v[244:245]
	v_pk_fma_f32 v[66:67], v[66:67], v[142:143], v[246:247]
	v_add_u32_e32 v169, 0xb0000, v160
	global_load_dwordx4 v[240:243], v169, s[36:37] offset:512
	global_load_dwordx4 v[244:247], v169, s[36:37] offset:528
	v_cvt_pk_bf16_f32 v68, v68, v69
	v_cvt_pk_bf16_f32 v69, v70, v71
	v_cvt_pk_bf16_f32 v70, v64, v65
	v_cvt_pk_bf16_f32 v71, v66, v67
	v_add_u32_e32 v170, 0x18000, v161
	global_store_dwordx4 v170, v[68:71], s[8:9] offset:256
	s_waitcnt vmcnt(22)
	v_pk_fma_f32 v[60:61], v[60:61], v[128:129], v[184:185]
	v_pk_fma_f32 v[62:63], v[62:63], v[130:131], v[186:187]
	v_pk_fma_f32 v[56:57], v[56:57], v[132:133], v[188:189]
	v_pk_fma_f32 v[58:59], v[58:59], v[134:135], v[190:191]
	v_cvt_pk_bf16_f32 v60, v60, v61
	v_cvt_pk_bf16_f32 v61, v62, v63
	v_cvt_pk_bf16_f32 v62, v56, v57
	v_cvt_pk_bf16_f32 v63, v58, v59
	v_add_u32_e32 v170, 0x40000, v161
	global_store_dwordx4 v170, v[60:63], s[8:9]
	s_waitcnt vmcnt(20)
	v_pk_fma_f32 v[52:53], v[52:53], v[136:137], v[192:193]
	v_pk_fma_f32 v[54:55], v[54:55], v[138:139], v[194:195]
	v_pk_fma_f32 v[48:49], v[48:49], v[140:141], v[196:197]
	v_pk_fma_f32 v[50:51], v[50:51], v[142:143], v[198:199]
	v_cvt_pk_bf16_f32 v52, v52, v53
	v_cvt_pk_bf16_f32 v53, v54, v55
	v_cvt_pk_bf16_f32 v54, v48, v49
	v_cvt_pk_bf16_f32 v55, v50, v51
	v_add_u32_e32 v170, 0x40000, v161
	global_store_dwordx4 v170, v[52:55], s[8:9] offset:256
	s_waitcnt vmcnt(18)
	v_pk_fma_f32 v[44:45], v[44:45], v[128:129], v[200:201]
	v_pk_fma_f32 v[46:47], v[46:47], v[130:131], v[202:203]
	v_pk_fma_f32 v[40:41], v[40:41], v[132:133], v[204:205]
	v_pk_fma_f32 v[42:43], v[42:43], v[134:135], v[206:207]
	v_cvt_pk_bf16_f32 v44, v44, v45
	v_cvt_pk_bf16_f32 v45, v46, v47
	v_cvt_pk_bf16_f32 v46, v40, v41
	v_cvt_pk_bf16_f32 v47, v42, v43
	v_add_u32_e32 v170, 0x48000, v161
	global_store_dwordx4 v170, v[44:47], s[8:9]
	s_waitcnt vmcnt(16)
	v_pk_fma_f32 v[36:37], v[36:37], v[136:137], v[208:209]
	v_pk_fma_f32 v[38:39], v[38:39], v[138:139], v[210:211]
	v_pk_fma_f32 v[32:33], v[32:33], v[140:141], v[212:213]
	v_pk_fma_f32 v[34:35], v[34:35], v[142:143], v[214:215]
	v_cvt_pk_bf16_f32 v36, v36, v37
	v_cvt_pk_bf16_f32 v37, v38, v39
	v_cvt_pk_bf16_f32 v38, v32, v33
	v_cvt_pk_bf16_f32 v39, v34, v35
	v_add_u32_e32 v170, 0x48000, v161
	global_store_dwordx4 v170, v[36:39], s[8:9] offset:256
	s_waitcnt vmcnt(14)
	v_pk_fma_f32 v[28:29], v[28:29], v[128:129], v[216:217]
	v_pk_fma_f32 v[30:31], v[30:31], v[130:131], v[218:219]
	v_pk_fma_f32 v[24:25], v[24:25], v[132:133], v[220:221]
	v_pk_fma_f32 v[26:27], v[26:27], v[134:135], v[222:223]
	v_cvt_pk_bf16_f32 v28, v28, v29
	v_cvt_pk_bf16_f32 v29, v30, v31
	v_cvt_pk_bf16_f32 v30, v24, v25
	v_cvt_pk_bf16_f32 v31, v26, v27
	v_add_u32_e32 v170, 0x50000, v161
	global_store_dwordx4 v170, v[28:31], s[8:9]
	s_waitcnt vmcnt(12)
	v_pk_fma_f32 v[20:21], v[20:21], v[136:137], v[224:225]
	v_pk_fma_f32 v[22:23], v[22:23], v[138:139], v[226:227]
	v_pk_fma_f32 v[16:17], v[16:17], v[140:141], v[228:229]
	v_pk_fma_f32 v[18:19], v[18:19], v[142:143], v[230:231]
	v_cvt_pk_bf16_f32 v20, v20, v21
	v_cvt_pk_bf16_f32 v21, v22, v23
	v_cvt_pk_bf16_f32 v22, v16, v17
	v_cvt_pk_bf16_f32 v23, v18, v19
	v_add_u32_e32 v170, 0x50000, v161
	global_store_dwordx4 v170, v[20:23], s[8:9] offset:256
	s_waitcnt vmcnt(10)
	v_pk_fma_f32 v[12:13], v[12:13], v[128:129], v[232:233]
	v_pk_fma_f32 v[14:15], v[14:15], v[130:131], v[234:235]
	v_pk_fma_f32 v[8:9], v[8:9], v[132:133], v[236:237]
	v_pk_fma_f32 v[10:11], v[10:11], v[134:135], v[238:239]
	v_cvt_pk_bf16_f32 v12, v12, v13
	v_cvt_pk_bf16_f32 v13, v14, v15
	v_cvt_pk_bf16_f32 v14, v8, v9
	v_cvt_pk_bf16_f32 v15, v10, v11
	v_add_u32_e32 v170, 0x58000, v161
	global_store_dwordx4 v170, v[12:15], s[8:9]
	s_waitcnt vmcnt(8)
	v_pk_fma_f32 v[4:5], v[4:5], v[136:137], v[240:241]
	v_pk_fma_f32 v[6:7], v[6:7], v[138:139], v[242:243]
	v_pk_fma_f32 v[0:1], v[0:1], v[140:141], v[244:245]
	v_pk_fma_f32 v[2:3], v[2:3], v[142:143], v[246:247]
	v_cvt_pk_bf16_f32 v4, v4, v5
	v_cvt_pk_bf16_f32 v5, v6, v7
	v_cvt_pk_bf16_f32 v6, v0, v1
	v_cvt_pk_bf16_f32 v7, v2, v3
	v_add_u32_e32 v170, 0x58000, v161
	global_store_dwordx4 v170, v[4:7], s[8:9] offset:256
	s_and_b64 vcc, exec, s[4:5]
	s_cbranch_vccz .LBB0_717
	s_waitcnt vmcnt(0)
	s_cmpk_gt_u32 s52, 0xff
	s_cbranch_scc1 .LBB0_728
	s_barrier

; #define PG8_STAGE(bufoff, gbase, voff) do { _Pragma("unroll") for (int _i = 0; _i < 2; ++_i) \
;         __builtin_amdgcn_global_load_lds((const unsigned*)((const char*)(gbase) + (voff)[_i]), (LAS unsigned*)(lds + (bufoff) + ldsw + _i * 8192), 16, 0, 0); } while (0)
; #define PG8_LDA(dst, b, h) do { _Pragma("unroll") for (int m = 0; m < 4; ++m) _Pragma("unroll") for (int k = 0; k < 2; ++k) dst[m][k] = *(const LAS bf16x8*)(lds + PG8_SA(b, h) + aoff + m * 2048 + k * 1024); } while (0)
; #define PG8_LDB(dst, b, h) do { _Pragma("unroll") for (int n = 0; n < 2; ++n) _Pragma("unroll") for (int k = 0; k < 2; ++k) dst[n][k] = *(const LAS bf16x8*)(lds + PG8_SB(b, h) + boff + n * 2048 + k * 1024); } while (0)
; template <class Epi>
; DI void gemm_phase(LAS unsigned char* lds, const Gemm g, const StaticOrder& S, const Epi& E) {
;     ...
;         const bool has_next = S.next(ui + 1, nxt);
;         const char* nA = has_next ? (const char*)g.A + (size_t)nxt.pm * tstep : cA; const char* nB = has_next ? (const char*)g.Bt + (size_t)nxt.pn * tstep : cB;
;         for (int t = 0; t < nt; t += 2) {
;             const bool last = (t == nt - 2);
;             const char* a1 = cA + (size_t)(t + 1) * kstep;
;             const char* a2 = last ? nA : cA + (size_t)(t + 2) * kstep; const char* b2 = last ? nB : cB + (size_t)(t + 2) * kstep;
;             const char* a3 = a2 + kstep; const char* b3 = b2 + kstep;
;             PG8_LDB(B0, 0, 0); PG8_SCHED; PG8_LDA(At, 0, 0); PG8_STAGE(PG8_SA(1, 1), a1 + hstep, voffA);
;             PG8_WAIT_L(8); PG8_BAR; PG8_WAIT_L(0); PG8_MMA(0, 0, At, B0); PG8_BAR; PG8_SCHED;
;             PG8_LDB(B1, 0, 1); PG8_STAGE(PG8_SB(0, 0), b2, voffB);
;             PG8_BAR; PG8_WAIT_L(0); PG8_MMA(0, 1, At, B1); PG8_BAR;
;             PG8_LDA(At, 0, 1); PG8_STAGE(PG8_SA(0, 0), a2, voffA);
;             PG8_BAR; PG8_WAIT_L(0); PG8_MMA(1, 0, At, B0); PG8_BAR; PG8_SCHED;
;             PG8_STAGE(PG8_SB(0, 1), b2 + hstep, voffB);
;             PG8_WAIT_V(6); PG8_BAR; PG8_MMA(1, 1, At, B1); PG8_BAR;
;             PG8_LDB(B0, 1, 0); PG8_SCHED; PG8_LDA(At, 1, 0); PG8_STAGE(PG8_SA(0, 1), a2 + hstep, voffA);
;             PG8_WAIT_L(8); PG8_BAR; PG8_WAIT_L(0); PG8_MMA(0, 0, At, B0); PG8_BAR; PG8_SCHED;
;             PG8_LDB(B1, 1, 1); PG8_STAGE(PG8_SB(1, 0), b3, voffB);
;             PG8_BAR; PG8_WAIT_L(0); PG8_MMA(0, 1, At, B1); PG8_BAR;
.LBB0_848:
	s_ashr_i32 s17, s16, 31
	v_cmp_lt_i64_e32 vcc, s[18:19], v[140:141]
	s_lshl_b64 s[18:19], s[16:17], 19
	s_add_u32 s18, s41, s18
	s_addc_u32 s19, s42, s19
	s_and_b64 s[20:21], vcc, exec
	s_cselect_b32 s17, s19, s25
	s_cselect_b32 s59, s18, s24
	s_ashr_i32 s15, s14, 31
	s_lshl_b64 s[20:21], s[14:15], 19
	s_add_u32 s20, s43, s20
	s_addc_u32 s21, s44, s21
	s_and_b64 s[38:39], vcc, exec
	s_cselect_b32 s15, s21, s37
	s_cselect_b32 s60, s20, s36
	s_add_u32 s24, s24, 0x40080
	s_addc_u32 s25, s25, 0
	s_add_u32 s61, s36, 0x100
	s_addc_u32 s62, s37, 0
	s_mov_b32 s63, -2
	v_add_u32_e32 v253, 0x18000, v147
	v_add_u32_e32 v252, 0x1c000, v147
	ds_read_b128 v[152:155], v149
	ds_read_b128 v[156:159], v149 offset:1024
	ds_read_b128 v[160:163], v149 offset:2048
	ds_read_b128 v[164:167], v149 offset:3072
	s_add_u32 s36, s24, 0xfffc0080
	s_addc_u32 s37, s25, -1
	s_cmp_eq_u32 s63, 12
	s_cselect_b32 s39, s17, s37
	s_cselect_b32 s38, s59, s36
	s_cselect_b32 s37, s15, s62
	s_cselect_b32 s36, s60, s61
	s_add_i32 m0, s23, 0xc000
	ds_read_b128 v[168:171], v150
	ds_read_b128 v[172:175], v150 offset:1024
	ds_read_b128 v[176:179], v150 offset:2048
	ds_read_b128 v[182:185], v150 offset:3072
	ds_read_b128 v[186:189], v150 offset:4096
	ds_read_b128 v[190:193], v150 offset:5120
	ds_read_b128 v[194:197], v150 offset:6144
	ds_read_b128 v[198:201], v150 offset:7168
	global_load_lds_dwordx4 v136, s[24:25]
	s_add_i32 m0, s23, 0xe000
	s_nop 0
	global_load_lds_dwordx4 v138, s[24:25]
	s_waitcnt lgkmcnt(8)
	s_barrier
	s_waitcnt lgkmcnt(7)
	v_mfma_f32_16x16x32_bf16 v[124:127], v[152:155], v[168:171], 0
	v_mfma_f32_16x16x32_bf16 v[120:123], v[160:163], v[168:171], 0
	s_waitcnt lgkmcnt(5)
	v_mfma_f32_16x16x32_bf16 v[108:111], v[152:155], v[176:179], 0
	v_mfma_f32_16x16x32_bf16 v[104:107], v[160:163], v[176:179], 0
	s_waitcnt lgkmcnt(3)
	v_mfma_f32_16x16x32_bf16 v[92:95], v[152:155], v[186:189], 0
	v_mfma_f32_16x16x32_bf16 v[88:91], v[160:163], v[186:189], 0
	s_waitcnt lgkmcnt(1)
	v_mfma_f32_16x16x32_bf16 v[76:79], v[152:155], v[194:197], 0
	v_mfma_f32_16x16x32_bf16 v[72:75], v[160:163], v[194:197], 0
	v_mfma_f32_16x16x32_bf16 v[124:127], v[156:159], v[172:175], v[124:127]
	v_mfma_f32_16x16x32_bf16 v[120:123], v[164:167], v[172:175], v[120:123]
	v_mfma_f32_16x16x32_bf16 v[108:111], v[156:159], v[182:185], v[108:111]
	v_mfma_f32_16x16x32_bf16 v[104:107], v[164:167], v[182:185], v[104:107]
	v_mfma_f32_16x16x32_bf16 v[92:95], v[156:159], v[190:193], v[92:95]
	v_mfma_f32_16x16x32_bf16 v[88:91], v[164:167], v[190:193], v[88:91]
	s_add_i32 s64, s55, s45
	s_add_u32 s86, s36, s12
	s_waitcnt lgkmcnt(0)
	v_mfma_f32_16x16x32_bf16 v[76:79], v[156:159], v[198:201], v[76:79]
	s_addc_u32 s87, s37, s13
	s_mov_b32 m0, s64
	v_mfma_f32_16x16x32_bf16 v[72:75], v[164:167], v[198:201], v[72:75]
	s_barrier
	ds_read_b128 v[202:205], v151
	ds_read_b128 v[206:209], v151 offset:1024
	ds_read_b128 v[210:213], v151 offset:2048
	ds_read_b128 v[214:217], v151 offset:3072
	global_load_lds_dwordx4 v132, s[36:37]
	s_add_i32 m0, s64, 0x2000
	s_nop 0
	global_load_lds_dwordx4 v128, s[36:37]
	s_barrier
	s_waitcnt lgkmcnt(3)
	v_mfma_f32_16x16x32_bf16 v[116:119], v[202:205], v[168:171], 0
	s_waitcnt lgkmcnt(1)
	v_mfma_f32_16x16x32_bf16 v[112:115], v[210:213], v[168:171], 0
	v_mfma_f32_16x16x32_bf16 v[100:103], v[202:205], v[176:179], 0
	v_mfma_f32_16x16x32_bf16 v[96:99], v[210:213], v[176:179], 0
	v_mfma_f32_16x16x32_bf16 v[84:87], v[202:205], v[186:189], 0
	v_mfma_f32_16x16x32_bf16 v[80:83], v[210:213], v[186:189], 0
	v_mfma_f32_16x16x32_bf16 v[68:71], v[202:205], v[194:197], 0
	v_mfma_f32_16x16x32_bf16 v[64:67], v[210:213], v[194:197], 0
	v_mfma_f32_16x16x32_bf16 v[116:119], v[206:209], v[172:175], v[116:119]
	s_waitcnt lgkmcnt(0)
	v_mfma_f32_16x16x32_bf16 v[112:115], v[214:217], v[172:175], v[112:115]
	v_mfma_f32_16x16x32_bf16 v[100:103], v[206:209], v[182:185], v[100:103]
	v_mfma_f32_16x16x32_bf16 v[96:99], v[214:217], v[182:185], v[96:99]
	v_mfma_f32_16x16x32_bf16 v[84:87], v[206:209], v[190:193], v[84:87]
	v_mfma_f32_16x16x32_bf16 v[80:83], v[214:217], v[190:193], v[80:83]
	s_mov_b32 m0, s23
	s_add_u32 s88, s38, s12
	v_mfma_f32_16x16x32_bf16 v[68:71], v[206:209], v[198:201], v[68:71]
	s_addc_u32 s89, s39, s13
	v_mfma_f32_16x16x32_bf16 v[64:67], v[214:217], v[198:201], v[64:67]
	s_barrier
	ds_read_b128 v[168:171], v150 offset:16384
	ds_read_b128 v[172:175], v150 offset:17408
	ds_read_b128 v[176:179], v150 offset:18432
	ds_read_b128 v[182:185], v150 offset:19456
	ds_read_b128 v[186:189], v150 offset:20480
	ds_read_b128 v[190:193], v150 offset:21504
	ds_read_b128 v[194:197], v150 offset:22528
	ds_read_b128 v[198:201], v150 offset:23552
	global_load_lds_dwordx4 v134, s[38:39]
	s_mov_b32 m0, s48
	s_nop 0
	global_load_lds_dwordx4 v130, s[38:39]
	s_barrier
	s_waitcnt lgkmcnt(7)
	v_mfma_f32_16x16x32_bf16 v[60:63], v[152:155], v[168:171], 0
	v_mfma_f32_16x16x32_bf16 v[56:59], v[160:163], v[168:171], 0
	s_waitcnt lgkmcnt(5)
	v_mfma_f32_16x16x32_bf16 v[44:47], v[152:155], v[176:179], 0
	v_mfma_f32_16x16x32_bf16 v[40:43], v[160:163], v[176:179], 0
	s_waitcnt lgkmcnt(3)
	v_mfma_f32_16x16x32_bf16 v[28:31], v[152:155], v[186:189], 0
	v_mfma_f32_16x16x32_bf16 v[24:27], v[160:163], v[186:189], 0
	s_waitcnt lgkmcnt(1)
	v_mfma_f32_16x16x32_bf16 v[12:15], v[152:155], v[194:197], 0
	v_mfma_f32_16x16x32_bf16 v[8:11], v[160:163], v[194:197], 0
	v_mfma_f32_16x16x32_bf16 v[60:63], v[156:159], v[172:175], v[60:63]
	v_mfma_f32_16x16x32_bf16 v[56:59], v[164:167], v[172:175], v[56:59]
	v_mfma_f32_16x16x32_bf16 v[44:47], v[156:159], v[182:185], v[44:47]
	v_mfma_f32_16x16x32_bf16 v[40:43], v[164:167], v[182:185], v[40:43]
	v_mfma_f32_16x16x32_bf16 v[28:31], v[156:159], v[190:193], v[28:31]
	v_mfma_f32_16x16x32_bf16 v[24:27], v[164:167], v[190:193], v[24:27]
	s_add_u32 s64, s36, 0x40000
	s_addc_u32 s65, s37, 0
	s_waitcnt lgkmcnt(0)
	v_mfma_f32_16x16x32_bf16 v[12:15], v[156:159], v[198:201], v[12:15]
	s_add_i32 s66, s56, s45
	s_mov_b32 m0, s66
	v_mfma_f32_16x16x32_bf16 v[8:11], v[164:167], v[198:201], v[8:11]
	s_barrier
; #define PG8_STAGE(bufoff, gbase, voff) do { _Pragma("unroll") for (int _i = 0; _i < 2; ++_i) \
;         __builtin_amdgcn_global_load_lds((const unsigned*)((const char*)(gbase) + (voff)[_i]), (LAS unsigned*)(lds + (bufoff) + ldsw + _i * 8192), 16, 0, 0); } while (0)
; #define PG8_LDA(dst, b, h) do { _Pragma("unroll") for (int m = 0; m < 4; ++m) _Pragma("unroll") for (int k = 0; k < 2; ++k) dst[m][k] = *(const LAS bf16x8*)(lds + PG8_SA(b, h) + aoff + m * 2048 + k * 1024); } while (0)
; #define PG8_LDB(dst, b, h) do { _Pragma("unroll") for (int n = 0; n < 2; ++n) _Pragma("unroll") for (int k = 0; k < 2; ++k) dst[n][k] = *(const LAS bf16x8*)(lds + PG8_SB(b, h) + boff + n * 2048 + k * 1024); } while (0)
; #define PG8_MMA(ai, bj, At, Bt) do { __builtin_amdgcn_s_setprio(1); _Pragma("unroll") for (int m = 0; m < 4; ++m) _Pragma("unroll") for (int n = 0; n < 2; ++n) _Pragma("unroll") for (int k = 0; k < 2; ++k) \
;         acc[ai][bj][m][n] = __builtin_amdgcn_mfma_f32_16x16x32_bf16(Bt[n][k], At[m][k], acc[ai][bj][m][n], 0, 0, 0); __builtin_amdgcn_s_setprio(0); } while (0)
; #define PG8_WAIT_V(n) asm volatile("s_waitcnt vmcnt(" #n ")" ::: "memory")
; #define PG8_WAIT_L(n) asm volatile("s_waitcnt lgkmcnt(" #n ")" ::: "memory")
; #define PG8_BAR __builtin_amdgcn_s_barrier()
; #define PG8_SCHED __builtin_amdgcn_sched_barrier(0)
; template <class Epi>
; DI void gemm_phase(LAS unsigned char* lds, const Gemm g, const StaticOrder& S, const Epi& E) {
;     ...
;             PG8_LDA(At, 0, 1); PG8_STAGE(PG8_SA(0, 0), a2, voffA);
;             PG8_BAR; PG8_WAIT_L(0); PG8_MMA(1, 0, At, B0); PG8_BAR; PG8_SCHED;
;             PG8_STAGE(PG8_SB(0, 1), b2 + hstep, voffB);
;             PG8_WAIT_V(6); PG8_BAR; PG8_MMA(1, 1, At, B1); PG8_BAR;
;             PG8_LDB(B0, 1, 0); PG8_SCHED; PG8_LDA(At, 1, 0); PG8_STAGE(PG8_SA(0, 1), a2 + hstep, voffA);
;             PG8_WAIT_L(8); PG8_BAR; PG8_WAIT_L(0); PG8_MMA(0, 0, At, B0); PG8_BAR; PG8_SCHED;
;             PG8_LDB(B1, 1, 1); PG8_STAGE(PG8_SB(1, 0), b3, voffB);
;             PG8_BAR; PG8_WAIT_L(0); PG8_MMA(0, 1, At, B1); PG8_BAR;
	global_load_lds_dwordx4 v132, s[64:65]
	s_add_i32 m0, s66, 0x2000
	s_nop 0
	global_load_lds_dwordx4 v128, s[64:65]
	s_waitcnt vmcnt(6)
	s_barrier
	v_mfma_f32_16x16x32_bf16 v[52:55], v[202:205], v[168:171], 0
	v_mfma_f32_16x16x32_bf16 v[48:51], v[210:213], v[168:171], 0
	v_mfma_f32_16x16x32_bf16 v[36:39], v[202:205], v[176:179], 0
	v_mfma_f32_16x16x32_bf16 v[32:35], v[210:213], v[176:179], 0
	v_mfma_f32_16x16x32_bf16 v[20:23], v[202:205], v[186:189], 0
	v_mfma_f32_16x16x32_bf16 v[16:19], v[210:213], v[186:189], 0
	v_mfma_f32_16x16x32_bf16 v[4:7], v[202:205], v[194:197], 0
	v_mfma_f32_16x16x32_bf16 v[0:3], v[210:213], v[194:197], 0
	v_mfma_f32_16x16x32_bf16 v[52:55], v[206:209], v[172:175], v[52:55]
	v_mfma_f32_16x16x32_bf16 v[48:51], v[214:217], v[172:175], v[48:51]
	v_mfma_f32_16x16x32_bf16 v[36:39], v[206:209], v[182:185], v[36:39]
	v_mfma_f32_16x16x32_bf16 v[32:35], v[214:217], v[182:185], v[32:35]
	v_mfma_f32_16x16x32_bf16 v[20:23], v[206:209], v[190:193], v[20:23]
	v_mfma_f32_16x16x32_bf16 v[16:19], v[214:217], v[190:193], v[16:19]
	v_mfma_f32_16x16x32_bf16 v[4:7], v[206:209], v[198:201], v[4:7]
	s_add_i32 s64, 0, 0x18000
	v_mfma_f32_16x16x32_bf16 v[0:3], v[214:217], v[198:201], v[0:3]
	s_barrier
	ds_read_b128 v[152:155], v253
	ds_read_b128 v[156:159], v253 offset:1024
	ds_read_b128 v[160:163], v253 offset:2048
	ds_read_b128 v[164:167], v253 offset:3072
	s_add_u32 s38, s38, 0x40000
	s_addc_u32 s39, s39, 0
	s_mov_b32 m0, s49
	ds_read_b128 v[168:171], v150 offset:32768
	ds_read_b128 v[172:175], v150 offset:33792
	ds_read_b128 v[176:179], v150 offset:34816
	ds_read_b128 v[182:185], v150 offset:35840
	ds_read_b128 v[186:189], v150 offset:36864
	ds_read_b128 v[190:193], v150 offset:37888
	ds_read_b128 v[194:197], v150 offset:38912
	ds_read_b128 v[198:201], v150 offset:39936
	global_load_lds_dwordx4 v134, s[38:39]
	s_mov_b32 m0, s50
	s_nop 0
	global_load_lds_dwordx4 v130, s[38:39]
	s_waitcnt lgkmcnt(8)
	s_barrier
	s_waitcnt lgkmcnt(7)
	v_mfma_f32_16x16x32_bf16 v[124:127], v[152:155], v[168:171], v[124:127]
	v_mfma_f32_16x16x32_bf16 v[120:123], v[160:163], v[168:171], v[120:123]
	s_waitcnt lgkmcnt(5)
	v_mfma_f32_16x16x32_bf16 v[108:111], v[152:155], v[176:179], v[108:111]
	v_mfma_f32_16x16x32_bf16 v[104:107], v[160:163], v[176:179], v[104:107]
	s_waitcnt lgkmcnt(3)
	v_mfma_f32_16x16x32_bf16 v[92:95], v[152:155], v[186:189], v[92:95]
	v_mfma_f32_16x16x32_bf16 v[88:91], v[160:163], v[186:189], v[88:91]
	s_waitcnt lgkmcnt(1)
	v_mfma_f32_16x16x32_bf16 v[76:79], v[152:155], v[194:197], v[76:79]
	v_mfma_f32_16x16x32_bf16 v[72:75], v[160:163], v[194:197], v[72:75]
	v_mfma_f32_16x16x32_bf16 v[124:127], v[156:159], v[172:175], v[124:127]
	v_mfma_f32_16x16x32_bf16 v[120:123], v[164:167], v[172:175], v[120:123]
	v_mfma_f32_16x16x32_bf16 v[108:111], v[156:159], v[182:185], v[108:111]
	v_mfma_f32_16x16x32_bf16 v[104:107], v[164:167], v[182:185], v[104:107]
	v_mfma_f32_16x16x32_bf16 v[92:95], v[156:159], v[190:193], v[92:95]
	v_mfma_f32_16x16x32_bf16 v[88:91], v[164:167], v[190:193], v[88:91]
	s_add_i32 s38, 0, 0x1c000
	s_add_i32 s39, s64, s45
	s_waitcnt lgkmcnt(0)
	v_mfma_f32_16x16x32_bf16 v[76:79], v[156:159], v[198:201], v[76:79]
	s_mov_b32 m0, s39
	v_mfma_f32_16x16x32_bf16 v[72:75], v[164:167], v[198:201], v[72:75]
	s_barrier
	ds_read_b128 v[202:205], v252
	ds_read_b128 v[206:209], v252 offset:1024
	ds_read_b128 v[210:213], v252 offset:2048
	ds_read_b128 v[214:217], v252 offset:3072
	global_load_lds_dwordx4 v132, s[86:87]
	s_add_i32 m0, s39, 0x2000
	s_nop 0
	global_load_lds_dwordx4 v128, s[86:87]
	s_barrier
	s_waitcnt lgkmcnt(3)
	v_mfma_f32_16x16x32_bf16 v[116:119], v[202:205], v[168:171], v[116:119]
	s_waitcnt lgkmcnt(1)
	v_mfma_f32_16x16x32_bf16 v[112:115], v[210:213], v[168:171], v[112:115]
	v_mfma_f32_16x16x32_bf16 v[100:103], v[202:205], v[176:179], v[100:103]
	v_mfma_f32_16x16x32_bf16 v[96:99], v[210:213], v[176:179], v[96:99]
	v_mfma_f32_16x16x32_bf16 v[84:87], v[202:205], v[186:189], v[84:87]
	v_mfma_f32_16x16x32_bf16 v[80:83], v[210:213], v[186:189], v[80:83]
	v_mfma_f32_16x16x32_bf16 v[68:71], v[202:205], v[194:197], v[68:71]
	v_mfma_f32_16x16x32_bf16 v[64:67], v[210:213], v[194:197], v[64:67]
	v_mfma_f32_16x16x32_bf16 v[116:119], v[206:209], v[172:175], v[116:119]
	s_waitcnt lgkmcnt(0)
	v_mfma_f32_16x16x32_bf16 v[112:115], v[214:217], v[172:175], v[112:115]
	v_mfma_f32_16x16x32_bf16 v[100:103], v[206:209], v[182:185], v[100:103]
	v_mfma_f32_16x16x32_bf16 v[96:99], v[214:217], v[182:185], v[96:99]
	v_mfma_f32_16x16x32_bf16 v[84:87], v[206:209], v[190:193], v[84:87]
	v_mfma_f32_16x16x32_bf16 v[80:83], v[214:217], v[190:193], v[80:83]
	v_mfma_f32_16x16x32_bf16 v[68:71], v[206:209], v[198:201], v[68:71]
	s_mov_b32 m0, s52
	v_mfma_f32_16x16x32_bf16 v[64:67], v[214:217], v[198:201], v[64:67]
	s_barrier
	ds_read_b128 v[168:171], v150 offset:49152
	ds_read_b128 v[172:175], v150 offset:50176
	ds_read_b128 v[176:179], v150 offset:51200
	ds_read_b128 v[182:185], v150 offset:52224
	ds_read_b128 v[186:189], v150 offset:53248
	ds_read_b128 v[190:193], v150 offset:54272
	ds_read_b128 v[194:197], v150 offset:55296
	ds_read_b128 v[198:201], v150 offset:56320
	global_load_lds_dwordx4 v134, s[88:89]
	s_mov_b32 m0, s53
	s_nop 0
	global_load_lds_dwordx4 v130, s[88:89]
	s_barrier
; #define PG8_STAGE(bufoff, gbase, voff) do { _Pragma("unroll") for (int _i = 0; _i < 2; ++_i) \
;         __builtin_amdgcn_global_load_lds((const unsigned*)((const char*)(gbase) + (voff)[_i]), (LAS unsigned*)(lds + (bufoff) + ldsw + _i * 8192), 16, 0, 0); } while (0)
; #define PG8_LDA(dst, b, h) do { _Pragma("unroll") for (int m = 0; m < 4; ++m) _Pragma("unroll") for (int k = 0; k < 2; ++k) dst[m][k] = *(const LAS bf16x8*)(lds + PG8_SA(b, h) + aoff + m * 2048 + k * 1024); } while (0)
; #define PG8_LDB(dst, b, h) do { _Pragma("unroll") for (int n = 0; n < 2; ++n) _Pragma("unroll") for (int k = 0; k < 2; ++k) dst[n][k] = *(const LAS bf16x8*)(lds + PG8_SB(b, h) + boff + n * 2048 + k * 1024); } while (0)
; #define PG8_MMA(ai, bj, At, Bt) do { __builtin_amdgcn_s_setprio(1); _Pragma("unroll") for (int m = 0; m < 4; ++m) _Pragma("unroll") for (int n = 0; n < 2; ++n) _Pragma("unroll") for (int k = 0; k < 2; ++k) \
;         acc[ai][bj][m][n] = __builtin_amdgcn_mfma_f32_16x16x32_bf16(Bt[n][k], At[m][k], acc[ai][bj][m][n], 0, 0, 0); __builtin_amdgcn_s_setprio(0); } while (0)
; #define PG8_WAIT_V(n) asm volatile("s_waitcnt vmcnt(" #n ")" ::: "memory")
; #define PG8_WAIT_L(n) asm volatile("s_waitcnt lgkmcnt(" #n ")" ::: "memory")
; #define PG8_BAR __builtin_amdgcn_s_barrier()
; #define PG8_SCHED __builtin_amdgcn_sched_barrier(0)
; template <class Epi>
; DI void gemm_phase(LAS unsigned char* lds, const Gemm g, const StaticOrder& S, const Epi& E) {
;     ...
;             PG8_LDB(B0, 0, 0); PG8_SCHED; PG8_LDA(At, 0, 0); PG8_STAGE(PG8_SA(1, 1), a1 + hstep, voffA);
;             PG8_WAIT_L(8); PG8_BAR; PG8_WAIT_L(0); PG8_MMA(0, 0, At, B0); PG8_BAR; PG8_SCHED;
;     ...
;             PG8_WAIT_V(6); PG8_BAR; PG8_MMA(1, 1, At, B1); PG8_BAR;
;             PG8_LDB(B0, 1, 0); PG8_SCHED; PG8_LDA(At, 1, 0); PG8_STAGE(PG8_SA(0, 1), a2 + hstep, voffA);
;             PG8_WAIT_L(8); PG8_BAR; PG8_WAIT_L(0); PG8_MMA(0, 0, At, B0); PG8_BAR; PG8_SCHED;
;             PG8_LDB(B1, 1, 1); PG8_STAGE(PG8_SB(1, 0), b3, voffB);
;             PG8_BAR; PG8_WAIT_L(0); PG8_MMA(0, 1, At, B1); PG8_BAR;
;             PG8_LDA(At, 1, 1); PG8_STAGE(PG8_SA(1, 0), a3, voffA);
;             PG8_BAR; PG8_WAIT_L(0); PG8_MMA(1, 0, At, B0); PG8_BAR; PG8_SCHED;
;             PG8_STAGE(PG8_SB(1, 1), b3 + hstep, voffB);
;             PG8_WAIT_V(6); PG8_BAR; PG8_MMA(1, 1, At, B1); PG8_BAR;
	s_waitcnt lgkmcnt(7)
	v_mfma_f32_16x16x32_bf16 v[60:63], v[152:155], v[168:171], v[60:63]
	v_mfma_f32_16x16x32_bf16 v[56:59], v[160:163], v[168:171], v[56:59]
	s_waitcnt lgkmcnt(5)
	v_mfma_f32_16x16x32_bf16 v[44:47], v[152:155], v[176:179], v[44:47]
	v_mfma_f32_16x16x32_bf16 v[40:43], v[160:163], v[176:179], v[40:43]
	s_waitcnt lgkmcnt(3)
	v_mfma_f32_16x16x32_bf16 v[28:31], v[152:155], v[186:189], v[28:31]
	v_mfma_f32_16x16x32_bf16 v[24:27], v[160:163], v[186:189], v[24:27]
	s_waitcnt lgkmcnt(1)
	v_mfma_f32_16x16x32_bf16 v[12:15], v[152:155], v[194:197], v[12:15]
	v_mfma_f32_16x16x32_bf16 v[8:11], v[160:163], v[194:197], v[8:11]
	v_mfma_f32_16x16x32_bf16 v[60:63], v[156:159], v[172:175], v[60:63]
	v_mfma_f32_16x16x32_bf16 v[56:59], v[164:167], v[172:175], v[56:59]
	v_mfma_f32_16x16x32_bf16 v[44:47], v[156:159], v[182:185], v[44:47]
	v_mfma_f32_16x16x32_bf16 v[40:43], v[164:167], v[182:185], v[40:43]
	v_mfma_f32_16x16x32_bf16 v[28:31], v[156:159], v[190:193], v[28:31]
	v_mfma_f32_16x16x32_bf16 v[24:27], v[164:167], v[190:193], v[24:27]
	s_add_u32 s36, s36, 0x40080
	s_addc_u32 s37, s37, 0
	s_waitcnt lgkmcnt(0)
	v_mfma_f32_16x16x32_bf16 v[12:15], v[156:159], v[198:201], v[12:15]
	s_add_i32 s38, s38, s45
	s_mov_b32 m0, s38
	v_mfma_f32_16x16x32_bf16 v[8:11], v[164:167], v[198:201], v[8:11]
	s_barrier
	global_load_lds_dwordx4 v132, s[36:37]
	s_add_i32 m0, s38, 0x2000
	s_nop 0
	global_load_lds_dwordx4 v128, s[36:37]
	s_waitcnt vmcnt(6)
	s_barrier
	v_mfma_f32_16x16x32_bf16 v[52:55], v[202:205], v[168:171], v[52:55]
	v_mfma_f32_16x16x32_bf16 v[48:51], v[210:213], v[168:171], v[48:51]
	v_mfma_f32_16x16x32_bf16 v[36:39], v[202:205], v[176:179], v[36:39]
	v_mfma_f32_16x16x32_bf16 v[32:35], v[210:213], v[176:179], v[32:35]
	v_mfma_f32_16x16x32_bf16 v[20:23], v[202:205], v[186:189], v[20:23]
	v_mfma_f32_16x16x32_bf16 v[16:19], v[210:213], v[186:189], v[16:19]
	v_mfma_f32_16x16x32_bf16 v[4:7], v[202:205], v[194:197], v[4:7]
	v_mfma_f32_16x16x32_bf16 v[0:3], v[210:213], v[194:197], v[0:3]
	v_mfma_f32_16x16x32_bf16 v[52:55], v[206:209], v[172:175], v[52:55]
	s_add_i32 s63, s63, 2
	s_add_u32 s24, s24, 0x100
	v_mfma_f32_16x16x32_bf16 v[48:51], v[214:217], v[172:175], v[48:51]
	s_addc_u32 s25, s25, 0
	s_add_u32 s61, s61, 0x100
	v_mfma_f32_16x16x32_bf16 v[36:39], v[206:209], v[182:185], v[36:39]
	s_addc_u32 s62, s62, 0
	s_add_u32 s36, s24, 0xfffc0080
	v_mfma_f32_16x16x32_bf16 v[32:35], v[214:217], v[182:185], v[32:35]
	s_addc_u32 s37, s25, -1
	s_cmp_eq_u32 s63, 12
	v_mfma_f32_16x16x32_bf16 v[20:23], v[206:209], v[190:193], v[20:23]
	s_cselect_b32 s39, s17, s37
	s_cselect_b32 s38, s59, s36
	v_mfma_f32_16x16x32_bf16 v[16:19], v[214:217], v[190:193], v[16:19]
	s_cselect_b32 s37, s15, s62
	s_cselect_b32 s36, s60, s61
	v_mfma_f32_16x16x32_bf16 v[4:7], v[206:209], v[198:201], v[4:7]
	s_add_i32 m0, s23, 0xc000
	v_mfma_f32_16x16x32_bf16 v[0:3], v[214:217], v[198:201], v[0:3]
	s_cmp_gt_u32 s63, 13
	s_barrier
.LBB0_849:
	ds_read_b128 v[152:155], v149
	ds_read_b128 v[156:159], v149 offset:1024
	ds_read_b128 v[160:163], v149 offset:2048
	ds_read_b128 v[164:167], v149 offset:3072
	ds_read_b128 v[168:171], v150
	ds_read_b128 v[172:175], v150 offset:1024
	ds_read_b128 v[176:179], v150 offset:2048
	ds_read_b128 v[182:185], v150 offset:3072
	ds_read_b128 v[186:189], v150 offset:4096
	ds_read_b128 v[190:193], v150 offset:5120
	ds_read_b128 v[194:197], v150 offset:6144
	ds_read_b128 v[198:201], v150 offset:7168
	global_load_lds_dwordx4 v136, s[24:25]
	s_add_i32 m0, s23, 0xe000
	s_nop 0
	global_load_lds_dwordx4 v138, s[24:25]
	s_waitcnt lgkmcnt(8)
	s_barrier
	s_waitcnt lgkmcnt(7)
	v_mfma_f32_16x16x32_bf16 v[124:127], v[152:155], v[168:171], v[124:127]
	v_mfma_f32_16x16x32_bf16 v[120:123], v[160:163], v[168:171], v[120:123]
	s_waitcnt lgkmcnt(5)
	v_mfma_f32_16x16x32_bf16 v[108:111], v[152:155], v[176:179], v[108:111]
	v_mfma_f32_16x16x32_bf16 v[104:107], v[160:163], v[176:179], v[104:107]
	s_waitcnt lgkmcnt(3)
	v_mfma_f32_16x16x32_bf16 v[92:95], v[152:155], v[186:189], v[92:95]
	v_mfma_f32_16x16x32_bf16 v[88:91], v[160:163], v[186:189], v[88:91]
	s_waitcnt lgkmcnt(1)
	v_mfma_f32_16x16x32_bf16 v[76:79], v[152:155], v[194:197], v[76:79]
	v_mfma_f32_16x16x32_bf16 v[72:75], v[160:163], v[194:197], v[72:75]
	v_mfma_f32_16x16x32_bf16 v[124:127], v[156:159], v[172:175], v[124:127]
	v_mfma_f32_16x16x32_bf16 v[120:123], v[164:167], v[172:175], v[120:123]
	v_mfma_f32_16x16x32_bf16 v[108:111], v[156:159], v[182:185], v[108:111]
	v_mfma_f32_16x16x32_bf16 v[104:107], v[164:167], v[182:185], v[104:107]
	v_mfma_f32_16x16x32_bf16 v[92:95], v[156:159], v[190:193], v[92:95]
	v_mfma_f32_16x16x32_bf16 v[88:91], v[164:167], v[190:193], v[88:91]
	s_add_i32 s64, s55, s45
	s_add_u32 s86, s36, s12
	s_waitcnt lgkmcnt(0)
	v_mfma_f32_16x16x32_bf16 v[76:79], v[156:159], v[198:201], v[76:79]
	s_addc_u32 s87, s37, s13
	s_mov_b32 m0, s64
	v_mfma_f32_16x16x32_bf16 v[72:75], v[164:167], v[198:201], v[72:75]
	s_barrier
	ds_read_b128 v[202:205], v151
	ds_read_b128 v[206:209], v151 offset:1024
	ds_read_b128 v[210:213], v151 offset:2048
	ds_read_b128 v[214:217], v151 offset:3072
	global_load_lds_dwordx4 v132, s[36:37]
	s_add_i32 m0, s64, 0x2000
	s_nop 0
	global_load_lds_dwordx4 v128, s[36:37]
	s_barrier
; #define PG8_STAGE(bufoff, gbase, voff) do { _Pragma("unroll") for (int _i = 0; _i < 2; ++_i) \
;         __builtin_amdgcn_global_load_lds((const unsigned*)((const char*)(gbase) + (voff)[_i]), (LAS unsigned*)(lds + (bufoff) + ldsw + _i * 8192), 16, 0, 0); } while (0)
; #define PG8_LDA(dst, b, h) do { _Pragma("unroll") for (int m = 0; m < 4; ++m) _Pragma("unroll") for (int k = 0; k < 2; ++k) dst[m][k] = *(const LAS bf16x8*)(lds + PG8_SA(b, h) + aoff + m * 2048 + k * 1024); } while (0)
; #define PG8_LDB(dst, b, h) do { _Pragma("unroll") for (int n = 0; n < 2; ++n) _Pragma("unroll") for (int k = 0; k < 2; ++k) dst[n][k] = *(const LAS bf16x8*)(lds + PG8_SB(b, h) + boff + n * 2048 + k * 1024); } while (0)
; #define PG8_MMA(ai, bj, At, Bt) do { __builtin_amdgcn_s_setprio(1); _Pragma("unroll") for (int m = 0; m < 4; ++m) _Pragma("unroll") for (int n = 0; n < 2; ++n) _Pragma("unroll") for (int k = 0; k < 2; ++k) \
;         acc[ai][bj][m][n] = __builtin_amdgcn_mfma_f32_16x16x32_bf16(Bt[n][k], At[m][k], acc[ai][bj][m][n], 0, 0, 0); __builtin_amdgcn_s_setprio(0); } while (0)
; #define PG8_WAIT_V(n) asm volatile("s_waitcnt vmcnt(" #n ")" ::: "memory")
; #define PG8_WAIT_L(n) asm volatile("s_waitcnt lgkmcnt(" #n ")" ::: "memory")
; #define PG8_BAR __builtin_amdgcn_s_barrier()
; #define PG8_SCHED __builtin_amdgcn_sched_barrier(0)
; template <class Epi>
; DI void gemm_phase(LAS unsigned char* lds, const Gemm g, const StaticOrder& S, const Epi& E) {
;     ...
;             PG8_LDB(B1, 0, 1); PG8_STAGE(PG8_SB(0, 0), b2, voffB);
;             PG8_BAR; PG8_WAIT_L(0); PG8_MMA(0, 1, At, B1); PG8_BAR;
;             PG8_LDA(At, 0, 1); PG8_STAGE(PG8_SA(0, 0), a2, voffA);
;             PG8_BAR; PG8_WAIT_L(0); PG8_MMA(1, 0, At, B0); PG8_BAR; PG8_SCHED;
;             PG8_STAGE(PG8_SB(0, 1), b2 + hstep, voffB);
;             PG8_WAIT_V(6); PG8_BAR; PG8_MMA(1, 1, At, B1); PG8_BAR;
;             PG8_LDB(B0, 1, 0); PG8_SCHED; PG8_LDA(At, 1, 0); PG8_STAGE(PG8_SA(0, 1), a2 + hstep, voffA);
	s_waitcnt lgkmcnt(3)
	v_mfma_f32_16x16x32_bf16 v[116:119], v[202:205], v[168:171], v[116:119]
	s_waitcnt lgkmcnt(1)
	v_mfma_f32_16x16x32_bf16 v[112:115], v[210:213], v[168:171], v[112:115]
	v_mfma_f32_16x16x32_bf16 v[100:103], v[202:205], v[176:179], v[100:103]
	v_mfma_f32_16x16x32_bf16 v[96:99], v[210:213], v[176:179], v[96:99]
	v_mfma_f32_16x16x32_bf16 v[84:87], v[202:205], v[186:189], v[84:87]
	v_mfma_f32_16x16x32_bf16 v[80:83], v[210:213], v[186:189], v[80:83]
	v_mfma_f32_16x16x32_bf16 v[68:71], v[202:205], v[194:197], v[68:71]
	v_mfma_f32_16x16x32_bf16 v[64:67], v[210:213], v[194:197], v[64:67]
	v_mfma_f32_16x16x32_bf16 v[116:119], v[206:209], v[172:175], v[116:119]
	s_waitcnt lgkmcnt(0)
	v_mfma_f32_16x16x32_bf16 v[112:115], v[214:217], v[172:175], v[112:115]
	v_mfma_f32_16x16x32_bf16 v[100:103], v[206:209], v[182:185], v[100:103]
	v_mfma_f32_16x16x32_bf16 v[96:99], v[214:217], v[182:185], v[96:99]
	v_mfma_f32_16x16x32_bf16 v[84:87], v[206:209], v[190:193], v[84:87]
	v_mfma_f32_16x16x32_bf16 v[80:83], v[214:217], v[190:193], v[80:83]
	s_mov_b32 m0, s23
	s_add_u32 s88, s38, s12
	v_mfma_f32_16x16x32_bf16 v[68:71], v[206:209], v[198:201], v[68:71]
	s_addc_u32 s89, s39, s13
	v_mfma_f32_16x16x32_bf16 v[64:67], v[214:217], v[198:201], v[64:67]
	s_barrier
	ds_read_b128 v[168:171], v150 offset:16384
	ds_read_b128 v[172:175], v150 offset:17408
	ds_read_b128 v[176:179], v150 offset:18432
	ds_read_b128 v[182:185], v150 offset:19456
	ds_read_b128 v[186:189], v150 offset:20480
	ds_read_b128 v[190:193], v150 offset:21504
	ds_read_b128 v[194:197], v150 offset:22528
	ds_read_b128 v[198:201], v150 offset:23552
	global_load_lds_dwordx4 v134, s[38:39]
	s_mov_b32 m0, s48
	s_nop 0
	global_load_lds_dwordx4 v130, s[38:39]
	s_barrier
	s_waitcnt lgkmcnt(7)
	v_mfma_f32_16x16x32_bf16 v[60:63], v[152:155], v[168:171], v[60:63]
	v_mfma_f32_16x16x32_bf16 v[56:59], v[160:163], v[168:171], v[56:59]
	s_waitcnt lgkmcnt(5)
	v_mfma_f32_16x16x32_bf16 v[44:47], v[152:155], v[176:179], v[44:47]
	v_mfma_f32_16x16x32_bf16 v[40:43], v[160:163], v[176:179], v[40:43]
	s_waitcnt lgkmcnt(3)
	v_mfma_f32_16x16x32_bf16 v[28:31], v[152:155], v[186:189], v[28:31]
	v_mfma_f32_16x16x32_bf16 v[24:27], v[160:163], v[186:189], v[24:27]
	s_waitcnt lgkmcnt(1)
	v_mfma_f32_16x16x32_bf16 v[12:15], v[152:155], v[194:197], v[12:15]
	v_mfma_f32_16x16x32_bf16 v[8:11], v[160:163], v[194:197], v[8:11]
	v_mfma_f32_16x16x32_bf16 v[60:63], v[156:159], v[172:175], v[60:63]
	v_mfma_f32_16x16x32_bf16 v[56:59], v[164:167], v[172:175], v[56:59]
	v_mfma_f32_16x16x32_bf16 v[44:47], v[156:159], v[182:185], v[44:47]
	v_mfma_f32_16x16x32_bf16 v[40:43], v[164:167], v[182:185], v[40:43]
	v_mfma_f32_16x16x32_bf16 v[28:31], v[156:159], v[190:193], v[28:31]
	v_mfma_f32_16x16x32_bf16 v[24:27], v[164:167], v[190:193], v[24:27]
	s_add_u32 s64, s36, 0x40000
	s_addc_u32 s65, s37, 0
	s_waitcnt lgkmcnt(0)
	v_mfma_f32_16x16x32_bf16 v[12:15], v[156:159], v[198:201], v[12:15]
	s_add_i32 s66, s56, s45
	s_mov_b32 m0, s66
	v_mfma_f32_16x16x32_bf16 v[8:11], v[164:167], v[198:201], v[8:11]
	s_barrier
	global_load_lds_dwordx4 v132, s[64:65]
	s_add_i32 m0, s66, 0x2000
	s_nop 0
	global_load_lds_dwordx4 v128, s[64:65]
	s_waitcnt vmcnt(6)
	s_barrier
	v_mfma_f32_16x16x32_bf16 v[52:55], v[202:205], v[168:171], v[52:55]
	v_mfma_f32_16x16x32_bf16 v[48:51], v[210:213], v[168:171], v[48:51]
	v_mfma_f32_16x16x32_bf16 v[36:39], v[202:205], v[176:179], v[36:39]
	v_mfma_f32_16x16x32_bf16 v[32:35], v[210:213], v[176:179], v[32:35]
	v_mfma_f32_16x16x32_bf16 v[20:23], v[202:205], v[186:189], v[20:23]
	v_mfma_f32_16x16x32_bf16 v[16:19], v[210:213], v[186:189], v[16:19]
	v_mfma_f32_16x16x32_bf16 v[4:7], v[202:205], v[194:197], v[4:7]
	v_mfma_f32_16x16x32_bf16 v[0:3], v[210:213], v[194:197], v[0:3]
	v_mfma_f32_16x16x32_bf16 v[52:55], v[206:209], v[172:175], v[52:55]
	v_mfma_f32_16x16x32_bf16 v[48:51], v[214:217], v[172:175], v[48:51]
	v_mfma_f32_16x16x32_bf16 v[36:39], v[206:209], v[182:185], v[36:39]
	v_mfma_f32_16x16x32_bf16 v[32:35], v[214:217], v[182:185], v[32:35]
	v_mfma_f32_16x16x32_bf16 v[20:23], v[206:209], v[190:193], v[20:23]
	v_mfma_f32_16x16x32_bf16 v[16:19], v[214:217], v[190:193], v[16:19]
	v_mfma_f32_16x16x32_bf16 v[4:7], v[206:209], v[198:201], v[4:7]
	s_add_i32 s64, 0, 0x18000
	v_mfma_f32_16x16x32_bf16 v[0:3], v[214:217], v[198:201], v[0:3]
	s_barrier
	ds_read_b128 v[152:155], v253
	ds_read_b128 v[156:159], v253 offset:1024
	ds_read_b128 v[160:163], v253 offset:2048
	ds_read_b128 v[164:167], v253 offset:3072
	s_add_u32 s38, s38, 0x40000
	s_addc_u32 s39, s39, 0
	s_mov_b32 m0, s49
	ds_read_b128 v[168:171], v150 offset:32768
	ds_read_b128 v[172:175], v150 offset:33792
	ds_read_b128 v[176:179], v150 offset:34816
	ds_read_b128 v[182:185], v150 offset:35840
	ds_read_b128 v[186:189], v150 offset:36864
	ds_read_b128 v[190:193], v150 offset:37888
	ds_read_b128 v[194:197], v150 offset:38912
	ds_read_b128 v[198:201], v150 offset:39936
	global_load_lds_dwordx4 v134, s[38:39]
	s_mov_b32 m0, s50
	s_nop 0
	global_load_lds_dwordx4 v130, s[38:39]
	s_waitcnt lgkmcnt(8)
	s_barrier
; #define PG8_STAGE(bufoff, gbase, voff) do { _Pragma("unroll") for (int _i = 0; _i < 2; ++_i) \
;         __builtin_amdgcn_global_load_lds((const unsigned*)((const char*)(gbase) + (voff)[_i]), (LAS unsigned*)(lds + (bufoff) + ldsw + _i * 8192), 16, 0, 0); } while (0)
; #define PG8_LDA(dst, b, h) do { _Pragma("unroll") for (int m = 0; m < 4; ++m) _Pragma("unroll") for (int k = 0; k < 2; ++k) dst[m][k] = *(const LAS bf16x8*)(lds + PG8_SA(b, h) + aoff + m * 2048 + k * 1024); } while (0)
; #define PG8_LDB(dst, b, h) do { _Pragma("unroll") for (int n = 0; n < 2; ++n) _Pragma("unroll") for (int k = 0; k < 2; ++k) dst[n][k] = *(const LAS bf16x8*)(lds + PG8_SB(b, h) + boff + n * 2048 + k * 1024); } while (0)
; #define PG8_MMA(ai, bj, At, Bt) do { __builtin_amdgcn_s_setprio(1); _Pragma("unroll") for (int m = 0; m < 4; ++m) _Pragma("unroll") for (int n = 0; n < 2; ++n) _Pragma("unroll") for (int k = 0; k < 2; ++k) \
;         acc[ai][bj][m][n] = __builtin_amdgcn_mfma_f32_16x16x32_bf16(Bt[n][k], At[m][k], acc[ai][bj][m][n], 0, 0, 0); __builtin_amdgcn_s_setprio(0); } while (0)
; #define PG8_WAIT_V(n) asm volatile("s_waitcnt vmcnt(" #n ")" ::: "memory")
; #define PG8_WAIT_L(n) asm volatile("s_waitcnt lgkmcnt(" #n ")" ::: "memory")
; #define PG8_BAR __builtin_amdgcn_s_barrier()
; #define PG8_SCHED __builtin_amdgcn_sched_barrier(0)
; template <class Epi>
; DI void gemm_phase(LAS unsigned char* lds, const Gemm g, const StaticOrder& S, const Epi& E) {
;     ...
;             PG8_LDB(B0, 1, 0); PG8_SCHED; PG8_LDA(At, 1, 0); PG8_STAGE(PG8_SA(0, 1), a2 + hstep, voffA);
;             PG8_WAIT_L(8); PG8_BAR; PG8_WAIT_L(0); PG8_MMA(0, 0, At, B0); PG8_BAR; PG8_SCHED;
;             PG8_LDB(B1, 1, 1); PG8_STAGE(PG8_SB(1, 0), b3, voffB);
;             PG8_BAR; PG8_WAIT_L(0); PG8_MMA(0, 1, At, B1); PG8_BAR;
;             PG8_LDA(At, 1, 1); PG8_STAGE(PG8_SA(1, 0), a3, voffA);
;             PG8_BAR; PG8_WAIT_L(0); PG8_MMA(1, 0, At, B0); PG8_BAR; PG8_SCHED;
;             PG8_STAGE(PG8_SB(1, 1), b3 + hstep, voffB);
;             PG8_WAIT_V(6); PG8_BAR; PG8_MMA(1, 1, At, B1); PG8_BAR;
	s_waitcnt lgkmcnt(7)
	v_mfma_f32_16x16x32_bf16 v[124:127], v[152:155], v[168:171], v[124:127]
	v_mfma_f32_16x16x32_bf16 v[120:123], v[160:163], v[168:171], v[120:123]
	s_waitcnt lgkmcnt(5)
	v_mfma_f32_16x16x32_bf16 v[108:111], v[152:155], v[176:179], v[108:111]
	v_mfma_f32_16x16x32_bf16 v[104:107], v[160:163], v[176:179], v[104:107]
	s_waitcnt lgkmcnt(3)
	v_mfma_f32_16x16x32_bf16 v[92:95], v[152:155], v[186:189], v[92:95]
	v_mfma_f32_16x16x32_bf16 v[88:91], v[160:163], v[186:189], v[88:91]
	s_waitcnt lgkmcnt(1)
	v_mfma_f32_16x16x32_bf16 v[76:79], v[152:155], v[194:197], v[76:79]
	v_mfma_f32_16x16x32_bf16 v[72:75], v[160:163], v[194:197], v[72:75]
	v_mfma_f32_16x16x32_bf16 v[124:127], v[156:159], v[172:175], v[124:127]
	v_mfma_f32_16x16x32_bf16 v[120:123], v[164:167], v[172:175], v[120:123]
	v_mfma_f32_16x16x32_bf16 v[108:111], v[156:159], v[182:185], v[108:111]
	v_mfma_f32_16x16x32_bf16 v[104:107], v[164:167], v[182:185], v[104:107]
	v_mfma_f32_16x16x32_bf16 v[92:95], v[156:159], v[190:193], v[92:95]
	v_mfma_f32_16x16x32_bf16 v[88:91], v[164:167], v[190:193], v[88:91]
	s_add_i32 s38, 0, 0x1c000
	s_add_i32 s39, s64, s45
	s_waitcnt lgkmcnt(0)
	v_mfma_f32_16x16x32_bf16 v[76:79], v[156:159], v[198:201], v[76:79]
	s_mov_b32 m0, s39
	v_mfma_f32_16x16x32_bf16 v[72:75], v[164:167], v[198:201], v[72:75]
	s_barrier
	ds_read_b128 v[202:205], v252
	ds_read_b128 v[206:209], v252 offset:1024
	ds_read_b128 v[210:213], v252 offset:2048
	ds_read_b128 v[214:217], v252 offset:3072
	global_load_lds_dwordx4 v132, s[86:87]
	s_add_i32 m0, s39, 0x2000
	s_nop 0
	global_load_lds_dwordx4 v128, s[86:87]
	s_barrier
	s_waitcnt lgkmcnt(3)
	v_mfma_f32_16x16x32_bf16 v[116:119], v[202:205], v[168:171], v[116:119]
	s_waitcnt lgkmcnt(1)
	v_mfma_f32_16x16x32_bf16 v[112:115], v[210:213], v[168:171], v[112:115]
	v_mfma_f32_16x16x32_bf16 v[100:103], v[202:205], v[176:179], v[100:103]
	v_mfma_f32_16x16x32_bf16 v[96:99], v[210:213], v[176:179], v[96:99]
	v_mfma_f32_16x16x32_bf16 v[84:87], v[202:205], v[186:189], v[84:87]
	v_mfma_f32_16x16x32_bf16 v[80:83], v[210:213], v[186:189], v[80:83]
	v_mfma_f32_16x16x32_bf16 v[68:71], v[202:205], v[194:197], v[68:71]
	v_mfma_f32_16x16x32_bf16 v[64:67], v[210:213], v[194:197], v[64:67]
	v_mfma_f32_16x16x32_bf16 v[116:119], v[206:209], v[172:175], v[116:119]
	s_waitcnt lgkmcnt(0)
	v_mfma_f32_16x16x32_bf16 v[112:115], v[214:217], v[172:175], v[112:115]
	v_mfma_f32_16x16x32_bf16 v[100:103], v[206:209], v[182:185], v[100:103]
	v_mfma_f32_16x16x32_bf16 v[96:99], v[214:217], v[182:185], v[96:99]
	v_mfma_f32_16x16x32_bf16 v[84:87], v[206:209], v[190:193], v[84:87]
	v_mfma_f32_16x16x32_bf16 v[80:83], v[214:217], v[190:193], v[80:83]
	v_mfma_f32_16x16x32_bf16 v[68:71], v[206:209], v[198:201], v[68:71]
	s_mov_b32 m0, s52
	v_mfma_f32_16x16x32_bf16 v[64:67], v[214:217], v[198:201], v[64:67]
	s_barrier
	ds_read_b128 v[168:171], v150 offset:49152
	ds_read_b128 v[172:175], v150 offset:50176
	ds_read_b128 v[176:179], v150 offset:51200
	ds_read_b128 v[182:185], v150 offset:52224
	ds_read_b128 v[186:189], v150 offset:53248
	ds_read_b128 v[190:193], v150 offset:54272
	ds_read_b128 v[194:197], v150 offset:55296
	ds_read_b128 v[198:201], v150 offset:56320
	global_load_lds_dwordx4 v134, s[88:89]
	s_mov_b32 m0, s53
	s_nop 0
	global_load_lds_dwordx4 v130, s[88:89]
	s_barrier
	s_waitcnt lgkmcnt(7)
	v_mfma_f32_16x16x32_bf16 v[60:63], v[152:155], v[168:171], v[60:63]
	v_mfma_f32_16x16x32_bf16 v[56:59], v[160:163], v[168:171], v[56:59]
	s_waitcnt lgkmcnt(5)
	v_mfma_f32_16x16x32_bf16 v[44:47], v[152:155], v[176:179], v[44:47]
	v_mfma_f32_16x16x32_bf16 v[40:43], v[160:163], v[176:179], v[40:43]
	s_waitcnt lgkmcnt(3)
	v_mfma_f32_16x16x32_bf16 v[28:31], v[152:155], v[186:189], v[28:31]
	v_mfma_f32_16x16x32_bf16 v[24:27], v[160:163], v[186:189], v[24:27]
	s_waitcnt lgkmcnt(1)
	v_mfma_f32_16x16x32_bf16 v[12:15], v[152:155], v[194:197], v[12:15]
	v_mfma_f32_16x16x32_bf16 v[8:11], v[160:163], v[194:197], v[8:11]
	v_mfma_f32_16x16x32_bf16 v[60:63], v[156:159], v[172:175], v[60:63]
	v_mfma_f32_16x16x32_bf16 v[56:59], v[164:167], v[172:175], v[56:59]
	v_mfma_f32_16x16x32_bf16 v[44:47], v[156:159], v[182:185], v[44:47]
	v_mfma_f32_16x16x32_bf16 v[40:43], v[164:167], v[182:185], v[40:43]
	v_mfma_f32_16x16x32_bf16 v[28:31], v[156:159], v[190:193], v[28:31]
	v_mfma_f32_16x16x32_bf16 v[24:27], v[164:167], v[190:193], v[24:27]
	s_add_u32 s36, s36, 0x40080
	s_addc_u32 s37, s37, 0
	s_waitcnt lgkmcnt(0)
	v_mfma_f32_16x16x32_bf16 v[12:15], v[156:159], v[198:201], v[12:15]
	s_add_i32 s38, s38, s45
	s_mov_b32 m0, s38
	v_mfma_f32_16x16x32_bf16 v[8:11], v[164:167], v[198:201], v[8:11]
	s_barrier
	global_load_lds_dwordx4 v132, s[36:37]
	s_add_i32 m0, s38, 0x2000
	s_nop 0
	global_load_lds_dwordx4 v128, s[36:37]
	s_waitcnt vmcnt(6)
	s_barrier
	v_mfma_f32_16x16x32_bf16 v[52:55], v[202:205], v[168:171], v[52:55]
	v_mfma_f32_16x16x32_bf16 v[48:51], v[210:213], v[168:171], v[48:51]
	v_mfma_f32_16x16x32_bf16 v[36:39], v[202:205], v[176:179], v[36:39]
	v_mfma_f32_16x16x32_bf16 v[32:35], v[210:213], v[176:179], v[32:35]
	v_mfma_f32_16x16x32_bf16 v[20:23], v[202:205], v[186:189], v[20:23]
	v_mfma_f32_16x16x32_bf16 v[16:19], v[210:213], v[186:189], v[16:19]
	v_mfma_f32_16x16x32_bf16 v[4:7], v[202:205], v[194:197], v[4:7]
	v_mfma_f32_16x16x32_bf16 v[0:3], v[210:213], v[194:197], v[0:3]
	v_mfma_f32_16x16x32_bf16 v[52:55], v[206:209], v[172:175], v[52:55]
	s_add_i32 s63, s63, 2
	s_add_u32 s24, s24, 0x100
	v_mfma_f32_16x16x32_bf16 v[48:51], v[214:217], v[172:175], v[48:51]
	s_addc_u32 s25, s25, 0
	s_add_u32 s61, s61, 0x100
	v_mfma_f32_16x16x32_bf16 v[36:39], v[206:209], v[182:185], v[36:39]
	s_addc_u32 s62, s62, 0
	s_add_u32 s36, s24, 0xfffc0080
	v_mfma_f32_16x16x32_bf16 v[32:35], v[214:217], v[182:185], v[32:35]
	s_addc_u32 s37, s25, -1
	s_cmp_eq_u32 s63, 12
	v_mfma_f32_16x16x32_bf16 v[20:23], v[206:209], v[190:193], v[20:23]
	s_cselect_b32 s39, s17, s37
	s_cselect_b32 s38, s59, s36
	v_mfma_f32_16x16x32_bf16 v[16:19], v[214:217], v[190:193], v[16:19]
	s_cselect_b32 s37, s15, s62
	s_cselect_b32 s36, s60, s61
	v_mfma_f32_16x16x32_bf16 v[4:7], v[206:209], v[198:201], v[4:7]
	s_add_i32 m0, s23, 0xc000
	v_mfma_f32_16x16x32_bf16 v[0:3], v[214:217], v[198:201], v[0:3]
	s_cmp_gt_u32 s63, 13
	s_barrier
; DI unsigned pk2(float a, float b) { f32x2 v = {a, b}; bf16x2_t r = __builtin_convertvector(v, bf16x2_t); return __builtin_bit_cast(unsigned, r); }
; DI float siluf_(float x) { return x * __builtin_amdgcn_rcpf(1.f + __expf(-x)); }
; template <class Epi>
; DI void gemm_phase(LAS unsigned char* lds, const Gemm g, const StaticOrder& S, const Epi& E) {
;     ...
;         if (!has_next) break;
;     DI void operator()(const f32x4 (&acc)[2][2][4][2], const Unit& u, int wr, int wc, int fr, int fq) const {
;         const int row0 = u.pm * BM + wr * 64 + fr, col0 = u.pn * HALF + wc * 32 + 8 * fq;
; #pragma unroll
;         for (int ai = 0; ai < 2; ++ai)
; #pragma unroll
;             for (int m = 0; m < 4; ++m) { bf16_t* rowp = O + (size_t)(row0 + ai * HALF + m * 16) * DFF + col0;
;                 f32x4 v0, v1;
; #pragma unroll
;                 for (int j = 0; j < 4; ++j) { v0[j] = siluf_(acc[ai][0][m][0][j]) * acc[ai][1][m][0][j]; v1[j] = siluf_(acc[ai][0][m][1][j]) * acc[ai][1][m][1][j]; }
;                 u32x4 w; w.x = pk2(v0[0], v0[1]); w.y = pk2(v0[2], v0[3]); w.z = pk2(v1[0], v1[1]); w.w = pk2(v1[2], v1[3]);
;                 *(u32x4*)rowp = w; }
	s_cbranch_scc0 .LBB0_849
	v_mul_f32_e32 v153, 0xbfb8aa3b, v124
	v_mul_f32_e32 v158, 0xbfb8aa3b, v120
	v_exp_f32_e32 v153, v153
	v_exp_f32_e32 v159, v158
	v_mul_f32_e32 v158, 0xbfb8aa3b, v125
	v_exp_f32_e32 v160, v158
	v_add_f32_e32 v153, 1.0, v153
	v_rcp_f32_e32 v158, v153
	v_add_f32_e32 v153, 1.0, v159
	v_add_f32_e32 v159, 1.0, v160
	v_rcp_f32_e32 v159, v159
	v_mul_f32_e32 v160, 0xbfb8aa3b, v121
	v_exp_f32_e32 v161, v160
	v_rcp_f32_e32 v160, v153
	v_pk_mul_f32 v[124:125], v[124:125], v[158:159]
	v_mul_f32_e32 v153, 0xbfb8aa3b, v127
	v_pk_mul_f32 v[116:117], v[124:125], v[116:117]
	v_add_f32_e32 v124, 1.0, v161
	v_mul_f32_e32 v125, 0xbfb8aa3b, v122
	v_rcp_f32_e32 v161, v124
	v_mul_f32_e32 v124, 0xbfb8aa3b, v126
	v_exp_f32_e32 v125, v125
	v_exp_f32_e32 v124, v124
	v_exp_f32_e32 v153, v153
	v_mul_f32_e32 v158, 0xbfb8aa3b, v123
	v_exp_f32_e32 v159, v158
	v_add_f32_e32 v125, 1.0, v125
	v_add_f32_e32 v124, 1.0, v124
	v_rcp_f32_e32 v158, v125
	v_add_f32_e32 v125, 1.0, v153
	v_rcp_f32_e32 v124, v124
	v_rcp_f32_e32 v125, v125
	v_add_f32_e32 v153, 1.0, v159
	v_rcp_f32_e32 v159, v153
	v_pk_mul_f32 v[120:121], v[120:121], v[160:161]
	v_lshl_or_b32 v154, s58, 7, v148
	v_pk_mul_f32 v[120:121], v[120:121], v[112:113]
	v_pk_mul_f32 v[112:113], v[126:127], v[124:125]
	v_lshl_add_u32 v152, s22, 8, v146
	v_ashrrev_i32_e32 v155, 31, v154
	v_mov_b64_e32 v[144:145], s[8:9]
	v_pk_mul_f32 v[118:119], v[112:113], v[118:119]
	v_pk_mul_f32 v[112:113], v[122:123], v[158:159]
	v_mad_i64_i32 v[156:157], s[24:25], v152, s57, v[144:145]
	v_pk_mul_f32 v[122:123], v[112:113], v[114:115]
	v_lshlrev_b64 v[112:113], 1, v[154:155]
	v_lshl_add_u64 v[124:125], v[156:157], 0, v[112:113]
	v_cvt_pk_bf16_f32 v114, v116, v117
	v_cvt_pk_bf16_f32 v115, v118, v119
	v_cvt_pk_bf16_f32 v116, v120, v121
	v_cvt_pk_bf16_f32 v117, v122, v123
	global_store_dwordx4 v[124:125], v[114:117], off
	v_mul_f32_e32 v118, 0xbfb8aa3b, v109
	v_exp_f32_e32 v118, v118
	v_mul_f32_e32 v116, 0xbfb8aa3b, v108
	v_mul_f32_e32 v117, 0xbfb8aa3b, v104
	v_exp_f32_e32 v116, v116
	v_exp_f32_e32 v117, v117
	v_or_b32_e32 v114, 16, v152
	v_mad_i64_i32 v[114:115], s[24:25], v114, s57, v[144:145]
	v_add_f32_e32 v116, 1.0, v116
	v_add_f32_e32 v119, 1.0, v117
	v_add_f32_e32 v117, 1.0, v118
	v_rcp_f32_e32 v116, v116
	v_rcp_f32_e32 v117, v117
	v_mul_f32_e32 v118, 0xbfb8aa3b, v105
	v_exp_f32_e32 v120, v118
	v_rcp_f32_e32 v118, v119
	v_pk_mul_f32 v[108:109], v[108:109], v[116:117]
	v_mul_f32_e32 v116, 0xbfb8aa3b, v111
	v_pk_mul_f32 v[100:101], v[108:109], v[100:101]
	v_add_f32_e32 v108, 1.0, v120
	v_rcp_f32_e32 v119, v108
	v_mul_f32_e32 v109, 0xbfb8aa3b, v106
	v_mul_f32_e32 v108, 0xbfb8aa3b, v110
	v_exp_f32_e32 v109, v109
	v_exp_f32_e32 v108, v108
	v_exp_f32_e32 v117, v116
	v_mul_f32_e32 v116, 0xbfb8aa3b, v107
	v_pk_mul_f32 v[104:105], v[104:105], v[118:119]
	v_exp_f32_e32 v118, v116
	v_add_f32_e32 v109, 1.0, v109
	v_add_f32_e32 v108, 1.0, v108
	v_rcp_f32_e32 v116, v109
	v_add_f32_e32 v109, 1.0, v117
	v_rcp_f32_e32 v108, v108
	v_rcp_f32_e32 v109, v109
	v_add_f32_e32 v117, 1.0, v118
	v_rcp_f32_e32 v117, v117
	v_pk_mul_f32 v[104:105], v[104:105], v[96:97]
	v_pk_mul_f32 v[96:97], v[110:111], v[108:109]
	v_lshl_add_u64 v[108:109], v[114:115], 0, v[112:113]
	v_pk_mul_f32 v[102:103], v[96:97], v[102:103]
	v_pk_mul_f32 v[96:97], v[106:107], v[116:117]
	s_and_b64 vcc, exec, s[4:5]
	v_pk_mul_f32 v[106:107], v[96:97], v[98:99]
	v_cvt_pk_bf16_f32 v96, v100, v101
	v_cvt_pk_bf16_f32 v97, v102, v103
	v_cvt_pk_bf16_f32 v98, v104, v105
	v_cvt_pk_bf16_f32 v99, v106, v107
	global_store_dwordx4 v[108:109], v[96:99], off
	v_mul_f32_e32 v100, 0xbfb8aa3b, v93
	v_exp_f32_e32 v100, v100
	v_mul_f32_e32 v98, 0xbfb8aa3b, v92
	v_mul_f32_e32 v99, 0xbfb8aa3b, v88
	v_exp_f32_e32 v98, v98
	v_exp_f32_e32 v99, v99
	v_or_b32_e32 v96, 32, v152
	v_mad_i64_i32 v[96:97], s[24:25], v96, s57, v[144:145]
	v_add_f32_e32 v98, 1.0, v98
	v_add_f32_e32 v101, 1.0, v99
	v_add_f32_e32 v99, 1.0, v100
	v_rcp_f32_e32 v98, v98
	v_rcp_f32_e32 v99, v99
	v_mul_f32_e32 v100, 0xbfb8aa3b, v89
	v_exp_f32_e32 v102, v100
	v_rcp_f32_e32 v100, v101
	v_pk_mul_f32 v[92:93], v[92:93], v[98:99]
	v_mul_f32_e32 v98, 0xbfb8aa3b, v95
	v_pk_mul_f32 v[84:85], v[92:93], v[84:85]
	v_add_f32_e32 v92, 1.0, v102
	v_rcp_f32_e32 v101, v92
	v_mul_f32_e32 v93, 0xbfb8aa3b, v90
	v_mul_f32_e32 v92, 0xbfb8aa3b, v94
	v_exp_f32_e32 v93, v93
	v_exp_f32_e32 v92, v92
	v_exp_f32_e32 v99, v98
	v_mul_f32_e32 v98, 0xbfb8aa3b, v91
	v_pk_mul_f32 v[88:89], v[88:89], v[100:101]
	v_exp_f32_e32 v100, v98
	v_add_f32_e32 v93, 1.0, v93
	v_add_f32_e32 v92, 1.0, v92
	v_rcp_f32_e32 v98, v93
	v_add_f32_e32 v93, 1.0, v99
	v_rcp_f32_e32 v92, v92
	v_rcp_f32_e32 v93, v93
	v_add_f32_e32 v99, 1.0, v100
	v_rcp_f32_e32 v99, v99
	v_pk_mul_f32 v[88:89], v[88:89], v[80:81]
	v_pk_mul_f32 v[80:81], v[94:95], v[92:93]
	v_lshl_add_u64 v[92:93], v[96:97], 0, v[112:113]
	v_pk_mul_f32 v[86:87], v[80:81], v[86:87]
	v_pk_mul_f32 v[80:81], v[90:91], v[98:99]
	s_mov_b32 s58, s14
	v_pk_mul_f32 v[90:91], v[80:81], v[82:83]
	v_cvt_pk_bf16_f32 v80, v84, v85
	v_cvt_pk_bf16_f32 v81, v86, v87
	v_cvt_pk_bf16_f32 v82, v88, v89
	v_cvt_pk_bf16_f32 v83, v90, v91
	global_store_dwordx4 v[92:93], v[80:83], off
	v_mul_f32_e32 v84, 0xbfb8aa3b, v77
	v_exp_f32_e32 v84, v84
	v_mul_f32_e32 v82, 0xbfb8aa3b, v76
	v_mul_f32_e32 v83, 0xbfb8aa3b, v72
	v_exp_f32_e32 v82, v82
	v_exp_f32_e32 v83, v83
	v_or_b32_e32 v80, 48, v152
	v_mad_i64_i32 v[80:81], s[24:25], v80, s57, v[144:145]
	v_add_f32_e32 v82, 1.0, v82
	v_add_f32_e32 v85, 1.0, v83
	v_add_f32_e32 v83, 1.0, v84
	v_rcp_f32_e32 v82, v82
	v_rcp_f32_e32 v83, v83
	v_mul_f32_e32 v84, 0xbfb8aa3b, v73
	v_exp_f32_e32 v86, v84
; DI unsigned pk2(float a, float b) { f32x2 v = {a, b}; bf16x2_t r = __builtin_convertvector(v, bf16x2_t); return __builtin_bit_cast(unsigned, r); }
; DI float siluf_(float x) { return x * __builtin_amdgcn_rcpf(1.f + __expf(-x)); }
;     DI void operator()(const f32x4 (&acc)[2][2][4][2], const Unit& u, int wr, int wc, int fr, int fq) const {
;     ...
;         for (int ai = 0; ai < 2; ++ai)
; #pragma unroll
;             for (int m = 0; m < 4; ++m) { bf16_t* rowp = O + (size_t)(row0 + ai * HALF + m * 16) * DFF + col0;
;                 f32x4 v0, v1;
; #pragma unroll
;                 for (int j = 0; j < 4; ++j) { v0[j] = siluf_(acc[ai][0][m][0][j]) * acc[ai][1][m][0][j]; v1[j] = siluf_(acc[ai][0][m][1][j]) * acc[ai][1][m][1][j]; }
;                 u32x4 w; w.x = pk2(v0[0], v0[1]); w.y = pk2(v0[2], v0[3]); w.z = pk2(v1[0], v1[1]); w.w = pk2(v1[2], v1[3]);
;                 *(u32x4*)rowp = w; }
	v_rcp_f32_e32 v84, v85
	v_pk_mul_f32 v[76:77], v[76:77], v[82:83]
	v_mul_f32_e32 v82, 0xbfb8aa3b, v79
	v_pk_mul_f32 v[68:69], v[76:77], v[68:69]
	v_add_f32_e32 v76, 1.0, v86
	v_rcp_f32_e32 v85, v76
	v_mul_f32_e32 v77, 0xbfb8aa3b, v74
	v_mul_f32_e32 v76, 0xbfb8aa3b, v78
	v_exp_f32_e32 v77, v77
	v_exp_f32_e32 v76, v76
	v_exp_f32_e32 v83, v82
	v_mul_f32_e32 v82, 0xbfb8aa3b, v75
	v_pk_mul_f32 v[72:73], v[72:73], v[84:85]
	v_exp_f32_e32 v84, v82
	v_add_f32_e32 v77, 1.0, v77
	v_add_f32_e32 v76, 1.0, v76
	v_rcp_f32_e32 v82, v77
	v_add_f32_e32 v77, 1.0, v83
	v_rcp_f32_e32 v76, v76
	v_rcp_f32_e32 v77, v77
	v_add_f32_e32 v83, 1.0, v84
	v_rcp_f32_e32 v83, v83
	v_pk_mul_f32 v[72:73], v[72:73], v[64:65]
	v_pk_mul_f32 v[64:65], v[78:79], v[76:77]
	v_lshl_add_u64 v[76:77], v[80:81], 0, v[112:113]
	v_pk_mul_f32 v[70:71], v[64:65], v[70:71]
	v_pk_mul_f32 v[64:65], v[74:75], v[82:83]
	s_mov_b32 s22, s16
	v_pk_mul_f32 v[74:75], v[64:65], v[66:67]
	v_cvt_pk_bf16_f32 v64, v68, v69
	v_cvt_pk_bf16_f32 v65, v70, v71
	v_cvt_pk_bf16_f32 v66, v72, v73
	v_cvt_pk_bf16_f32 v67, v74, v75
	global_store_dwordx4 v[76:77], v[64:67], off
	v_mul_f32_e32 v68, 0xbfb8aa3b, v61
	v_exp_f32_e32 v68, v68
	v_mul_f32_e32 v66, 0xbfb8aa3b, v60
	v_mul_f32_e32 v67, 0xbfb8aa3b, v56
	v_exp_f32_e32 v66, v66
	v_exp_f32_e32 v67, v67
	v_add_u32_e32 v64, 0x80, v152
	v_mad_i64_i32 v[64:65], s[24:25], v64, s57, v[144:145]
	v_add_f32_e32 v66, 1.0, v66
	v_add_f32_e32 v69, 1.0, v67
	v_add_f32_e32 v67, 1.0, v68
	v_rcp_f32_e32 v66, v66
	v_rcp_f32_e32 v67, v67
	v_mul_f32_e32 v68, 0xbfb8aa3b, v57
	v_exp_f32_e32 v70, v68
	v_rcp_f32_e32 v68, v69
	v_pk_mul_f32 v[60:61], v[60:61], v[66:67]
	v_mul_f32_e32 v66, 0xbfb8aa3b, v63
	v_pk_mul_f32 v[52:53], v[60:61], v[52:53]
	v_add_f32_e32 v60, 1.0, v70
	v_rcp_f32_e32 v69, v60
	v_mul_f32_e32 v61, 0xbfb8aa3b, v58
	v_mul_f32_e32 v60, 0xbfb8aa3b, v62
	v_exp_f32_e32 v61, v61
	v_exp_f32_e32 v60, v60
	v_exp_f32_e32 v67, v66
	v_mul_f32_e32 v66, 0xbfb8aa3b, v59
	v_pk_mul_f32 v[56:57], v[56:57], v[68:69]
	v_exp_f32_e32 v68, v66
	v_add_f32_e32 v61, 1.0, v61
	v_add_f32_e32 v60, 1.0, v60
	v_rcp_f32_e32 v66, v61
	v_add_f32_e32 v61, 1.0, v67
	v_rcp_f32_e32 v60, v60
	v_rcp_f32_e32 v61, v61
	v_add_f32_e32 v67, 1.0, v68
	v_rcp_f32_e32 v67, v67
	v_pk_mul_f32 v[56:57], v[56:57], v[48:49]
	v_pk_mul_f32 v[48:49], v[62:63], v[60:61]
	v_lshl_add_u64 v[60:61], v[64:65], 0, v[112:113]
	v_pk_mul_f32 v[54:55], v[48:49], v[54:55]
	v_pk_mul_f32 v[48:49], v[58:59], v[66:67]
	s_mov_b64 s[36:37], s[20:21]
	v_pk_mul_f32 v[58:59], v[48:49], v[50:51]
	v_cvt_pk_bf16_f32 v48, v52, v53
	v_cvt_pk_bf16_f32 v49, v54, v55
	v_cvt_pk_bf16_f32 v50, v56, v57
	v_cvt_pk_bf16_f32 v51, v58, v59
	global_store_dwordx4 v[60:61], v[48:51], off
	v_mul_f32_e32 v52, 0xbfb8aa3b, v45
	v_exp_f32_e32 v52, v52
	v_mul_f32_e32 v50, 0xbfb8aa3b, v44
	v_mul_f32_e32 v51, 0xbfb8aa3b, v40
	v_exp_f32_e32 v50, v50
	v_exp_f32_e32 v51, v51
	v_add_u32_e32 v48, 0x90, v152
	v_mad_i64_i32 v[48:49], s[24:25], v48, s57, v[144:145]
	v_add_f32_e32 v50, 1.0, v50
	v_add_f32_e32 v53, 1.0, v51
	v_add_f32_e32 v51, 1.0, v52
	v_rcp_f32_e32 v50, v50
	v_rcp_f32_e32 v51, v51
	v_mul_f32_e32 v52, 0xbfb8aa3b, v41
	v_exp_f32_e32 v54, v52
	v_rcp_f32_e32 v52, v53
	v_pk_mul_f32 v[44:45], v[44:45], v[50:51]
	v_mul_f32_e32 v50, 0xbfb8aa3b, v47
	v_pk_mul_f32 v[36:37], v[44:45], v[36:37]
	v_add_f32_e32 v44, 1.0, v54
	v_rcp_f32_e32 v53, v44
	v_mul_f32_e32 v45, 0xbfb8aa3b, v42
	v_mul_f32_e32 v44, 0xbfb8aa3b, v46
	v_exp_f32_e32 v45, v45
	v_exp_f32_e32 v44, v44
	v_exp_f32_e32 v51, v50
	v_mul_f32_e32 v50, 0xbfb8aa3b, v43
	v_pk_mul_f32 v[40:41], v[40:41], v[52:53]
	v_exp_f32_e32 v52, v50
	v_add_f32_e32 v45, 1.0, v45
	v_add_f32_e32 v44, 1.0, v44
	v_rcp_f32_e32 v50, v45
	v_add_f32_e32 v45, 1.0, v51
	v_rcp_f32_e32 v44, v44
; DI unsigned pk2(float a, float b) { f32x2 v = {a, b}; bf16x2_t r = __builtin_convertvector(v, bf16x2_t); return __builtin_bit_cast(unsigned, r); }
; DI float siluf_(float x) { return x * __builtin_amdgcn_rcpf(1.f + __expf(-x)); }
; template <class Epi>
; DI void gemm_phase(LAS unsigned char* lds, const Gemm g, const StaticOrder& S, const Epi& E) {
;     ...
;         if (!has_next) break;
;     DI void operator()(const f32x4 (&acc)[2][2][4][2], const Unit& u, int wr, int wc, int fr, int fq) const {
;     ...
;         for (int ai = 0; ai < 2; ++ai)
; #pragma unroll
;             for (int m = 0; m < 4; ++m) { bf16_t* rowp = O + (size_t)(row0 + ai * HALF + m * 16) * DFF + col0;
;                 f32x4 v0, v1;
; #pragma unroll
;                 for (int j = 0; j < 4; ++j) { v0[j] = siluf_(acc[ai][0][m][0][j]) * acc[ai][1][m][0][j]; v1[j] = siluf_(acc[ai][0][m][1][j]) * acc[ai][1][m][1][j]; }
;                 u32x4 w; w.x = pk2(v0[0], v0[1]); w.y = pk2(v0[2], v0[3]); w.z = pk2(v1[0], v1[1]); w.w = pk2(v1[2], v1[3]);
;                 *(u32x4*)rowp = w; }
	v_rcp_f32_e32 v45, v45
	v_add_f32_e32 v51, 1.0, v52
	v_rcp_f32_e32 v51, v51
	v_pk_mul_f32 v[40:41], v[40:41], v[32:33]
	v_pk_mul_f32 v[32:33], v[46:47], v[44:45]
	v_lshl_add_u64 v[44:45], v[48:49], 0, v[112:113]
	v_pk_mul_f32 v[38:39], v[32:33], v[38:39]
	v_pk_mul_f32 v[32:33], v[42:43], v[50:51]
	s_nop 0
	v_pk_mul_f32 v[42:43], v[32:33], v[34:35]
	v_cvt_pk_bf16_f32 v32, v36, v37
	v_cvt_pk_bf16_f32 v33, v38, v39
	v_cvt_pk_bf16_f32 v34, v40, v41
	v_cvt_pk_bf16_f32 v35, v42, v43
	global_store_dwordx4 v[44:45], v[32:35], off
	v_mul_f32_e32 v36, 0xbfb8aa3b, v29
	v_exp_f32_e32 v36, v36
	v_mul_f32_e32 v34, 0xbfb8aa3b, v28
	v_mul_f32_e32 v35, 0xbfb8aa3b, v24
	v_exp_f32_e32 v34, v34
	v_exp_f32_e32 v35, v35
	v_add_u32_e32 v32, 0xa0, v152
	v_mad_i64_i32 v[32:33], s[24:25], v32, s57, v[144:145]
	v_add_f32_e32 v34, 1.0, v34
	v_add_f32_e32 v37, 1.0, v35
	v_add_f32_e32 v35, 1.0, v36
	v_rcp_f32_e32 v34, v34
	v_rcp_f32_e32 v35, v35
	v_mul_f32_e32 v36, 0xbfb8aa3b, v25
	v_exp_f32_e32 v38, v36
	v_rcp_f32_e32 v36, v37
	v_pk_mul_f32 v[28:29], v[28:29], v[34:35]
	v_mul_f32_e32 v34, 0xbfb8aa3b, v31
	v_pk_mul_f32 v[20:21], v[28:29], v[20:21]
	v_add_f32_e32 v28, 1.0, v38
	v_rcp_f32_e32 v37, v28
	v_mul_f32_e32 v29, 0xbfb8aa3b, v26
	v_mul_f32_e32 v28, 0xbfb8aa3b, v30
	v_exp_f32_e32 v29, v29
	v_exp_f32_e32 v28, v28
	v_exp_f32_e32 v35, v34
	v_mul_f32_e32 v34, 0xbfb8aa3b, v27
	v_pk_mul_f32 v[24:25], v[24:25], v[36:37]
	v_exp_f32_e32 v36, v34
	v_add_f32_e32 v29, 1.0, v29
	v_add_f32_e32 v28, 1.0, v28
	v_rcp_f32_e32 v34, v29
	v_add_f32_e32 v29, 1.0, v35
	v_rcp_f32_e32 v28, v28
	v_rcp_f32_e32 v29, v29
	v_add_f32_e32 v35, 1.0, v36
	v_rcp_f32_e32 v35, v35
	v_pk_mul_f32 v[24:25], v[24:25], v[16:17]
	v_pk_mul_f32 v[16:17], v[30:31], v[28:29]
	v_lshl_add_u64 v[28:29], v[32:33], 0, v[112:113]
	v_pk_mul_f32 v[22:23], v[16:17], v[22:23]
	v_pk_mul_f32 v[16:17], v[26:27], v[34:35]
	s_nop 0
	v_pk_mul_f32 v[26:27], v[16:17], v[18:19]
	v_cvt_pk_bf16_f32 v16, v20, v21
	v_cvt_pk_bf16_f32 v17, v22, v23
	v_cvt_pk_bf16_f32 v18, v24, v25
	v_cvt_pk_bf16_f32 v19, v26, v27
	global_store_dwordx4 v[28:29], v[16:19], off
	v_mul_f32_e32 v20, 0xbfb8aa3b, v13
	v_exp_f32_e32 v20, v20
	v_mul_f32_e32 v18, 0xbfb8aa3b, v12
	v_mul_f32_e32 v19, 0xbfb8aa3b, v8
	v_exp_f32_e32 v18, v18
	v_exp_f32_e32 v19, v19
	v_add_u32_e32 v16, 0xb0, v152
	v_mad_i64_i32 v[16:17], s[24:25], v16, s57, v[144:145]
	v_add_f32_e32 v18, 1.0, v18
	v_add_f32_e32 v21, 1.0, v19
	v_add_f32_e32 v19, 1.0, v20
	v_rcp_f32_e32 v18, v18
	v_rcp_f32_e32 v19, v19
	v_mul_f32_e32 v20, 0xbfb8aa3b, v9
	v_exp_f32_e32 v22, v20
	v_rcp_f32_e32 v20, v21
	v_pk_mul_f32 v[12:13], v[12:13], v[18:19]
	v_mul_f32_e32 v18, 0xbfb8aa3b, v15
	v_pk_mul_f32 v[4:5], v[12:13], v[4:5]
	v_add_f32_e32 v12, 1.0, v22
	v_rcp_f32_e32 v21, v12
	v_mul_f32_e32 v13, 0xbfb8aa3b, v10
	v_mul_f32_e32 v12, 0xbfb8aa3b, v14
	v_exp_f32_e32 v13, v13
	v_exp_f32_e32 v12, v12
	v_exp_f32_e32 v19, v18
	v_mul_f32_e32 v18, 0xbfb8aa3b, v11
	v_pk_mul_f32 v[8:9], v[8:9], v[20:21]
	v_exp_f32_e32 v20, v18
	v_add_f32_e32 v13, 1.0, v13
	v_add_f32_e32 v12, 1.0, v12
	v_rcp_f32_e32 v18, v13
	v_add_f32_e32 v13, 1.0, v19
	v_rcp_f32_e32 v12, v12
	v_rcp_f32_e32 v13, v13
	v_add_f32_e32 v19, 1.0, v20
	v_rcp_f32_e32 v19, v19
	v_pk_mul_f32 v[8:9], v[8:9], v[0:1]
	v_pk_mul_f32 v[0:1], v[14:15], v[12:13]
	v_lshl_add_u64 v[12:13], v[16:17], 0, v[112:113]
	v_pk_mul_f32 v[6:7], v[0:1], v[6:7]
	v_pk_mul_f32 v[0:1], v[10:11], v[18:19]
	s_mov_b64 s[24:25], s[18:19]
	v_pk_mul_f32 v[10:11], v[0:1], v[2:3]
	v_cvt_pk_bf16_f32 v0, v4, v5
	v_cvt_pk_bf16_f32 v1, v6, v7
	v_cvt_pk_bf16_f32 v2, v8, v9
	v_cvt_pk_bf16_f32 v3, v10, v11
	global_store_dwordx4 v[12:13], v[0:3], off
	s_cbranch_vccz .LBB0_846
	s_waitcnt vmcnt(0)
	s_cmpk_gt_u32 s40, 0xff
	s_cbranch_scc1 .LBB0_853
	s_barrier

; #define PG8_STAGE(bufoff, gbase, voff) do { _Pragma("unroll") for (int _i = 0; _i < 2; ++_i) \
;         __builtin_amdgcn_global_load_lds((const unsigned*)((const char*)(gbase) + (voff)[_i]), (LAS unsigned*)(lds + (bufoff) + ldsw + _i * 8192), 16, 0, 0); } while (0)
; #define PG8_LDA(dst, b, h) do { _Pragma("unroll") for (int m = 0; m < 4; ++m) _Pragma("unroll") for (int k = 0; k < 2; ++k) dst[m][k] = *(const LAS bf16x8*)(lds + PG8_SA(b, h) + aoff + m * 2048 + k * 1024); } while (0)
; #define PG8_LDB(dst, b, h) do { _Pragma("unroll") for (int n = 0; n < 2; ++n) _Pragma("unroll") for (int k = 0; k < 2; ++k) dst[n][k] = *(const LAS bf16x8*)(lds + PG8_SB(b, h) + boff + n * 2048 + k * 1024); } while (0)
; template <class Epi>
; DI void gemm_phase(LAS unsigned char* lds, const Gemm g, const StaticOrder& S, const Epi& E) {
;     ...
;         const bool has_next = S.next(ui + 1, nxt);
;         const char* nA = has_next ? (const char*)g.A + (size_t)nxt.pm * tstep : cA; const char* nB = has_next ? (const char*)g.Bt + (size_t)nxt.pn * tstep : cB;
;         for (int t = 0; t < nt; t += 2) {
;             const bool last = (t == nt - 2);
;             const char* a1 = cA + (size_t)(t + 1) * kstep;
;             const char* a2 = last ? nA : cA + (size_t)(t + 2) * kstep; const char* b2 = last ? nB : cB + (size_t)(t + 2) * kstep;
;             const char* a3 = a2 + kstep; const char* b3 = b2 + kstep;
;             PG8_LDB(B0, 0, 0); PG8_SCHED; PG8_LDA(At, 0, 0); PG8_STAGE(PG8_SA(1, 1), a1 + hstep, voffA);
;             PG8_WAIT_L(8); PG8_BAR; PG8_WAIT_L(0); PG8_MMA(0, 0, At, B0); PG8_BAR; PG8_SCHED;
;             PG8_LDB(B1, 0, 1); PG8_STAGE(PG8_SB(0, 0), b2, voffB);
;             PG8_BAR; PG8_WAIT_L(0); PG8_MMA(0, 1, At, B1); PG8_BAR;
;             PG8_LDA(At, 0, 1); PG8_STAGE(PG8_SA(0, 0), a2, voffA);
;             PG8_BAR; PG8_WAIT_L(0); PG8_MMA(1, 0, At, B0); PG8_BAR; PG8_SCHED;
;             PG8_STAGE(PG8_SB(0, 1), b2 + hstep, voffB);
;             PG8_WAIT_V(6); PG8_BAR; PG8_MMA(1, 1, At, B1); PG8_BAR;
;             PG8_LDB(B0, 1, 0); PG8_SCHED; PG8_LDA(At, 1, 0); PG8_STAGE(PG8_SA(0, 1), a2 + hstep, voffA);
;             PG8_WAIT_L(8); PG8_BAR; PG8_WAIT_L(0); PG8_MMA(0, 0, At, B0); PG8_BAR; PG8_SCHED;
;             PG8_LDB(B1, 1, 1); PG8_STAGE(PG8_SB(1, 0), b3, voffB);
;             PG8_BAR; PG8_WAIT_L(0); PG8_MMA(0, 1, At, B1); PG8_BAR;
.LBB0_927:
	s_add_u32 s36, s36, 0xb0080
	s_addc_u32 s37, s37, 0
	s_add_u32 s71, s38, 0x100
	s_addc_u32 s72, s39, 0
	s_mov_b32 s73, -2
	v_add_u32_e32 v253, 0x18000, v171
	v_add_u32_e32 v252, 0x1c000, v171
	ds_read_b128 v[128:131], v173
	ds_read_b128 v[132:135], v173 offset:1024
	ds_read_b128 v[136:139], v173 offset:2048
	ds_read_b128 v[140:143], v173 offset:3072
	s_add_u32 s38, s36, 0xfff50080
	s_addc_u32 s39, s37, -1
	s_cmp_eq_u32 s73, 40
	s_cselect_b32 s41, s7, s39
	s_cselect_b32 s40, s6, s38
	s_cselect_b32 s39, s9, s72
	s_cselect_b32 s38, s8, s71
	s_add_i32 m0, s49, 0xc000
	ds_read_b128 v[144:147], v174
	ds_read_b128 v[164:167], v174 offset:1024
	ds_read_b128 v[176:179], v174 offset:2048
	ds_read_b128 v[182:185], v174 offset:3072
	ds_read_b128 v[186:189], v174 offset:4096
	ds_read_b128 v[190:193], v174 offset:5120
	ds_read_b128 v[194:197], v174 offset:6144
	ds_read_b128 v[198:201], v174 offset:7168
	global_load_lds_dwordx4 v156, s[36:37]
	s_add_i32 m0, s49, 0xe000
	s_nop 0
	global_load_lds_dwordx4 v158, s[36:37]
	s_waitcnt lgkmcnt(8)
	s_barrier
	s_waitcnt lgkmcnt(7)
	v_mfma_f32_16x16x32_bf16 v[124:127], v[128:131], v[144:147], 0
	v_mfma_f32_16x16x32_bf16 v[120:123], v[136:139], v[144:147], 0
	s_waitcnt lgkmcnt(5)
	v_mfma_f32_16x16x32_bf16 v[116:119], v[128:131], v[176:179], 0
	v_mfma_f32_16x16x32_bf16 v[108:111], v[136:139], v[176:179], 0
	s_waitcnt lgkmcnt(3)
	v_mfma_f32_16x16x32_bf16 v[92:95], v[128:131], v[186:189], 0
	v_mfma_f32_16x16x32_bf16 v[88:91], v[136:139], v[186:189], 0
	s_waitcnt lgkmcnt(1)
	v_mfma_f32_16x16x32_bf16 v[76:79], v[128:131], v[194:197], 0
	v_mfma_f32_16x16x32_bf16 v[72:75], v[136:139], v[194:197], 0
	v_mfma_f32_16x16x32_bf16 v[124:127], v[132:135], v[164:167], v[124:127]
	v_mfma_f32_16x16x32_bf16 v[120:123], v[140:143], v[164:167], v[120:123]
	v_mfma_f32_16x16x32_bf16 v[116:119], v[132:135], v[182:185], v[116:119]
	v_mfma_f32_16x16x32_bf16 v[108:111], v[140:143], v[182:185], v[108:111]
	v_mfma_f32_16x16x32_bf16 v[92:95], v[132:135], v[190:193], v[92:95]
	v_mfma_f32_16x16x32_bf16 v[88:91], v[140:143], v[190:193], v[88:91]
	s_add_i32 s74, s59, s48
	s_add_u32 s86, s38, s16
	s_waitcnt lgkmcnt(0)
	v_mfma_f32_16x16x32_bf16 v[76:79], v[132:135], v[198:201], v[76:79]
	s_addc_u32 s87, s39, s17
	s_mov_b32 m0, s74
	v_mfma_f32_16x16x32_bf16 v[72:75], v[140:143], v[198:201], v[72:75]
	s_barrier
	ds_read_b128 v[202:205], v175
	ds_read_b128 v[206:209], v175 offset:1024
	ds_read_b128 v[210:213], v175 offset:2048
	ds_read_b128 v[214:217], v175 offset:3072
	global_load_lds_dwordx4 v150, s[38:39]
	s_add_i32 m0, s74, 0x2000
	s_nop 0
	global_load_lds_dwordx4 v154, s[38:39]
	s_barrier
	s_waitcnt lgkmcnt(3)
	v_mfma_f32_16x16x32_bf16 v[112:115], v[202:205], v[144:147], 0
	s_waitcnt lgkmcnt(1)
	v_mfma_f32_16x16x32_bf16 v[104:107], v[210:213], v[144:147], 0
	v_mfma_f32_16x16x32_bf16 v[100:103], v[202:205], v[176:179], 0
	v_mfma_f32_16x16x32_bf16 v[96:99], v[210:213], v[176:179], 0
	v_mfma_f32_16x16x32_bf16 v[84:87], v[202:205], v[186:189], 0
	v_mfma_f32_16x16x32_bf16 v[80:83], v[210:213], v[186:189], 0
	v_mfma_f32_16x16x32_bf16 v[68:71], v[202:205], v[194:197], 0
	v_mfma_f32_16x16x32_bf16 v[64:67], v[210:213], v[194:197], 0
	v_mfma_f32_16x16x32_bf16 v[112:115], v[206:209], v[164:167], v[112:115]
	s_waitcnt lgkmcnt(0)
	v_mfma_f32_16x16x32_bf16 v[104:107], v[214:217], v[164:167], v[104:107]
	v_mfma_f32_16x16x32_bf16 v[100:103], v[206:209], v[182:185], v[100:103]
	v_mfma_f32_16x16x32_bf16 v[96:99], v[214:217], v[182:185], v[96:99]
	v_mfma_f32_16x16x32_bf16 v[84:87], v[206:209], v[190:193], v[84:87]
	v_mfma_f32_16x16x32_bf16 v[80:83], v[214:217], v[190:193], v[80:83]
	s_mov_b32 m0, s49
	s_add_u32 s88, s40, s16
	v_mfma_f32_16x16x32_bf16 v[68:71], v[206:209], v[198:201], v[68:71]
	s_addc_u32 s89, s41, s17
	v_mfma_f32_16x16x32_bf16 v[64:67], v[214:217], v[198:201], v[64:67]
	s_barrier
	ds_read_b128 v[144:147], v174 offset:16384
	ds_read_b128 v[164:167], v174 offset:17408
	ds_read_b128 v[176:179], v174 offset:18432
	ds_read_b128 v[182:185], v174 offset:19456
	ds_read_b128 v[186:189], v174 offset:20480
	ds_read_b128 v[190:193], v174 offset:21504
	ds_read_b128 v[194:197], v174 offset:22528
	ds_read_b128 v[198:201], v174 offset:23552
	global_load_lds_dwordx4 v148, s[40:41]
	s_mov_b32 m0, s50
	s_nop 0
	global_load_lds_dwordx4 v152, s[40:41]
	s_barrier
	s_waitcnt lgkmcnt(7)
	v_mfma_f32_16x16x32_bf16 v[60:63], v[128:131], v[144:147], 0
	v_mfma_f32_16x16x32_bf16 v[56:59], v[136:139], v[144:147], 0
	s_waitcnt lgkmcnt(5)
	v_mfma_f32_16x16x32_bf16 v[44:47], v[128:131], v[176:179], 0
	v_mfma_f32_16x16x32_bf16 v[40:43], v[136:139], v[176:179], 0
	s_waitcnt lgkmcnt(3)
	v_mfma_f32_16x16x32_bf16 v[36:39], v[128:131], v[186:189], 0
	v_mfma_f32_16x16x32_bf16 v[32:35], v[136:139], v[186:189], 0
	s_waitcnt lgkmcnt(1)
	v_mfma_f32_16x16x32_bf16 v[20:23], v[128:131], v[194:197], 0
	v_mfma_f32_16x16x32_bf16 v[16:19], v[136:139], v[194:197], 0
	v_mfma_f32_16x16x32_bf16 v[60:63], v[132:135], v[164:167], v[60:63]
	v_mfma_f32_16x16x32_bf16 v[56:59], v[140:143], v[164:167], v[56:59]
	v_mfma_f32_16x16x32_bf16 v[44:47], v[132:135], v[182:185], v[44:47]
	v_mfma_f32_16x16x32_bf16 v[40:43], v[140:143], v[182:185], v[40:43]
	v_mfma_f32_16x16x32_bf16 v[36:39], v[132:135], v[190:193], v[36:39]
	v_mfma_f32_16x16x32_bf16 v[32:35], v[140:143], v[190:193], v[32:35]
	s_add_u32 s74, s38, 0xb0000
	s_addc_u32 s75, s39, 0
	s_waitcnt lgkmcnt(0)
	v_mfma_f32_16x16x32_bf16 v[20:23], v[132:135], v[198:201], v[20:23]
	s_add_i32 s76, s60, s48
	s_mov_b32 m0, s76
	v_mfma_f32_16x16x32_bf16 v[16:19], v[140:143], v[198:201], v[16:19]
	s_barrier
; #define PG8_STAGE(bufoff, gbase, voff) do { _Pragma("unroll") for (int _i = 0; _i < 2; ++_i) \
;         __builtin_amdgcn_global_load_lds((const unsigned*)((const char*)(gbase) + (voff)[_i]), (LAS unsigned*)(lds + (bufoff) + ldsw + _i * 8192), 16, 0, 0); } while (0)
; #define PG8_LDA(dst, b, h) do { _Pragma("unroll") for (int m = 0; m < 4; ++m) _Pragma("unroll") for (int k = 0; k < 2; ++k) dst[m][k] = *(const LAS bf16x8*)(lds + PG8_SA(b, h) + aoff + m * 2048 + k * 1024); } while (0)
; #define PG8_LDB(dst, b, h) do { _Pragma("unroll") for (int n = 0; n < 2; ++n) _Pragma("unroll") for (int k = 0; k < 2; ++k) dst[n][k] = *(const LAS bf16x8*)(lds + PG8_SB(b, h) + boff + n * 2048 + k * 1024); } while (0)
; #define PG8_MMA(ai, bj, At, Bt) do { __builtin_amdgcn_s_setprio(1); _Pragma("unroll") for (int m = 0; m < 4; ++m) _Pragma("unroll") for (int n = 0; n < 2; ++n) _Pragma("unroll") for (int k = 0; k < 2; ++k) \
;         acc[ai][bj][m][n] = __builtin_amdgcn_mfma_f32_16x16x32_bf16(Bt[n][k], At[m][k], acc[ai][bj][m][n], 0, 0, 0); __builtin_amdgcn_s_setprio(0); } while (0)
; #define PG8_WAIT_V(n) asm volatile("s_waitcnt vmcnt(" #n ")" ::: "memory")
; #define PG8_WAIT_L(n) asm volatile("s_waitcnt lgkmcnt(" #n ")" ::: "memory")
; #define PG8_BAR __builtin_amdgcn_s_barrier()
; #define PG8_SCHED __builtin_amdgcn_sched_barrier(0)
; template <class Epi>
; DI void gemm_phase(LAS unsigned char* lds, const Gemm g, const StaticOrder& S, const Epi& E) {
;     ...
;             PG8_LDA(At, 0, 1); PG8_STAGE(PG8_SA(0, 0), a2, voffA);
;             PG8_BAR; PG8_WAIT_L(0); PG8_MMA(1, 0, At, B0); PG8_BAR; PG8_SCHED;
;             PG8_STAGE(PG8_SB(0, 1), b2 + hstep, voffB);
;             PG8_WAIT_V(6); PG8_BAR; PG8_MMA(1, 1, At, B1); PG8_BAR;
;             PG8_LDB(B0, 1, 0); PG8_SCHED; PG8_LDA(At, 1, 0); PG8_STAGE(PG8_SA(0, 1), a2 + hstep, voffA);
;             PG8_WAIT_L(8); PG8_BAR; PG8_WAIT_L(0); PG8_MMA(0, 0, At, B0); PG8_BAR; PG8_SCHED;
;             PG8_LDB(B1, 1, 1); PG8_STAGE(PG8_SB(1, 0), b3, voffB);
;             PG8_BAR; PG8_WAIT_L(0); PG8_MMA(0, 1, At, B1); PG8_BAR;
	global_load_lds_dwordx4 v150, s[74:75]
	s_add_i32 m0, s76, 0x2000
	s_nop 0
	global_load_lds_dwordx4 v154, s[74:75]
	s_waitcnt vmcnt(6)
	s_barrier
	v_mfma_f32_16x16x32_bf16 v[52:55], v[202:205], v[144:147], 0
	v_mfma_f32_16x16x32_bf16 v[48:51], v[210:213], v[144:147], 0
	v_mfma_f32_16x16x32_bf16 v[28:31], v[202:205], v[176:179], 0
	v_mfma_f32_16x16x32_bf16 v[24:27], v[210:213], v[176:179], 0
	v_mfma_f32_16x16x32_bf16 v[12:15], v[202:205], v[186:189], 0
	v_mfma_f32_16x16x32_bf16 v[8:11], v[210:213], v[186:189], 0
	v_mfma_f32_16x16x32_bf16 v[4:7], v[202:205], v[194:197], 0
	v_mfma_f32_16x16x32_bf16 v[0:3], v[210:213], v[194:197], 0
	v_mfma_f32_16x16x32_bf16 v[52:55], v[206:209], v[164:167], v[52:55]
	v_mfma_f32_16x16x32_bf16 v[48:51], v[214:217], v[164:167], v[48:51]
	v_mfma_f32_16x16x32_bf16 v[28:31], v[206:209], v[182:185], v[28:31]
	v_mfma_f32_16x16x32_bf16 v[24:27], v[214:217], v[182:185], v[24:27]
	v_mfma_f32_16x16x32_bf16 v[12:15], v[206:209], v[190:193], v[12:15]
	v_mfma_f32_16x16x32_bf16 v[8:11], v[214:217], v[190:193], v[8:11]
	v_mfma_f32_16x16x32_bf16 v[4:7], v[206:209], v[198:201], v[4:7]
	s_add_i32 s74, 0, 0x18000
	v_mfma_f32_16x16x32_bf16 v[0:3], v[214:217], v[198:201], v[0:3]
	s_barrier
	ds_read_b128 v[128:131], v253
	ds_read_b128 v[132:135], v253 offset:1024
	ds_read_b128 v[136:139], v253 offset:2048
	ds_read_b128 v[140:143], v253 offset:3072
	s_add_u32 s40, s40, 0xb0000
	s_addc_u32 s41, s41, 0
	s_mov_b32 m0, s51
	ds_read_b128 v[144:147], v174 offset:32768
	ds_read_b128 v[164:167], v174 offset:33792
	ds_read_b128 v[176:179], v174 offset:34816
	ds_read_b128 v[182:185], v174 offset:35840
	ds_read_b128 v[186:189], v174 offset:36864
	ds_read_b128 v[190:193], v174 offset:37888
	ds_read_b128 v[194:197], v174 offset:38912
	ds_read_b128 v[198:201], v174 offset:39936
	global_load_lds_dwordx4 v148, s[40:41]
	s_mov_b32 m0, s52
	s_nop 0
	global_load_lds_dwordx4 v152, s[40:41]
	s_waitcnt lgkmcnt(8)
	s_barrier
	s_waitcnt lgkmcnt(7)
	v_mfma_f32_16x16x32_bf16 v[124:127], v[128:131], v[144:147], v[124:127]
	v_mfma_f32_16x16x32_bf16 v[120:123], v[136:139], v[144:147], v[120:123]
	s_waitcnt lgkmcnt(5)
	v_mfma_f32_16x16x32_bf16 v[116:119], v[128:131], v[176:179], v[116:119]
	v_mfma_f32_16x16x32_bf16 v[108:111], v[136:139], v[176:179], v[108:111]
	s_waitcnt lgkmcnt(3)
	v_mfma_f32_16x16x32_bf16 v[92:95], v[128:131], v[186:189], v[92:95]
	v_mfma_f32_16x16x32_bf16 v[88:91], v[136:139], v[186:189], v[88:91]
	s_waitcnt lgkmcnt(1)
	v_mfma_f32_16x16x32_bf16 v[76:79], v[128:131], v[194:197], v[76:79]
	v_mfma_f32_16x16x32_bf16 v[72:75], v[136:139], v[194:197], v[72:75]
	v_mfma_f32_16x16x32_bf16 v[124:127], v[132:135], v[164:167], v[124:127]
	v_mfma_f32_16x16x32_bf16 v[120:123], v[140:143], v[164:167], v[120:123]
	v_mfma_f32_16x16x32_bf16 v[116:119], v[132:135], v[182:185], v[116:119]
	v_mfma_f32_16x16x32_bf16 v[108:111], v[140:143], v[182:185], v[108:111]
	v_mfma_f32_16x16x32_bf16 v[92:95], v[132:135], v[190:193], v[92:95]
	v_mfma_f32_16x16x32_bf16 v[88:91], v[140:143], v[190:193], v[88:91]
	s_add_i32 s40, 0, 0x1c000
	s_add_i32 s41, s74, s48
	s_waitcnt lgkmcnt(0)
	v_mfma_f32_16x16x32_bf16 v[76:79], v[132:135], v[198:201], v[76:79]
	s_mov_b32 m0, s41
	v_mfma_f32_16x16x32_bf16 v[72:75], v[140:143], v[198:201], v[72:75]
	s_barrier
	ds_read_b128 v[202:205], v252
	ds_read_b128 v[206:209], v252 offset:1024
	ds_read_b128 v[210:213], v252 offset:2048
	ds_read_b128 v[214:217], v252 offset:3072
	global_load_lds_dwordx4 v150, s[86:87]
	s_add_i32 m0, s41, 0x2000
	s_nop 0
	global_load_lds_dwordx4 v154, s[86:87]
	s_barrier
	s_waitcnt lgkmcnt(3)
	v_mfma_f32_16x16x32_bf16 v[112:115], v[202:205], v[144:147], v[112:115]
	s_waitcnt lgkmcnt(1)
	v_mfma_f32_16x16x32_bf16 v[104:107], v[210:213], v[144:147], v[104:107]
	v_mfma_f32_16x16x32_bf16 v[100:103], v[202:205], v[176:179], v[100:103]
	v_mfma_f32_16x16x32_bf16 v[96:99], v[210:213], v[176:179], v[96:99]
	v_mfma_f32_16x16x32_bf16 v[84:87], v[202:205], v[186:189], v[84:87]
	v_mfma_f32_16x16x32_bf16 v[80:83], v[210:213], v[186:189], v[80:83]
	v_mfma_f32_16x16x32_bf16 v[68:71], v[202:205], v[194:197], v[68:71]
	v_mfma_f32_16x16x32_bf16 v[64:67], v[210:213], v[194:197], v[64:67]
	v_mfma_f32_16x16x32_bf16 v[112:115], v[206:209], v[164:167], v[112:115]
	s_waitcnt lgkmcnt(0)
	v_mfma_f32_16x16x32_bf16 v[104:107], v[214:217], v[164:167], v[104:107]
	v_mfma_f32_16x16x32_bf16 v[100:103], v[206:209], v[182:185], v[100:103]
	v_mfma_f32_16x16x32_bf16 v[96:99], v[214:217], v[182:185], v[96:99]
	v_mfma_f32_16x16x32_bf16 v[84:87], v[206:209], v[190:193], v[84:87]
	v_mfma_f32_16x16x32_bf16 v[80:83], v[214:217], v[190:193], v[80:83]
	v_mfma_f32_16x16x32_bf16 v[68:71], v[206:209], v[198:201], v[68:71]
	s_mov_b32 m0, s56
	v_mfma_f32_16x16x32_bf16 v[64:67], v[214:217], v[198:201], v[64:67]
	s_barrier
	ds_read_b128 v[144:147], v174 offset:49152
	ds_read_b128 v[164:167], v174 offset:50176
	ds_read_b128 v[176:179], v174 offset:51200
	ds_read_b128 v[182:185], v174 offset:52224
	ds_read_b128 v[186:189], v174 offset:53248
	ds_read_b128 v[190:193], v174 offset:54272
	ds_read_b128 v[194:197], v174 offset:55296
	ds_read_b128 v[198:201], v174 offset:56320
	global_load_lds_dwordx4 v148, s[88:89]
	s_mov_b32 m0, s57
	s_nop 0
	global_load_lds_dwordx4 v152, s[88:89]
	s_barrier
; #define PG8_STAGE(bufoff, gbase, voff) do { _Pragma("unroll") for (int _i = 0; _i < 2; ++_i) \
;         __builtin_amdgcn_global_load_lds((const unsigned*)((const char*)(gbase) + (voff)[_i]), (LAS unsigned*)(lds + (bufoff) + ldsw + _i * 8192), 16, 0, 0); } while (0)
; #define PG8_LDA(dst, b, h) do { _Pragma("unroll") for (int m = 0; m < 4; ++m) _Pragma("unroll") for (int k = 0; k < 2; ++k) dst[m][k] = *(const LAS bf16x8*)(lds + PG8_SA(b, h) + aoff + m * 2048 + k * 1024); } while (0)
; #define PG8_LDB(dst, b, h) do { _Pragma("unroll") for (int n = 0; n < 2; ++n) _Pragma("unroll") for (int k = 0; k < 2; ++k) dst[n][k] = *(const LAS bf16x8*)(lds + PG8_SB(b, h) + boff + n * 2048 + k * 1024); } while (0)
; #define PG8_MMA(ai, bj, At, Bt) do { __builtin_amdgcn_s_setprio(1); _Pragma("unroll") for (int m = 0; m < 4; ++m) _Pragma("unroll") for (int n = 0; n < 2; ++n) _Pragma("unroll") for (int k = 0; k < 2; ++k) \
;         acc[ai][bj][m][n] = __builtin_amdgcn_mfma_f32_16x16x32_bf16(Bt[n][k], At[m][k], acc[ai][bj][m][n], 0, 0, 0); __builtin_amdgcn_s_setprio(0); } while (0)
; #define PG8_WAIT_V(n) asm volatile("s_waitcnt vmcnt(" #n ")" ::: "memory")
; #define PG8_WAIT_L(n) asm volatile("s_waitcnt lgkmcnt(" #n ")" ::: "memory")
; #define PG8_BAR __builtin_amdgcn_s_barrier()
; #define PG8_SCHED __builtin_amdgcn_sched_barrier(0)
; template <class Epi>
; DI void gemm_phase(LAS unsigned char* lds, const Gemm g, const StaticOrder& S, const Epi& E) {
;     ...
;             PG8_LDB(B0, 0, 0); PG8_SCHED; PG8_LDA(At, 0, 0); PG8_STAGE(PG8_SA(1, 1), a1 + hstep, voffA);
;             PG8_WAIT_L(8); PG8_BAR; PG8_WAIT_L(0); PG8_MMA(0, 0, At, B0); PG8_BAR; PG8_SCHED;
;     ...
;             PG8_WAIT_V(6); PG8_BAR; PG8_MMA(1, 1, At, B1); PG8_BAR;
;             PG8_LDB(B0, 1, 0); PG8_SCHED; PG8_LDA(At, 1, 0); PG8_STAGE(PG8_SA(0, 1), a2 + hstep, voffA);
;             PG8_WAIT_L(8); PG8_BAR; PG8_WAIT_L(0); PG8_MMA(0, 0, At, B0); PG8_BAR; PG8_SCHED;
;             PG8_LDB(B1, 1, 1); PG8_STAGE(PG8_SB(1, 0), b3, voffB);
;             PG8_BAR; PG8_WAIT_L(0); PG8_MMA(0, 1, At, B1); PG8_BAR;
;             PG8_LDA(At, 1, 1); PG8_STAGE(PG8_SA(1, 0), a3, voffA);
;             PG8_BAR; PG8_WAIT_L(0); PG8_MMA(1, 0, At, B0); PG8_BAR; PG8_SCHED;
;             PG8_STAGE(PG8_SB(1, 1), b3 + hstep, voffB);
;             PG8_WAIT_V(6); PG8_BAR; PG8_MMA(1, 1, At, B1); PG8_BAR;
	s_waitcnt lgkmcnt(7)
	v_mfma_f32_16x16x32_bf16 v[60:63], v[128:131], v[144:147], v[60:63]
	v_mfma_f32_16x16x32_bf16 v[56:59], v[136:139], v[144:147], v[56:59]
	s_waitcnt lgkmcnt(5)
	v_mfma_f32_16x16x32_bf16 v[44:47], v[128:131], v[176:179], v[44:47]
	v_mfma_f32_16x16x32_bf16 v[40:43], v[136:139], v[176:179], v[40:43]
	s_waitcnt lgkmcnt(3)
	v_mfma_f32_16x16x32_bf16 v[36:39], v[128:131], v[186:189], v[36:39]
	v_mfma_f32_16x16x32_bf16 v[32:35], v[136:139], v[186:189], v[32:35]
	s_waitcnt lgkmcnt(1)
	v_mfma_f32_16x16x32_bf16 v[20:23], v[128:131], v[194:197], v[20:23]
	v_mfma_f32_16x16x32_bf16 v[16:19], v[136:139], v[194:197], v[16:19]
	v_mfma_f32_16x16x32_bf16 v[60:63], v[132:135], v[164:167], v[60:63]
	v_mfma_f32_16x16x32_bf16 v[56:59], v[140:143], v[164:167], v[56:59]
	v_mfma_f32_16x16x32_bf16 v[44:47], v[132:135], v[182:185], v[44:47]
	v_mfma_f32_16x16x32_bf16 v[40:43], v[140:143], v[182:185], v[40:43]
	v_mfma_f32_16x16x32_bf16 v[36:39], v[132:135], v[190:193], v[36:39]
	v_mfma_f32_16x16x32_bf16 v[32:35], v[140:143], v[190:193], v[32:35]
	s_add_u32 s38, s38, 0xb0080
	s_addc_u32 s39, s39, 0
	s_waitcnt lgkmcnt(0)
	v_mfma_f32_16x16x32_bf16 v[20:23], v[132:135], v[198:201], v[20:23]
	s_add_i32 s40, s40, s48
	s_mov_b32 m0, s40
	v_mfma_f32_16x16x32_bf16 v[16:19], v[140:143], v[198:201], v[16:19]
	s_barrier
	global_load_lds_dwordx4 v150, s[38:39]
	s_add_i32 m0, s40, 0x2000
	s_nop 0
	global_load_lds_dwordx4 v154, s[38:39]
	s_waitcnt vmcnt(6)
	s_barrier
	v_mfma_f32_16x16x32_bf16 v[52:55], v[202:205], v[144:147], v[52:55]
	v_mfma_f32_16x16x32_bf16 v[48:51], v[210:213], v[144:147], v[48:51]
	v_mfma_f32_16x16x32_bf16 v[28:31], v[202:205], v[176:179], v[28:31]
	v_mfma_f32_16x16x32_bf16 v[24:27], v[210:213], v[176:179], v[24:27]
	v_mfma_f32_16x16x32_bf16 v[12:15], v[202:205], v[186:189], v[12:15]
	v_mfma_f32_16x16x32_bf16 v[8:11], v[210:213], v[186:189], v[8:11]
	v_mfma_f32_16x16x32_bf16 v[4:7], v[202:205], v[194:197], v[4:7]
	v_mfma_f32_16x16x32_bf16 v[0:3], v[210:213], v[194:197], v[0:3]
	v_mfma_f32_16x16x32_bf16 v[52:55], v[206:209], v[164:167], v[52:55]
	s_add_i32 s73, s73, 2
	s_add_u32 s36, s36, 0x100
	v_mfma_f32_16x16x32_bf16 v[48:51], v[214:217], v[164:167], v[48:51]
	s_addc_u32 s37, s37, 0
	s_add_u32 s71, s71, 0x100
	v_mfma_f32_16x16x32_bf16 v[28:31], v[206:209], v[182:185], v[28:31]
	s_addc_u32 s72, s72, 0
	s_add_u32 s38, s36, 0xfff50080
	v_mfma_f32_16x16x32_bf16 v[24:27], v[214:217], v[182:185], v[24:27]
	s_addc_u32 s39, s37, -1
	s_cmp_eq_u32 s73, 40
	v_mfma_f32_16x16x32_bf16 v[12:15], v[206:209], v[190:193], v[12:15]
	s_cselect_b32 s41, s7, s39
	s_cselect_b32 s40, s6, s38
	v_mfma_f32_16x16x32_bf16 v[8:11], v[214:217], v[190:193], v[8:11]
	s_cselect_b32 s39, s9, s72
	s_cselect_b32 s38, s8, s71
	v_mfma_f32_16x16x32_bf16 v[4:7], v[206:209], v[198:201], v[4:7]
	s_add_i32 m0, s49, 0xc000
	v_mfma_f32_16x16x32_bf16 v[0:3], v[214:217], v[198:201], v[0:3]
	s_cmp_gt_u32 s73, 41
	s_barrier
.LBB0_928:
	ds_read_b128 v[128:131], v173
	ds_read_b128 v[132:135], v173 offset:1024
	ds_read_b128 v[136:139], v173 offset:2048
	ds_read_b128 v[140:143], v173 offset:3072
	ds_read_b128 v[144:147], v174
	ds_read_b128 v[164:167], v174 offset:1024
	ds_read_b128 v[176:179], v174 offset:2048
	ds_read_b128 v[182:185], v174 offset:3072
	ds_read_b128 v[186:189], v174 offset:4096
	ds_read_b128 v[190:193], v174 offset:5120
	ds_read_b128 v[194:197], v174 offset:6144
	ds_read_b128 v[198:201], v174 offset:7168
	global_load_lds_dwordx4 v156, s[36:37]
	s_add_i32 m0, s49, 0xe000
	s_nop 0
	global_load_lds_dwordx4 v158, s[36:37]
	s_waitcnt lgkmcnt(8)
	s_barrier
	s_waitcnt lgkmcnt(7)
	v_mfma_f32_16x16x32_bf16 v[124:127], v[128:131], v[144:147], v[124:127]
	v_mfma_f32_16x16x32_bf16 v[120:123], v[136:139], v[144:147], v[120:123]
	s_waitcnt lgkmcnt(5)
	v_mfma_f32_16x16x32_bf16 v[116:119], v[128:131], v[176:179], v[116:119]
	v_mfma_f32_16x16x32_bf16 v[108:111], v[136:139], v[176:179], v[108:111]
	s_waitcnt lgkmcnt(3)
	v_mfma_f32_16x16x32_bf16 v[92:95], v[128:131], v[186:189], v[92:95]
	v_mfma_f32_16x16x32_bf16 v[88:91], v[136:139], v[186:189], v[88:91]
	s_waitcnt lgkmcnt(1)
	v_mfma_f32_16x16x32_bf16 v[76:79], v[128:131], v[194:197], v[76:79]
	v_mfma_f32_16x16x32_bf16 v[72:75], v[136:139], v[194:197], v[72:75]
	v_mfma_f32_16x16x32_bf16 v[124:127], v[132:135], v[164:167], v[124:127]
	v_mfma_f32_16x16x32_bf16 v[120:123], v[140:143], v[164:167], v[120:123]
	v_mfma_f32_16x16x32_bf16 v[116:119], v[132:135], v[182:185], v[116:119]
	v_mfma_f32_16x16x32_bf16 v[108:111], v[140:143], v[182:185], v[108:111]
	v_mfma_f32_16x16x32_bf16 v[92:95], v[132:135], v[190:193], v[92:95]
	v_mfma_f32_16x16x32_bf16 v[88:91], v[140:143], v[190:193], v[88:91]
	s_add_i32 s74, s59, s48
	s_add_u32 s86, s38, s16
	s_waitcnt lgkmcnt(0)
	v_mfma_f32_16x16x32_bf16 v[76:79], v[132:135], v[198:201], v[76:79]
	s_addc_u32 s87, s39, s17
	s_mov_b32 m0, s74
	v_mfma_f32_16x16x32_bf16 v[72:75], v[140:143], v[198:201], v[72:75]
	s_barrier
	ds_read_b128 v[202:205], v175
	ds_read_b128 v[206:209], v175 offset:1024
	ds_read_b128 v[210:213], v175 offset:2048
	ds_read_b128 v[214:217], v175 offset:3072
	global_load_lds_dwordx4 v150, s[38:39]
	s_add_i32 m0, s74, 0x2000
	s_nop 0
	global_load_lds_dwordx4 v154, s[38:39]
	s_barrier
; #define PG8_STAGE(bufoff, gbase, voff) do { _Pragma("unroll") for (int _i = 0; _i < 2; ++_i) \
;         __builtin_amdgcn_global_load_lds((const unsigned*)((const char*)(gbase) + (voff)[_i]), (LAS unsigned*)(lds + (bufoff) + ldsw + _i * 8192), 16, 0, 0); } while (0)
; #define PG8_LDA(dst, b, h) do { _Pragma("unroll") for (int m = 0; m < 4; ++m) _Pragma("unroll") for (int k = 0; k < 2; ++k) dst[m][k] = *(const LAS bf16x8*)(lds + PG8_SA(b, h) + aoff + m * 2048 + k * 1024); } while (0)
; #define PG8_LDB(dst, b, h) do { _Pragma("unroll") for (int n = 0; n < 2; ++n) _Pragma("unroll") for (int k = 0; k < 2; ++k) dst[n][k] = *(const LAS bf16x8*)(lds + PG8_SB(b, h) + boff + n * 2048 + k * 1024); } while (0)
; #define PG8_MMA(ai, bj, At, Bt) do { __builtin_amdgcn_s_setprio(1); _Pragma("unroll") for (int m = 0; m < 4; ++m) _Pragma("unroll") for (int n = 0; n < 2; ++n) _Pragma("unroll") for (int k = 0; k < 2; ++k) \
;         acc[ai][bj][m][n] = __builtin_amdgcn_mfma_f32_16x16x32_bf16(Bt[n][k], At[m][k], acc[ai][bj][m][n], 0, 0, 0); __builtin_amdgcn_s_setprio(0); } while (0)
; #define PG8_WAIT_V(n) asm volatile("s_waitcnt vmcnt(" #n ")" ::: "memory")
; #define PG8_WAIT_L(n) asm volatile("s_waitcnt lgkmcnt(" #n ")" ::: "memory")
; #define PG8_BAR __builtin_amdgcn_s_barrier()
; #define PG8_SCHED __builtin_amdgcn_sched_barrier(0)
; template <class Epi>
; DI void gemm_phase(LAS unsigned char* lds, const Gemm g, const StaticOrder& S, const Epi& E) {
;     ...
;             PG8_LDB(B1, 0, 1); PG8_STAGE(PG8_SB(0, 0), b2, voffB);
;             PG8_BAR; PG8_WAIT_L(0); PG8_MMA(0, 1, At, B1); PG8_BAR;
;             PG8_LDA(At, 0, 1); PG8_STAGE(PG8_SA(0, 0), a2, voffA);
;             PG8_BAR; PG8_WAIT_L(0); PG8_MMA(1, 0, At, B0); PG8_BAR; PG8_SCHED;
;             PG8_STAGE(PG8_SB(0, 1), b2 + hstep, voffB);
;             PG8_WAIT_V(6); PG8_BAR; PG8_MMA(1, 1, At, B1); PG8_BAR;
;             PG8_LDB(B0, 1, 0); PG8_SCHED; PG8_LDA(At, 1, 0); PG8_STAGE(PG8_SA(0, 1), a2 + hstep, voffA);
	s_waitcnt lgkmcnt(3)
	v_mfma_f32_16x16x32_bf16 v[112:115], v[202:205], v[144:147], v[112:115]
	s_waitcnt lgkmcnt(1)
	v_mfma_f32_16x16x32_bf16 v[104:107], v[210:213], v[144:147], v[104:107]
	v_mfma_f32_16x16x32_bf16 v[100:103], v[202:205], v[176:179], v[100:103]
	v_mfma_f32_16x16x32_bf16 v[96:99], v[210:213], v[176:179], v[96:99]
	v_mfma_f32_16x16x32_bf16 v[84:87], v[202:205], v[186:189], v[84:87]
	v_mfma_f32_16x16x32_bf16 v[80:83], v[210:213], v[186:189], v[80:83]
	v_mfma_f32_16x16x32_bf16 v[68:71], v[202:205], v[194:197], v[68:71]
	v_mfma_f32_16x16x32_bf16 v[64:67], v[210:213], v[194:197], v[64:67]
	v_mfma_f32_16x16x32_bf16 v[112:115], v[206:209], v[164:167], v[112:115]
	s_waitcnt lgkmcnt(0)
	v_mfma_f32_16x16x32_bf16 v[104:107], v[214:217], v[164:167], v[104:107]
	v_mfma_f32_16x16x32_bf16 v[100:103], v[206:209], v[182:185], v[100:103]
	v_mfma_f32_16x16x32_bf16 v[96:99], v[214:217], v[182:185], v[96:99]
	v_mfma_f32_16x16x32_bf16 v[84:87], v[206:209], v[190:193], v[84:87]
	v_mfma_f32_16x16x32_bf16 v[80:83], v[214:217], v[190:193], v[80:83]
	s_mov_b32 m0, s49
	s_add_u32 s88, s40, s16
	v_mfma_f32_16x16x32_bf16 v[68:71], v[206:209], v[198:201], v[68:71]
	s_addc_u32 s89, s41, s17
	v_mfma_f32_16x16x32_bf16 v[64:67], v[214:217], v[198:201], v[64:67]
	s_barrier
	ds_read_b128 v[144:147], v174 offset:16384
	ds_read_b128 v[164:167], v174 offset:17408
	ds_read_b128 v[176:179], v174 offset:18432
	ds_read_b128 v[182:185], v174 offset:19456
	ds_read_b128 v[186:189], v174 offset:20480
	ds_read_b128 v[190:193], v174 offset:21504
	ds_read_b128 v[194:197], v174 offset:22528
	ds_read_b128 v[198:201], v174 offset:23552
	global_load_lds_dwordx4 v148, s[40:41]
	s_mov_b32 m0, s50
	s_nop 0
	global_load_lds_dwordx4 v152, s[40:41]
	s_barrier
	s_waitcnt lgkmcnt(7)
	v_mfma_f32_16x16x32_bf16 v[60:63], v[128:131], v[144:147], v[60:63]
	v_mfma_f32_16x16x32_bf16 v[56:59], v[136:139], v[144:147], v[56:59]
	s_waitcnt lgkmcnt(5)
	v_mfma_f32_16x16x32_bf16 v[44:47], v[128:131], v[176:179], v[44:47]
	v_mfma_f32_16x16x32_bf16 v[40:43], v[136:139], v[176:179], v[40:43]
	s_waitcnt lgkmcnt(3)
	v_mfma_f32_16x16x32_bf16 v[36:39], v[128:131], v[186:189], v[36:39]
	v_mfma_f32_16x16x32_bf16 v[32:35], v[136:139], v[186:189], v[32:35]
	s_waitcnt lgkmcnt(1)
	v_mfma_f32_16x16x32_bf16 v[20:23], v[128:131], v[194:197], v[20:23]
	v_mfma_f32_16x16x32_bf16 v[16:19], v[136:139], v[194:197], v[16:19]
	v_mfma_f32_16x16x32_bf16 v[60:63], v[132:135], v[164:167], v[60:63]
	v_mfma_f32_16x16x32_bf16 v[56:59], v[140:143], v[164:167], v[56:59]
	v_mfma_f32_16x16x32_bf16 v[44:47], v[132:135], v[182:185], v[44:47]
	v_mfma_f32_16x16x32_bf16 v[40:43], v[140:143], v[182:185], v[40:43]
	v_mfma_f32_16x16x32_bf16 v[36:39], v[132:135], v[190:193], v[36:39]
	v_mfma_f32_16x16x32_bf16 v[32:35], v[140:143], v[190:193], v[32:35]
	s_add_u32 s74, s38, 0xb0000
	s_addc_u32 s75, s39, 0
	s_waitcnt lgkmcnt(0)
	v_mfma_f32_16x16x32_bf16 v[20:23], v[132:135], v[198:201], v[20:23]
	s_add_i32 s76, s60, s48
	s_mov_b32 m0, s76
	v_mfma_f32_16x16x32_bf16 v[16:19], v[140:143], v[198:201], v[16:19]
	s_barrier
	global_load_lds_dwordx4 v150, s[74:75]
	s_add_i32 m0, s76, 0x2000
	s_nop 0
	global_load_lds_dwordx4 v154, s[74:75]
	s_waitcnt vmcnt(6)
	s_barrier
	v_mfma_f32_16x16x32_bf16 v[52:55], v[202:205], v[144:147], v[52:55]
	v_mfma_f32_16x16x32_bf16 v[48:51], v[210:213], v[144:147], v[48:51]
	v_mfma_f32_16x16x32_bf16 v[28:31], v[202:205], v[176:179], v[28:31]
	v_mfma_f32_16x16x32_bf16 v[24:27], v[210:213], v[176:179], v[24:27]
	v_mfma_f32_16x16x32_bf16 v[12:15], v[202:205], v[186:189], v[12:15]
	v_mfma_f32_16x16x32_bf16 v[8:11], v[210:213], v[186:189], v[8:11]
	v_mfma_f32_16x16x32_bf16 v[4:7], v[202:205], v[194:197], v[4:7]
	v_mfma_f32_16x16x32_bf16 v[0:3], v[210:213], v[194:197], v[0:3]
	v_mfma_f32_16x16x32_bf16 v[52:55], v[206:209], v[164:167], v[52:55]
	v_mfma_f32_16x16x32_bf16 v[48:51], v[214:217], v[164:167], v[48:51]
	v_mfma_f32_16x16x32_bf16 v[28:31], v[206:209], v[182:185], v[28:31]
	v_mfma_f32_16x16x32_bf16 v[24:27], v[214:217], v[182:185], v[24:27]
	v_mfma_f32_16x16x32_bf16 v[12:15], v[206:209], v[190:193], v[12:15]
	v_mfma_f32_16x16x32_bf16 v[8:11], v[214:217], v[190:193], v[8:11]
	v_mfma_f32_16x16x32_bf16 v[4:7], v[206:209], v[198:201], v[4:7]
	s_add_i32 s74, 0, 0x18000
	v_mfma_f32_16x16x32_bf16 v[0:3], v[214:217], v[198:201], v[0:3]
	s_barrier
	ds_read_b128 v[128:131], v253
	ds_read_b128 v[132:135], v253 offset:1024
	ds_read_b128 v[136:139], v253 offset:2048
	ds_read_b128 v[140:143], v253 offset:3072
	s_add_u32 s40, s40, 0xb0000
	s_addc_u32 s41, s41, 0
	s_mov_b32 m0, s51
	ds_read_b128 v[144:147], v174 offset:32768
	ds_read_b128 v[164:167], v174 offset:33792
	ds_read_b128 v[176:179], v174 offset:34816
	ds_read_b128 v[182:185], v174 offset:35840
	ds_read_b128 v[186:189], v174 offset:36864
	ds_read_b128 v[190:193], v174 offset:37888
	ds_read_b128 v[194:197], v174 offset:38912
	ds_read_b128 v[198:201], v174 offset:39936
	global_load_lds_dwordx4 v148, s[40:41]
	s_mov_b32 m0, s52
	s_nop 0
	global_load_lds_dwordx4 v152, s[40:41]
	s_waitcnt lgkmcnt(8)
	s_barrier
; #define PG8_STAGE(bufoff, gbase, voff) do { _Pragma("unroll") for (int _i = 0; _i < 2; ++_i) \
;         __builtin_amdgcn_global_load_lds((const unsigned*)((const char*)(gbase) + (voff)[_i]), (LAS unsigned*)(lds + (bufoff) + ldsw + _i * 8192), 16, 0, 0); } while (0)
; #define PG8_LDA(dst, b, h) do { _Pragma("unroll") for (int m = 0; m < 4; ++m) _Pragma("unroll") for (int k = 0; k < 2; ++k) dst[m][k] = *(const LAS bf16x8*)(lds + PG8_SA(b, h) + aoff + m * 2048 + k * 1024); } while (0)
; #define PG8_LDB(dst, b, h) do { _Pragma("unroll") for (int n = 0; n < 2; ++n) _Pragma("unroll") for (int k = 0; k < 2; ++k) dst[n][k] = *(const LAS bf16x8*)(lds + PG8_SB(b, h) + boff + n * 2048 + k * 1024); } while (0)
; #define PG8_MMA(ai, bj, At, Bt) do { __builtin_amdgcn_s_setprio(1); _Pragma("unroll") for (int m = 0; m < 4; ++m) _Pragma("unroll") for (int n = 0; n < 2; ++n) _Pragma("unroll") for (int k = 0; k < 2; ++k) \
;         acc[ai][bj][m][n] = __builtin_amdgcn_mfma_f32_16x16x32_bf16(Bt[n][k], At[m][k], acc[ai][bj][m][n], 0, 0, 0); __builtin_amdgcn_s_setprio(0); } while (0)
; #define PG8_WAIT_V(n) asm volatile("s_waitcnt vmcnt(" #n ")" ::: "memory")
; #define PG8_WAIT_L(n) asm volatile("s_waitcnt lgkmcnt(" #n ")" ::: "memory")
; #define PG8_BAR __builtin_amdgcn_s_barrier()
; #define PG8_SCHED __builtin_amdgcn_sched_barrier(0)
; template <class Epi>
; DI void gemm_phase(LAS unsigned char* lds, const Gemm g, const StaticOrder& S, const Epi& E) {
;     ...
;             PG8_LDB(B0, 1, 0); PG8_SCHED; PG8_LDA(At, 1, 0); PG8_STAGE(PG8_SA(0, 1), a2 + hstep, voffA);
;             PG8_WAIT_L(8); PG8_BAR; PG8_WAIT_L(0); PG8_MMA(0, 0, At, B0); PG8_BAR; PG8_SCHED;
;             PG8_LDB(B1, 1, 1); PG8_STAGE(PG8_SB(1, 0), b3, voffB);
;             PG8_BAR; PG8_WAIT_L(0); PG8_MMA(0, 1, At, B1); PG8_BAR;
;             PG8_LDA(At, 1, 1); PG8_STAGE(PG8_SA(1, 0), a3, voffA);
;             PG8_BAR; PG8_WAIT_L(0); PG8_MMA(1, 0, At, B0); PG8_BAR; PG8_SCHED;
;             PG8_STAGE(PG8_SB(1, 1), b3 + hstep, voffB);
;             PG8_WAIT_V(6); PG8_BAR; PG8_MMA(1, 1, At, B1); PG8_BAR;
	s_waitcnt lgkmcnt(7)
	v_mfma_f32_16x16x32_bf16 v[124:127], v[128:131], v[144:147], v[124:127]
	v_mfma_f32_16x16x32_bf16 v[120:123], v[136:139], v[144:147], v[120:123]
	s_waitcnt lgkmcnt(5)
	v_mfma_f32_16x16x32_bf16 v[116:119], v[128:131], v[176:179], v[116:119]
	v_mfma_f32_16x16x32_bf16 v[108:111], v[136:139], v[176:179], v[108:111]
	s_waitcnt lgkmcnt(3)
	v_mfma_f32_16x16x32_bf16 v[92:95], v[128:131], v[186:189], v[92:95]
	v_mfma_f32_16x16x32_bf16 v[88:91], v[136:139], v[186:189], v[88:91]
	s_waitcnt lgkmcnt(1)
	v_mfma_f32_16x16x32_bf16 v[76:79], v[128:131], v[194:197], v[76:79]
	v_mfma_f32_16x16x32_bf16 v[72:75], v[136:139], v[194:197], v[72:75]
	v_mfma_f32_16x16x32_bf16 v[124:127], v[132:135], v[164:167], v[124:127]
	v_mfma_f32_16x16x32_bf16 v[120:123], v[140:143], v[164:167], v[120:123]
	v_mfma_f32_16x16x32_bf16 v[116:119], v[132:135], v[182:185], v[116:119]
	v_mfma_f32_16x16x32_bf16 v[108:111], v[140:143], v[182:185], v[108:111]
	v_mfma_f32_16x16x32_bf16 v[92:95], v[132:135], v[190:193], v[92:95]
	v_mfma_f32_16x16x32_bf16 v[88:91], v[140:143], v[190:193], v[88:91]
	s_add_i32 s40, 0, 0x1c000
	s_add_i32 s41, s74, s48
	s_waitcnt lgkmcnt(0)
	v_mfma_f32_16x16x32_bf16 v[76:79], v[132:135], v[198:201], v[76:79]
	s_mov_b32 m0, s41
	v_mfma_f32_16x16x32_bf16 v[72:75], v[140:143], v[198:201], v[72:75]
	s_barrier
	ds_read_b128 v[202:205], v252
	ds_read_b128 v[206:209], v252 offset:1024
	ds_read_b128 v[210:213], v252 offset:2048
	ds_read_b128 v[214:217], v252 offset:3072
	global_load_lds_dwordx4 v150, s[86:87]
	s_add_i32 m0, s41, 0x2000
	s_nop 0
	global_load_lds_dwordx4 v154, s[86:87]
	s_barrier
	s_waitcnt lgkmcnt(3)
	v_mfma_f32_16x16x32_bf16 v[112:115], v[202:205], v[144:147], v[112:115]
	s_waitcnt lgkmcnt(1)
	v_mfma_f32_16x16x32_bf16 v[104:107], v[210:213], v[144:147], v[104:107]
	v_mfma_f32_16x16x32_bf16 v[100:103], v[202:205], v[176:179], v[100:103]
	v_mfma_f32_16x16x32_bf16 v[96:99], v[210:213], v[176:179], v[96:99]
	v_mfma_f32_16x16x32_bf16 v[84:87], v[202:205], v[186:189], v[84:87]
	v_mfma_f32_16x16x32_bf16 v[80:83], v[210:213], v[186:189], v[80:83]
	v_mfma_f32_16x16x32_bf16 v[68:71], v[202:205], v[194:197], v[68:71]
	v_mfma_f32_16x16x32_bf16 v[64:67], v[210:213], v[194:197], v[64:67]
	v_mfma_f32_16x16x32_bf16 v[112:115], v[206:209], v[164:167], v[112:115]
	s_waitcnt lgkmcnt(0)
	v_mfma_f32_16x16x32_bf16 v[104:107], v[214:217], v[164:167], v[104:107]
	v_mfma_f32_16x16x32_bf16 v[100:103], v[206:209], v[182:185], v[100:103]
	v_mfma_f32_16x16x32_bf16 v[96:99], v[214:217], v[182:185], v[96:99]
	v_mfma_f32_16x16x32_bf16 v[84:87], v[206:209], v[190:193], v[84:87]
	v_mfma_f32_16x16x32_bf16 v[80:83], v[214:217], v[190:193], v[80:83]
	v_mfma_f32_16x16x32_bf16 v[68:71], v[206:209], v[198:201], v[68:71]
	s_mov_b32 m0, s56
	v_mfma_f32_16x16x32_bf16 v[64:67], v[214:217], v[198:201], v[64:67]
	s_barrier
	ds_read_b128 v[144:147], v174 offset:49152
	ds_read_b128 v[164:167], v174 offset:50176
	ds_read_b128 v[176:179], v174 offset:51200
	ds_read_b128 v[182:185], v174 offset:52224
	ds_read_b128 v[186:189], v174 offset:53248
	ds_read_b128 v[190:193], v174 offset:54272
	ds_read_b128 v[194:197], v174 offset:55296
	ds_read_b128 v[198:201], v174 offset:56320
	global_load_lds_dwordx4 v148, s[88:89]
	s_mov_b32 m0, s57
	s_nop 0
	global_load_lds_dwordx4 v152, s[88:89]
	s_barrier
	s_waitcnt lgkmcnt(7)
	v_mfma_f32_16x16x32_bf16 v[60:63], v[128:131], v[144:147], v[60:63]
	v_mfma_f32_16x16x32_bf16 v[56:59], v[136:139], v[144:147], v[56:59]
	s_waitcnt lgkmcnt(5)
	v_mfma_f32_16x16x32_bf16 v[44:47], v[128:131], v[176:179], v[44:47]
	v_mfma_f32_16x16x32_bf16 v[40:43], v[136:139], v[176:179], v[40:43]
	s_waitcnt lgkmcnt(3)
	v_mfma_f32_16x16x32_bf16 v[36:39], v[128:131], v[186:189], v[36:39]
	v_mfma_f32_16x16x32_bf16 v[32:35], v[136:139], v[186:189], v[32:35]
	s_waitcnt lgkmcnt(1)
	v_mfma_f32_16x16x32_bf16 v[20:23], v[128:131], v[194:197], v[20:23]
	v_mfma_f32_16x16x32_bf16 v[16:19], v[136:139], v[194:197], v[16:19]
	v_mfma_f32_16x16x32_bf16 v[60:63], v[132:135], v[164:167], v[60:63]
	v_mfma_f32_16x16x32_bf16 v[56:59], v[140:143], v[164:167], v[56:59]
	v_mfma_f32_16x16x32_bf16 v[44:47], v[132:135], v[182:185], v[44:47]
	v_mfma_f32_16x16x32_bf16 v[40:43], v[140:143], v[182:185], v[40:43]
	v_mfma_f32_16x16x32_bf16 v[36:39], v[132:135], v[190:193], v[36:39]
	v_mfma_f32_16x16x32_bf16 v[32:35], v[140:143], v[190:193], v[32:35]
	s_add_u32 s38, s38, 0xb0080
	s_addc_u32 s39, s39, 0
	s_waitcnt lgkmcnt(0)
	v_mfma_f32_16x16x32_bf16 v[20:23], v[132:135], v[198:201], v[20:23]
	s_add_i32 s40, s40, s48
	s_mov_b32 m0, s40
	v_mfma_f32_16x16x32_bf16 v[16:19], v[140:143], v[198:201], v[16:19]
	s_barrier
	global_load_lds_dwordx4 v150, s[38:39]
	s_add_i32 m0, s40, 0x2000
	s_nop 0
	global_load_lds_dwordx4 v154, s[38:39]
	s_waitcnt vmcnt(6)
	s_barrier
	v_mfma_f32_16x16x32_bf16 v[52:55], v[202:205], v[144:147], v[52:55]
	v_mfma_f32_16x16x32_bf16 v[48:51], v[210:213], v[144:147], v[48:51]
	v_mfma_f32_16x16x32_bf16 v[28:31], v[202:205], v[176:179], v[28:31]
	v_mfma_f32_16x16x32_bf16 v[24:27], v[210:213], v[176:179], v[24:27]
	v_mfma_f32_16x16x32_bf16 v[12:15], v[202:205], v[186:189], v[12:15]
	v_mfma_f32_16x16x32_bf16 v[8:11], v[210:213], v[186:189], v[8:11]
	v_mfma_f32_16x16x32_bf16 v[4:7], v[202:205], v[194:197], v[4:7]
	v_mfma_f32_16x16x32_bf16 v[0:3], v[210:213], v[194:197], v[0:3]
	v_mfma_f32_16x16x32_bf16 v[52:55], v[206:209], v[164:167], v[52:55]
	s_add_i32 s73, s73, 2
	s_add_u32 s36, s36, 0x100
	v_mfma_f32_16x16x32_bf16 v[48:51], v[214:217], v[164:167], v[48:51]
	s_addc_u32 s37, s37, 0
	s_add_u32 s71, s71, 0x100
	v_mfma_f32_16x16x32_bf16 v[28:31], v[206:209], v[182:185], v[28:31]
	s_addc_u32 s72, s72, 0
	s_add_u32 s38, s36, 0xfff50080
	v_mfma_f32_16x16x32_bf16 v[24:27], v[214:217], v[182:185], v[24:27]
	s_addc_u32 s39, s37, -1
	s_cmp_eq_u32 s73, 40
	v_mfma_f32_16x16x32_bf16 v[12:15], v[206:209], v[190:193], v[12:15]
	s_cselect_b32 s41, s7, s39
	s_cselect_b32 s40, s6, s38
	v_mfma_f32_16x16x32_bf16 v[8:11], v[214:217], v[190:193], v[8:11]
	s_cselect_b32 s39, s9, s72
	s_cselect_b32 s38, s8, s71
	v_mfma_f32_16x16x32_bf16 v[4:7], v[206:209], v[198:201], v[4:7]
	s_add_i32 m0, s49, 0xc000
	v_mfma_f32_16x16x32_bf16 v[0:3], v[214:217], v[198:201], v[0:3]
	s_cmp_gt_u32 s73, 41
	s_barrier
; DI unsigned pk2(float a, float b) { f32x2 v = {a, b}; bf16x2_t r = __builtin_convertvector(v, bf16x2_t); return __builtin_bit_cast(unsigned, r); }
; DI float bflo(unsigned u) { return __uint_as_float(u << 16); }
; DI float bfhi(unsigned u) { return __uint_as_float(u & 0xffff0000u); }
; template <class Epi>
; DI void gemm_phase(LAS unsigned char* lds, const Gemm g, const StaticOrder& S, const Epi& E) {
;     ...
;         if (!has_next) break;
;     DI void operator()(const f32x4 (&acc)[2][2][4][2], const Unit& u, int wr, int wc, int fr, int fq) const {
;         const int row0 = u.pm * BM + wr * 64 + fr, col0 = u.pn * BM + wc * 32 + 8 * fq;
;         const float* gp = gate + (size_t)((u.pm * BM) >> 12) * NMODC + col0;
;         f32x4 gv[2][2];
; #pragma unroll
;         for (int bj = 0; bj < 2; ++bj)
; #pragma unroll
;             for (int n = 0; n < 2; ++n) gv[bj][n] = *(const f32x4*)(gp + bj * HALF + n * 4);
; #pragma unroll
;         for (int ai = 0; ai < 2; ++ai)
; #pragma unroll
;             for (int m = 0; m < 4; ++m) { const size_t ro = (size_t)(row0 + ai * HALF + m * 16) * DM + col0;
; #pragma unroll
;                 for (int bj = 0; bj < 2; ++bj) {
;                     const u32x4 q = *(const u32x4*)(xb + ro + bj * HALF);
;                     const f32x4 b0 = {bflo(q.x), bfhi(q.x), bflo(q.y), bfhi(q.y)}, b1 = {bflo(q.z), bfhi(q.z), bflo(q.w), bfhi(q.w)};
;                     const f32x4 x0 = b0 + gv[bj][0] * acc[ai][bj][m][0], x1 = b1 + gv[bj][1] * acc[ai][bj][m][1];
;                     u32x4 w; w.x = pk2(x0.x, x0.y); w.y = pk2(x0.z, x0.w); w.z = pk2(x1.x, x1.y); w.w = pk2(x1.z, x1.w);
;                     *(u32x4*)(xb + ro + bj * HALF) = w; } }
	s_cbranch_scc0 .LBB0_928
	v_lshl_add_u32 v147, s67, 8, v170
	v_lshl_or_b32 v164, s70, 8, v172
	s_ashr_i32 s36, s67, 4
	s_mul_hi_i32 s37, s36, 0x6000
	s_mulk_i32 s36, 0x6000
	s_add_u32 s36, s54, s36
	s_addc_u32 s37, s55, s37
	v_lshlrev_b32_e32 v145, 2, v164
	v_lshlrev_b32_e32 v144, 11, v147
	global_load_dwordx4 v[128:131], v145, s[36:37]
	global_load_dwordx4 v[132:135], v145, s[36:37] offset:16
	global_load_dwordx4 v[136:139], v145, s[36:37] offset:512
	global_load_dwordx4 v[140:143], v145, s[36:37] offset:528
	v_lshl_add_u32 v144, v164, 1, v144
	s_mov_b32 s70, s65
	s_mov_b32 s67, s66
	s_mov_b64 s[38:39], s[8:9]
	s_mov_b64 s[36:37], s[6:7]
	global_load_dwordx4 v[184:187], v144, s[14:15]
	global_load_dwordx4 v[188:191], v144, s[14:15] offset:256
	v_add_u32_e32 v146, 0x8000, v144
	global_load_dwordx4 v[192:195], v146, s[14:15]
	global_load_dwordx4 v[196:199], v146, s[14:15] offset:256
	v_add_u32_e32 v146, 0x10000, v144
	global_load_dwordx4 v[200:203], v146, s[14:15]
	global_load_dwordx4 v[204:207], v146, s[14:15] offset:256
	v_add_u32_e32 v146, 0x18000, v144
	global_load_dwordx4 v[208:211], v146, s[14:15]
	global_load_dwordx4 v[212:215], v146, s[14:15] offset:256
	v_add_u32_e32 v146, 0x40000, v144
	global_load_dwordx4 v[216:219], v146, s[14:15]
	global_load_dwordx4 v[220:223], v146, s[14:15] offset:256
	v_add_u32_e32 v146, 0x48000, v144
	global_load_dwordx4 v[224:227], v146, s[14:15]
	global_load_dwordx4 v[228:231], v146, s[14:15] offset:256
	v_add_u32_e32 v146, 0x50000, v144
	global_load_dwordx4 v[232:235], v146, s[14:15]
	global_load_dwordx4 v[236:239], v146, s[14:15] offset:256
	v_add_u32_e32 v146, 0x58000, v144
	global_load_dwordx4 v[240:243], v146, s[14:15]
	global_load_dwordx4 v[244:247], v146, s[14:15] offset:256
	s_waitcnt vmcnt(15)
	v_lshlrev_b32_e32 v248, 16, v184
	v_and_b32_e32 v249, 0xffff0000, v184
	v_lshlrev_b32_e32 v250, 16, v185
	v_and_b32_e32 v251, 0xffff0000, v185
	v_lshlrev_b32_e32 v252, 16, v186
	v_and_b32_e32 v253, 0xffff0000, v186
	v_lshlrev_b32_e32 v254, 16, v187
	v_and_b32_e32 v255, 0xffff0000, v187
	v_pk_fma_f32 v[124:125], v[124:125], v[128:129], v[248:249]
	v_pk_fma_f32 v[126:127], v[126:127], v[130:131], v[250:251]
	v_pk_fma_f32 v[120:121], v[120:121], v[132:133], v[252:253]
	v_pk_fma_f32 v[122:123], v[122:123], v[134:135], v[254:255]
	v_cvt_pk_bf16_f32 v124, v124, v125
	v_cvt_pk_bf16_f32 v125, v126, v127
	v_cvt_pk_bf16_f32 v126, v120, v121
	v_cvt_pk_bf16_f32 v127, v122, v123
	global_store_dwordx4 v144, v[124:127], s[14:15]
	s_waitcnt vmcnt(15)
	v_lshlrev_b32_e32 v248, 16, v188
	v_and_b32_e32 v249, 0xffff0000, v188
	v_lshlrev_b32_e32 v250, 16, v189
	v_and_b32_e32 v251, 0xffff0000, v189
	v_lshlrev_b32_e32 v252, 16, v190
	v_and_b32_e32 v253, 0xffff0000, v190
	v_lshlrev_b32_e32 v254, 16, v191
	v_and_b32_e32 v255, 0xffff0000, v191
	v_pk_fma_f32 v[112:113], v[112:113], v[136:137], v[248:249]
	v_pk_fma_f32 v[114:115], v[114:115], v[138:139], v[250:251]
	v_pk_fma_f32 v[104:105], v[104:105], v[140:141], v[252:253]
	v_pk_fma_f32 v[106:107], v[106:107], v[142:143], v[254:255]
	v_cvt_pk_bf16_f32 v112, v112, v113
	v_cvt_pk_bf16_f32 v113, v114, v115
	v_cvt_pk_bf16_f32 v114, v104, v105
	v_cvt_pk_bf16_f32 v115, v106, v107
	global_store_dwordx4 v144, v[112:115], s[14:15] offset:256
	s_waitcnt vmcnt(15)
	v_lshlrev_b32_e32 v248, 16, v192
	v_and_b32_e32 v249, 0xffff0000, v192
	v_lshlrev_b32_e32 v250, 16, v193
	v_and_b32_e32 v251, 0xffff0000, v193
	v_lshlrev_b32_e32 v252, 16, v194
	v_and_b32_e32 v253, 0xffff0000, v194
	v_lshlrev_b32_e32 v254, 16, v195
	v_and_b32_e32 v255, 0xffff0000, v195
	v_pk_fma_f32 v[116:117], v[116:117], v[128:129], v[248:249]
	v_pk_fma_f32 v[118:119], v[118:119], v[130:131], v[250:251]
	v_pk_fma_f32 v[108:109], v[108:109], v[132:133], v[252:253]
	v_pk_fma_f32 v[110:111], v[110:111], v[134:135], v[254:255]
	v_cvt_pk_bf16_f32 v116, v116, v117
	v_cvt_pk_bf16_f32 v117, v118, v119
	v_cvt_pk_bf16_f32 v118, v108, v109
	v_cvt_pk_bf16_f32 v119, v110, v111
	v_add_u32_e32 v146, 0x8000, v144
	global_store_dwordx4 v146, v[116:119], s[14:15]
	s_waitcnt vmcnt(15)
	v_lshlrev_b32_e32 v248, 16, v196
	v_and_b32_e32 v249, 0xffff0000, v196
	v_lshlrev_b32_e32 v250, 16, v197
	v_and_b32_e32 v251, 0xffff0000, v197
	v_lshlrev_b32_e32 v252, 16, v198
	v_and_b32_e32 v253, 0xffff0000, v198
	v_lshlrev_b32_e32 v254, 16, v199
	v_and_b32_e32 v255, 0xffff0000, v199
	v_pk_fma_f32 v[100:101], v[100:101], v[136:137], v[248:249]
	v_pk_fma_f32 v[102:103], v[102:103], v[138:139], v[250:251]
	v_pk_fma_f32 v[96:97], v[96:97], v[140:141], v[252:253]
	v_pk_fma_f32 v[98:99], v[98:99], v[142:143], v[254:255]
	v_cvt_pk_bf16_f32 v100, v100, v101
	v_cvt_pk_bf16_f32 v101, v102, v103
	v_cvt_pk_bf16_f32 v102, v96, v97
	v_cvt_pk_bf16_f32 v103, v98, v99
	v_add_u32_e32 v146, 0x8000, v144
	global_store_dwordx4 v146, v[100:103], s[14:15] offset:256
	s_waitcnt vmcnt(15)
	v_lshlrev_b32_e32 v248, 16, v200
	v_and_b32_e32 v249, 0xffff0000, v200
	v_lshlrev_b32_e32 v250, 16, v201
	v_and_b32_e32 v251, 0xffff0000, v201
	v_lshlrev_b32_e32 v252, 16, v202
	v_and_b32_e32 v253, 0xffff0000, v202
	v_lshlrev_b32_e32 v254, 16, v203
	v_and_b32_e32 v255, 0xffff0000, v203
	v_pk_fma_f32 v[92:93], v[92:93], v[128:129], v[248:249]
	v_pk_fma_f32 v[94:95], v[94:95], v[130:131], v[250:251]
	v_pk_fma_f32 v[88:89], v[88:89], v[132:133], v[252:253]
	v_pk_fma_f32 v[90:91], v[90:91], v[134:135], v[254:255]
	v_cvt_pk_bf16_f32 v92, v92, v93
	v_cvt_pk_bf16_f32 v93, v94, v95
	v_cvt_pk_bf16_f32 v94, v88, v89
	v_cvt_pk_bf16_f32 v95, v90, v91
	v_add_u32_e32 v146, 0x10000, v144
	global_store_dwordx4 v146, v[92:95], s[14:15]
	s_waitcnt vmcnt(15)
; DI unsigned pk2(float a, float b) { f32x2 v = {a, b}; bf16x2_t r = __builtin_convertvector(v, bf16x2_t); return __builtin_bit_cast(unsigned, r); }
; DI float bflo(unsigned u) { return __uint_as_float(u << 16); }
; DI float bfhi(unsigned u) { return __uint_as_float(u & 0xffff0000u); }
;     DI void operator()(const f32x4 (&acc)[2][2][4][2], const Unit& u, int wr, int wc, int fr, int fq) const {
;     ...
;         for (int ai = 0; ai < 2; ++ai)
; #pragma unroll
;             for (int m = 0; m < 4; ++m) { const size_t ro = (size_t)(row0 + ai * HALF + m * 16) * DM + col0;
; #pragma unroll
;                 for (int bj = 0; bj < 2; ++bj) {
;                     const u32x4 q = *(const u32x4*)(xb + ro + bj * HALF);
;                     const f32x4 b0 = {bflo(q.x), bfhi(q.x), bflo(q.y), bfhi(q.y)}, b1 = {bflo(q.z), bfhi(q.z), bflo(q.w), bfhi(q.w)};
;                     const f32x4 x0 = b0 + gv[bj][0] * acc[ai][bj][m][0], x1 = b1 + gv[bj][1] * acc[ai][bj][m][1];
;                     u32x4 w; w.x = pk2(x0.x, x0.y); w.y = pk2(x0.z, x0.w); w.z = pk2(x1.x, x1.y); w.w = pk2(x1.z, x1.w);
;                     *(u32x4*)(xb + ro + bj * HALF) = w; } }
	v_lshlrev_b32_e32 v248, 16, v204
	v_and_b32_e32 v249, 0xffff0000, v204
	v_lshlrev_b32_e32 v250, 16, v205
	v_and_b32_e32 v251, 0xffff0000, v205
	v_lshlrev_b32_e32 v252, 16, v206
	v_and_b32_e32 v253, 0xffff0000, v206
	v_lshlrev_b32_e32 v254, 16, v207
	v_and_b32_e32 v255, 0xffff0000, v207
	v_pk_fma_f32 v[84:85], v[84:85], v[136:137], v[248:249]
	v_pk_fma_f32 v[86:87], v[86:87], v[138:139], v[250:251]
	v_pk_fma_f32 v[80:81], v[80:81], v[140:141], v[252:253]
	v_pk_fma_f32 v[82:83], v[82:83], v[142:143], v[254:255]
	v_cvt_pk_bf16_f32 v84, v84, v85
	v_cvt_pk_bf16_f32 v85, v86, v87
	v_cvt_pk_bf16_f32 v86, v80, v81
	v_cvt_pk_bf16_f32 v87, v82, v83
	v_add_u32_e32 v146, 0x10000, v144
	global_store_dwordx4 v146, v[84:87], s[14:15] offset:256
	s_waitcnt vmcnt(15)
	v_lshlrev_b32_e32 v248, 16, v208
	v_and_b32_e32 v249, 0xffff0000, v208
	v_lshlrev_b32_e32 v250, 16, v209
	v_and_b32_e32 v251, 0xffff0000, v209
	v_lshlrev_b32_e32 v252, 16, v210
	v_and_b32_e32 v253, 0xffff0000, v210
	v_lshlrev_b32_e32 v254, 16, v211
	v_and_b32_e32 v255, 0xffff0000, v211
	v_pk_fma_f32 v[76:77], v[76:77], v[128:129], v[248:249]
	v_pk_fma_f32 v[78:79], v[78:79], v[130:131], v[250:251]
	v_pk_fma_f32 v[72:73], v[72:73], v[132:133], v[252:253]
	v_pk_fma_f32 v[74:75], v[74:75], v[134:135], v[254:255]
	v_cvt_pk_bf16_f32 v76, v76, v77
	v_cvt_pk_bf16_f32 v77, v78, v79
	v_cvt_pk_bf16_f32 v78, v72, v73
	v_cvt_pk_bf16_f32 v79, v74, v75
	v_add_u32_e32 v146, 0x18000, v144
	global_store_dwordx4 v146, v[76:79], s[14:15]
	s_waitcnt vmcnt(15)
	v_lshlrev_b32_e32 v248, 16, v212
	v_and_b32_e32 v249, 0xffff0000, v212
	v_lshlrev_b32_e32 v250, 16, v213
	v_and_b32_e32 v251, 0xffff0000, v213
	v_lshlrev_b32_e32 v252, 16, v214
	v_and_b32_e32 v253, 0xffff0000, v214
	v_lshlrev_b32_e32 v254, 16, v215
	v_and_b32_e32 v255, 0xffff0000, v215
	v_pk_fma_f32 v[68:69], v[68:69], v[136:137], v[248:249]
	v_pk_fma_f32 v[70:71], v[70:71], v[138:139], v[250:251]
	v_pk_fma_f32 v[64:65], v[64:65], v[140:141], v[252:253]
	v_pk_fma_f32 v[66:67], v[66:67], v[142:143], v[254:255]
	v_cvt_pk_bf16_f32 v68, v68, v69
	v_cvt_pk_bf16_f32 v69, v70, v71
	v_cvt_pk_bf16_f32 v70, v64, v65
	v_cvt_pk_bf16_f32 v71, v66, v67
	v_add_u32_e32 v146, 0x18000, v144
	global_store_dwordx4 v146, v[68:71], s[14:15] offset:256
	s_waitcnt vmcnt(15)
	v_lshlrev_b32_e32 v248, 16, v216
	v_and_b32_e32 v249, 0xffff0000, v216
	v_lshlrev_b32_e32 v250, 16, v217
	v_and_b32_e32 v251, 0xffff0000, v217
	v_lshlrev_b32_e32 v252, 16, v218
	v_and_b32_e32 v253, 0xffff0000, v218
	v_lshlrev_b32_e32 v254, 16, v219
	v_and_b32_e32 v255, 0xffff0000, v219
	v_pk_fma_f32 v[60:61], v[60:61], v[128:129], v[248:249]
	v_pk_fma_f32 v[62:63], v[62:63], v[130:131], v[250:251]
	v_pk_fma_f32 v[56:57], v[56:57], v[132:133], v[252:253]
	v_pk_fma_f32 v[58:59], v[58:59], v[134:135], v[254:255]
	v_cvt_pk_bf16_f32 v60, v60, v61
	v_cvt_pk_bf16_f32 v61, v62, v63
	v_cvt_pk_bf16_f32 v62, v56, v57
	v_cvt_pk_bf16_f32 v63, v58, v59
	v_add_u32_e32 v146, 0x40000, v144
	global_store_dwordx4 v146, v[60:63], s[14:15]
	s_waitcnt vmcnt(15)
	v_lshlrev_b32_e32 v248, 16, v220
	v_and_b32_e32 v249, 0xffff0000, v220
	v_lshlrev_b32_e32 v250, 16, v221
	v_and_b32_e32 v251, 0xffff0000, v221
	v_lshlrev_b32_e32 v252, 16, v222
	v_and_b32_e32 v253, 0xffff0000, v222
	v_lshlrev_b32_e32 v254, 16, v223
	v_and_b32_e32 v255, 0xffff0000, v223
	v_pk_fma_f32 v[52:53], v[52:53], v[136:137], v[248:249]
	v_pk_fma_f32 v[54:55], v[54:55], v[138:139], v[250:251]
	v_pk_fma_f32 v[48:49], v[48:49], v[140:141], v[252:253]
	v_pk_fma_f32 v[50:51], v[50:51], v[142:143], v[254:255]
	v_cvt_pk_bf16_f32 v52, v52, v53
	v_cvt_pk_bf16_f32 v53, v54, v55
	v_cvt_pk_bf16_f32 v54, v48, v49
	v_cvt_pk_bf16_f32 v55, v50, v51
	v_add_u32_e32 v146, 0x40000, v144
	global_store_dwordx4 v146, v[52:55], s[14:15] offset:256
	s_waitcnt vmcnt(15)
	v_lshlrev_b32_e32 v248, 16, v224
	v_and_b32_e32 v249, 0xffff0000, v224
	v_lshlrev_b32_e32 v250, 16, v225
	v_and_b32_e32 v251, 0xffff0000, v225
	v_lshlrev_b32_e32 v252, 16, v226
	v_and_b32_e32 v253, 0xffff0000, v226
	v_lshlrev_b32_e32 v254, 16, v227
	v_and_b32_e32 v255, 0xffff0000, v227
	v_pk_fma_f32 v[44:45], v[44:45], v[128:129], v[248:249]
	v_pk_fma_f32 v[46:47], v[46:47], v[130:131], v[250:251]
	v_pk_fma_f32 v[40:41], v[40:41], v[132:133], v[252:253]
	v_pk_fma_f32 v[42:43], v[42:43], v[134:135], v[254:255]
	v_cvt_pk_bf16_f32 v44, v44, v45
	v_cvt_pk_bf16_f32 v45, v46, v47
	v_cvt_pk_bf16_f32 v46, v40, v41
	v_cvt_pk_bf16_f32 v47, v42, v43
	v_add_u32_e32 v146, 0x48000, v144
	global_store_dwordx4 v146, v[44:47], s[14:15]
	s_waitcnt vmcnt(15)
; DI unsigned pk2(float a, float b) { f32x2 v = {a, b}; bf16x2_t r = __builtin_convertvector(v, bf16x2_t); return __builtin_bit_cast(unsigned, r); }
; DI float bflo(unsigned u) { return __uint_as_float(u << 16); }
; DI float bfhi(unsigned u) { return __uint_as_float(u & 0xffff0000u); }
; template <class Epi>
; DI void gemm_phase(LAS unsigned char* lds, const Gemm g, const StaticOrder& S, const Epi& E) {
;     ...
;         if (!has_next) break;
;     DI void operator()(const f32x4 (&acc)[2][2][4][2], const Unit& u, int wr, int wc, int fr, int fq) const {
;     ...
;         for (int ai = 0; ai < 2; ++ai)
; #pragma unroll
;             for (int m = 0; m < 4; ++m) { const size_t ro = (size_t)(row0 + ai * HALF + m * 16) * DM + col0;
; #pragma unroll
;                 for (int bj = 0; bj < 2; ++bj) {
;                     const u32x4 q = *(const u32x4*)(xb + ro + bj * HALF);
;                     const f32x4 b0 = {bflo(q.x), bfhi(q.x), bflo(q.y), bfhi(q.y)}, b1 = {bflo(q.z), bfhi(q.z), bflo(q.w), bfhi(q.w)};
;                     const f32x4 x0 = b0 + gv[bj][0] * acc[ai][bj][m][0], x1 = b1 + gv[bj][1] * acc[ai][bj][m][1];
;                     u32x4 w; w.x = pk2(x0.x, x0.y); w.y = pk2(x0.z, x0.w); w.z = pk2(x1.x, x1.y); w.w = pk2(x1.z, x1.w);
;                     *(u32x4*)(xb + ro + bj * HALF) = w; } }
	v_lshlrev_b32_e32 v248, 16, v228
	v_and_b32_e32 v249, 0xffff0000, v228
	v_lshlrev_b32_e32 v250, 16, v229
	v_and_b32_e32 v251, 0xffff0000, v229
	v_lshlrev_b32_e32 v252, 16, v230
	v_and_b32_e32 v253, 0xffff0000, v230
	v_lshlrev_b32_e32 v254, 16, v231
	v_and_b32_e32 v255, 0xffff0000, v231
	v_pk_fma_f32 v[28:29], v[28:29], v[136:137], v[248:249]
	v_pk_fma_f32 v[30:31], v[30:31], v[138:139], v[250:251]
	v_pk_fma_f32 v[24:25], v[24:25], v[140:141], v[252:253]
	v_pk_fma_f32 v[26:27], v[26:27], v[142:143], v[254:255]
	v_cvt_pk_bf16_f32 v28, v28, v29
	v_cvt_pk_bf16_f32 v29, v30, v31
	v_cvt_pk_bf16_f32 v30, v24, v25
	v_cvt_pk_bf16_f32 v31, v26, v27
	v_add_u32_e32 v146, 0x48000, v144
	global_store_dwordx4 v146, v[28:31], s[14:15] offset:256
	s_waitcnt vmcnt(15)
	v_lshlrev_b32_e32 v248, 16, v232
	v_and_b32_e32 v249, 0xffff0000, v232
	v_lshlrev_b32_e32 v250, 16, v233
	v_and_b32_e32 v251, 0xffff0000, v233
	v_lshlrev_b32_e32 v252, 16, v234
	v_and_b32_e32 v253, 0xffff0000, v234
	v_lshlrev_b32_e32 v254, 16, v235
	v_and_b32_e32 v255, 0xffff0000, v235
	v_pk_fma_f32 v[36:37], v[36:37], v[128:129], v[248:249]
	v_pk_fma_f32 v[38:39], v[38:39], v[130:131], v[250:251]
	v_pk_fma_f32 v[32:33], v[32:33], v[132:133], v[252:253]
	v_pk_fma_f32 v[34:35], v[34:35], v[134:135], v[254:255]
	v_cvt_pk_bf16_f32 v36, v36, v37
	v_cvt_pk_bf16_f32 v37, v38, v39
	v_cvt_pk_bf16_f32 v38, v32, v33
	v_cvt_pk_bf16_f32 v39, v34, v35
	v_add_u32_e32 v146, 0x50000, v144
	global_store_dwordx4 v146, v[36:39], s[14:15]
	s_waitcnt vmcnt(15)
	v_lshlrev_b32_e32 v248, 16, v236
	v_and_b32_e32 v249, 0xffff0000, v236
	v_lshlrev_b32_e32 v250, 16, v237
	v_and_b32_e32 v251, 0xffff0000, v237
	v_lshlrev_b32_e32 v252, 16, v238
	v_and_b32_e32 v253, 0xffff0000, v238
	v_lshlrev_b32_e32 v254, 16, v239
	v_and_b32_e32 v255, 0xffff0000, v239
	v_pk_fma_f32 v[12:13], v[12:13], v[136:137], v[248:249]
	v_pk_fma_f32 v[14:15], v[14:15], v[138:139], v[250:251]
	v_pk_fma_f32 v[8:9], v[8:9], v[140:141], v[252:253]
	v_pk_fma_f32 v[10:11], v[10:11], v[142:143], v[254:255]
	v_cvt_pk_bf16_f32 v12, v12, v13
	v_cvt_pk_bf16_f32 v13, v14, v15
	v_cvt_pk_bf16_f32 v14, v8, v9
	v_cvt_pk_bf16_f32 v15, v10, v11
	v_add_u32_e32 v146, 0x50000, v144
	global_store_dwordx4 v146, v[12:15], s[14:15] offset:256
	s_waitcnt vmcnt(15)
	v_lshlrev_b32_e32 v248, 16, v240
	v_and_b32_e32 v249, 0xffff0000, v240
	v_lshlrev_b32_e32 v250, 16, v241
	v_and_b32_e32 v251, 0xffff0000, v241
	v_lshlrev_b32_e32 v252, 16, v242
	v_and_b32_e32 v253, 0xffff0000, v242
	v_lshlrev_b32_e32 v254, 16, v243
	v_and_b32_e32 v255, 0xffff0000, v243
	v_pk_fma_f32 v[20:21], v[20:21], v[128:129], v[248:249]
	v_pk_fma_f32 v[22:23], v[22:23], v[130:131], v[250:251]
	v_pk_fma_f32 v[16:17], v[16:17], v[132:133], v[252:253]
	v_pk_fma_f32 v[18:19], v[18:19], v[134:135], v[254:255]
	v_cvt_pk_bf16_f32 v20, v20, v21
	v_cvt_pk_bf16_f32 v21, v22, v23
	v_cvt_pk_bf16_f32 v22, v16, v17
	v_cvt_pk_bf16_f32 v23, v18, v19
	v_add_u32_e32 v146, 0x58000, v144
	global_store_dwordx4 v146, v[20:23], s[14:15]
	s_waitcnt vmcnt(15)
	v_lshlrev_b32_e32 v248, 16, v244
	v_and_b32_e32 v249, 0xffff0000, v244
	v_lshlrev_b32_e32 v250, 16, v245
	v_and_b32_e32 v251, 0xffff0000, v245
	v_lshlrev_b32_e32 v252, 16, v246
	v_and_b32_e32 v253, 0xffff0000, v246
	v_lshlrev_b32_e32 v254, 16, v247
	v_and_b32_e32 v255, 0xffff0000, v247
	v_pk_fma_f32 v[4:5], v[4:5], v[136:137], v[248:249]
	v_pk_fma_f32 v[6:7], v[6:7], v[138:139], v[250:251]
	v_pk_fma_f32 v[0:1], v[0:1], v[140:141], v[252:253]
	v_pk_fma_f32 v[2:3], v[2:3], v[142:143], v[254:255]
	v_cvt_pk_bf16_f32 v4, v4, v5
	v_cvt_pk_bf16_f32 v5, v6, v7
	v_cvt_pk_bf16_f32 v6, v0, v1
	v_cvt_pk_bf16_f32 v7, v2, v3
	v_add_u32_e32 v146, 0x58000, v144
	global_store_dwordx4 v146, v[4:7], s[14:15] offset:256
	s_and_b64 vcc, exec, s[4:5]
	s_cbranch_vccz .LBB0_917
	s_waitcnt vmcnt(0)
	s_cmpk_gt_u32 s42, 0xff
	s_cbranch_scc1 .LBB0_932
	s_barrier
